# in-projection and up-projection GEMM main loops: per-phase s_setprio flips replaced by s_nop (priority left at 0)
# speedup vs baseline: 1.0031x; 1.0031x over previous
; #define G_STAGE(bufoff, gbase, voff) do { _Pragma("unroll") for (int _i = 0; _i < 2; ++_i) \
;         __builtin_amdgcn_global_load_lds((const unsigned*)((const char*)(gbase) + (voff)[_i]), (LAS unsigned*)(lds + (bufoff) + ldsw + _i * 8192), 16, 0, 0); } while (0)
; #define G_LDA(dst, b, h) do { _Pragma("unroll") for (int m = 0; m < 4; ++m) _Pragma("unroll") for (int k = 0; k < 2; ++k) dst[m][k] = *(const LAS bf16x8*)(lds + G_SA(b, h) + aoff + m * 2048 + k * 1024); } while (0)
; #define G_LDB(dst, b, h) do { _Pragma("unroll") for (int n = 0; n < 2; ++n) _Pragma("unroll") for (int k = 0; k < 2; ++k) dst[n][k] = *(const LAS bf16x8*)(lds + G_SB(b, h) + boff + n * 2048 + k * 1024); } while (0)
; #define G_MMA(ai, bj, At, Bt_) do { __builtin_amdgcn_s_setprio(1); _Pragma("unroll") for (int m = 0; m < 4; ++m) _Pragma("unroll") for (int n = 0; n < 2; ++n) _Pragma("unroll") for (int k = 0; k < 2; ++k) \
;         acc[ai][bj][m][n] = __builtin_amdgcn_mfma_f32_16x16x32_bf16(Bt_[n][k], At[m][k], acc[ai][bj][m][n], 0, 0, 0); __builtin_amdgcn_s_setprio(0); } while (0)
; #define G_WAIT_V(n) asm volatile("s_waitcnt vmcnt(" #n ")" ::: "memory")
; #define G_WAIT_L(n) asm volatile("s_waitcnt lgkmcnt(" #n ")" ::: "memory")
; #define G_BAR __builtin_amdgcn_s_barrier()
; #define G_SCHED __builtin_amdgcn_sched_barrier(0)
; template <class Epi, bool PERMROWS = false>
; DI void gemm_phase(LAS unsigned char* lds, const bf16_t* A, int lda, const bf16_t* Bt, int K, const Sched& S, const Epi& E) {
;     ...
;             G_LDB(B0, 0, 0); G_SCHED; G_LDA(At, 0, 0); G_STAGE(G_SA(1, 1), a1 + hstepA, voffA);
;             G_WAIT_L(8); G_BAR; G_WAIT_L(0); G_MMA(0, 0, At, B0); G_BAR; G_SCHED;
;             G_LDB(B1, 0, 1); G_STAGE(G_SB(0, 0), b2, voffB);
;             G_BAR; G_WAIT_L(0); G_MMA(0, 1, At, B1); G_BAR;
;             G_LDA(At, 0, 1); G_STAGE(G_SA(0, 0), a2, voffA);
;             G_BAR; G_WAIT_L(0); G_MMA(1, 0, At, B0); G_BAR; G_SCHED;
;             G_STAGE(G_SB(0, 1), b2 + hstepB, voffB);
;             G_WAIT_V(6); G_BAR; G_MMA(1, 1, At, B1); G_BAR;
.LBB0_534:
	s_waitcnt lgkmcnt(0)
	ds_read_b128 v[150:153], v174
	ds_read_b128 v[154:157], v174 offset:1024
	ds_read_b128 v[158:161], v174 offset:2048
	ds_read_b128 v[162:165], v174 offset:3072
	s_add_u32 s12, s10, 0xfff80080
	s_addc_u32 s13, s11, -1
	s_cmp_eq_u32 s62, 28
	s_cselect_b32 s57, s2, s13
	s_cselect_b32 s56, s3, s12
	s_cselect_b32 s13, s9, s37
	s_cselect_b32 s12, s27, s35
	v_lshl_add_u64 v[208:209], s[10:11], 0, v[144:145]
	s_add_i32 m0, s71, 0xc000
	ds_read_b128 v[166:169], v175
	ds_read_b128 v[178:181], v175 offset:1024
	ds_read_b128 v[182:185], v175 offset:2048
	ds_read_b128 v[186:189], v175 offset:3072
	ds_read_b128 v[190:193], v175 offset:4096
	ds_read_b128 v[194:197], v175 offset:5120
	ds_read_b128 v[198:201], v175 offset:6144
	ds_read_b128 v[204:207], v175 offset:7168
	global_load_lds_dwordx4 v[208:209], off
	v_lshl_add_u64 v[208:209], s[10:11], 0, v[142:143]
	s_add_i32 m0, s71, 0xe000
	s_nop 0
	global_load_lds_dwordx4 v[208:209], off
	s_waitcnt lgkmcnt(8)
	s_barrier
	s_waitcnt lgkmcnt(0)
	s_nop 0
	s_waitcnt lgkmcnt(0)
	v_mfma_f32_16x16x32_bf16 v[124:127], v[150:153], v[166:169], v[124:127]
	v_mfma_f32_16x16x32_bf16 v[120:123], v[158:161], v[166:169], v[120:123]
	v_mfma_f32_16x16x32_bf16 v[108:111], v[150:153], v[182:185], v[108:111]
	v_mfma_f32_16x16x32_bf16 v[104:107], v[158:161], v[182:185], v[104:107]
	v_mfma_f32_16x16x32_bf16 v[92:95], v[150:153], v[190:193], v[92:95]
	v_mfma_f32_16x16x32_bf16 v[88:91], v[158:161], v[190:193], v[88:91]
	v_mfma_f32_16x16x32_bf16 v[76:79], v[150:153], v[198:201], v[76:79]
	v_mfma_f32_16x16x32_bf16 v[72:75], v[158:161], v[198:201], v[72:75]
	v_mfma_f32_16x16x32_bf16 v[124:127], v[154:157], v[178:181], v[124:127]
	v_mfma_f32_16x16x32_bf16 v[120:123], v[162:165], v[178:181], v[120:123]
	v_mfma_f32_16x16x32_bf16 v[108:111], v[154:157], v[186:189], v[108:111]
	v_mfma_f32_16x16x32_bf16 v[104:107], v[162:165], v[186:189], v[104:107]
	v_mfma_f32_16x16x32_bf16 v[92:95], v[154:157], v[194:197], v[92:95]
	v_mfma_f32_16x16x32_bf16 v[88:91], v[162:165], v[194:197], v[88:91]
	v_mfma_f32_16x16x32_bf16 v[76:79], v[154:157], v[204:207], v[76:79]
	v_mfma_f32_16x16x32_bf16 v[72:75], v[162:165], v[204:207], v[72:75]
	s_nop 0
	s_barrier
	s_add_i32 s28, s85, s70
	v_lshl_add_u64 v[224:225], s[12:13], 0, v[128:129]
	s_mov_b32 m0, s28
	ds_read_b128 v[208:211], v176
	ds_read_b128 v[212:215], v176 offset:1024
	ds_read_b128 v[216:219], v176 offset:2048
	ds_read_b128 v[220:223], v176 offset:3072
	global_load_lds_dwordx4 v[224:225], off
	v_lshl_add_u64 v[226:227], s[12:13], 0, v[130:131]
	s_add_i32 m0, s28, 0x2000
	s_nop 0
	global_load_lds_dwordx4 v[226:227], off
	s_barrier
	s_waitcnt lgkmcnt(0)
	s_nop 0
	s_waitcnt lgkmcnt(0)
	v_mfma_f32_16x16x32_bf16 v[116:119], v[208:211], v[166:169], v[116:119]
	v_mfma_f32_16x16x32_bf16 v[112:115], v[216:219], v[166:169], v[112:115]
	v_mfma_f32_16x16x32_bf16 v[100:103], v[208:211], v[182:185], v[100:103]
	v_mfma_f32_16x16x32_bf16 v[96:99], v[216:219], v[182:185], v[96:99]
	v_mfma_f32_16x16x32_bf16 v[84:87], v[208:211], v[190:193], v[84:87]
	v_mfma_f32_16x16x32_bf16 v[80:83], v[216:219], v[190:193], v[80:83]
	v_mfma_f32_16x16x32_bf16 v[68:71], v[208:211], v[198:201], v[68:71]
	v_mfma_f32_16x16x32_bf16 v[64:67], v[216:219], v[198:201], v[64:67]
	v_mfma_f32_16x16x32_bf16 v[116:119], v[212:215], v[178:181], v[116:119]
	v_mfma_f32_16x16x32_bf16 v[112:115], v[220:223], v[178:181], v[112:115]
	v_mfma_f32_16x16x32_bf16 v[100:103], v[212:215], v[186:189], v[100:103]
	v_mfma_f32_16x16x32_bf16 v[96:99], v[220:223], v[186:189], v[96:99]
	v_mfma_f32_16x16x32_bf16 v[84:87], v[212:215], v[194:197], v[84:87]
	v_mfma_f32_16x16x32_bf16 v[80:83], v[220:223], v[194:197], v[80:83]
	v_mfma_f32_16x16x32_bf16 v[68:71], v[212:215], v[204:207], v[68:71]
	v_mfma_f32_16x16x32_bf16 v[64:67], v[220:223], v[204:207], v[64:67]
	s_nop 0
	s_mov_b32 m0, s71
	v_lshl_add_u64 v[228:229], s[56:57], 0, v[128:129]
	s_barrier
	ds_read_b128 v[166:169], v175 offset:16384
	ds_read_b128 v[178:181], v175 offset:17408
	ds_read_b128 v[182:185], v175 offset:18432
	ds_read_b128 v[186:189], v175 offset:19456
	ds_read_b128 v[190:193], v175 offset:20480
	ds_read_b128 v[194:197], v175 offset:21504
	ds_read_b128 v[198:201], v175 offset:22528
	ds_read_b128 v[204:207], v175 offset:23552
	global_load_lds_dwordx4 v[228:229], off
	v_lshl_add_u64 v[230:231], s[56:57], 0, v[130:131]
	s_mov_b32 m0, s72
	s_nop 0
	global_load_lds_dwordx4 v[230:231], off
	s_barrier
	s_waitcnt lgkmcnt(0)
	s_nop 0
	s_waitcnt lgkmcnt(0)
	v_mfma_f32_16x16x32_bf16 v[60:63], v[150:153], v[166:169], v[60:63]
	v_mfma_f32_16x16x32_bf16 v[56:59], v[158:161], v[166:169], v[56:59]
	v_mfma_f32_16x16x32_bf16 v[44:47], v[150:153], v[182:185], v[44:47]
	v_mfma_f32_16x16x32_bf16 v[40:43], v[158:161], v[182:185], v[40:43]
	v_mfma_f32_16x16x32_bf16 v[28:31], v[150:153], v[190:193], v[28:31]
	v_mfma_f32_16x16x32_bf16 v[24:27], v[158:161], v[190:193], v[24:27]
	v_mfma_f32_16x16x32_bf16 v[12:15], v[150:153], v[198:201], v[12:15]
	v_mfma_f32_16x16x32_bf16 v[8:11], v[158:161], v[198:201], v[8:11]
	v_mfma_f32_16x16x32_bf16 v[60:63], v[154:157], v[178:181], v[60:63]
	v_mfma_f32_16x16x32_bf16 v[56:59], v[162:165], v[178:181], v[56:59]
	v_mfma_f32_16x16x32_bf16 v[44:47], v[154:157], v[186:189], v[44:47]
	v_mfma_f32_16x16x32_bf16 v[40:43], v[162:165], v[186:189], v[40:43]
	v_mfma_f32_16x16x32_bf16 v[28:31], v[154:157], v[194:197], v[28:31]
	v_mfma_f32_16x16x32_bf16 v[24:27], v[162:165], v[194:197], v[24:27]
	v_mfma_f32_16x16x32_bf16 v[12:15], v[154:157], v[204:207], v[12:15]
	v_mfma_f32_16x16x32_bf16 v[8:11], v[162:165], v[204:207], v[8:11]
	s_nop 0
	s_barrier
; #define G_STAGE(bufoff, gbase, voff) do { _Pragma("unroll") for (int _i = 0; _i < 2; ++_i) \
;         __builtin_amdgcn_global_load_lds((const unsigned*)((const char*)(gbase) + (voff)[_i]), (LAS unsigned*)(lds + (bufoff) + ldsw + _i * 8192), 16, 0, 0); } while (0)
; #define G_LDA(dst, b, h) do { _Pragma("unroll") for (int m = 0; m < 4; ++m) _Pragma("unroll") for (int k = 0; k < 2; ++k) dst[m][k] = *(const LAS bf16x8*)(lds + G_SA(b, h) + aoff + m * 2048 + k * 1024); } while (0)
; #define G_LDB(dst, b, h) do { _Pragma("unroll") for (int n = 0; n < 2; ++n) _Pragma("unroll") for (int k = 0; k < 2; ++k) dst[n][k] = *(const LAS bf16x8*)(lds + G_SB(b, h) + boff + n * 2048 + k * 1024); } while (0)
; #define G_MMA(ai, bj, At, Bt_) do { __builtin_amdgcn_s_setprio(1); _Pragma("unroll") for (int m = 0; m < 4; ++m) _Pragma("unroll") for (int n = 0; n < 2; ++n) _Pragma("unroll") for (int k = 0; k < 2; ++k) \
;         acc[ai][bj][m][n] = __builtin_amdgcn_mfma_f32_16x16x32_bf16(Bt_[n][k], At[m][k], acc[ai][bj][m][n], 0, 0, 0); __builtin_amdgcn_s_setprio(0); } while (0)
; #define G_WAIT_V(n) asm volatile("s_waitcnt vmcnt(" #n ")" ::: "memory")
; #define G_WAIT_L(n) asm volatile("s_waitcnt lgkmcnt(" #n ")" ::: "memory")
; #define G_BAR __builtin_amdgcn_s_barrier()
; #define G_SCHED __builtin_amdgcn_sched_barrier(0)
; template <class Epi, bool PERMROWS = false>
; DI void gemm_phase(LAS unsigned char* lds, const bf16_t* A, int lda, const bf16_t* Bt, int K, const Sched& S, const Epi& E) {
;     ...
;             G_WAIT_V(6); G_BAR; G_MMA(1, 1, At, B1); G_BAR;
;             G_LDB(B0, 1, 0); G_SCHED; G_LDA(At, 1, 0); G_STAGE(G_SA(0, 1), a2 + hstepA, voffA);
;             G_WAIT_L(8); G_BAR; G_WAIT_L(0); G_MMA(0, 0, At, B0); G_BAR; G_SCHED;
;             G_LDB(B1, 1, 1); G_STAGE(G_SB(1, 0), b3, voffB);
;             G_BAR; G_WAIT_L(0); G_MMA(0, 1, At, B1); G_BAR;
;             G_LDA(At, 1, 1); G_STAGE(G_SA(1, 0), a3, voffA);
;             G_BAR; G_WAIT_L(0); G_MMA(1, 0, At, B0); G_BAR; G_SCHED;
	s_add_u32 s28, s12, 0x80000
	s_addc_u32 s29, s13, 0
	s_add_i32 s63, s86, s70
	v_lshl_add_u64 v[150:151], s[28:29], 0, v[128:129]
	s_mov_b32 m0, s63
	s_nop 0
	global_load_lds_dwordx4 v[150:151], off
	v_lshl_add_u64 v[150:151], s[28:29], 0, v[130:131]
	s_add_i32 m0, s63, 0x2000
	s_nop 0
	global_load_lds_dwordx4 v[150:151], off
	s_waitcnt vmcnt(6)
	s_barrier
	s_nop 0
	v_mfma_f32_16x16x32_bf16 v[52:55], v[208:211], v[166:169], v[52:55]
	v_mfma_f32_16x16x32_bf16 v[48:51], v[216:219], v[166:169], v[48:51]
	v_mfma_f32_16x16x32_bf16 v[36:39], v[208:211], v[182:185], v[36:39]
	v_mfma_f32_16x16x32_bf16 v[32:35], v[216:219], v[182:185], v[32:35]
	v_mfma_f32_16x16x32_bf16 v[20:23], v[208:211], v[190:193], v[20:23]
	v_mfma_f32_16x16x32_bf16 v[16:19], v[216:219], v[190:193], v[16:19]
	v_mfma_f32_16x16x32_bf16 v[4:7], v[208:211], v[198:201], v[4:7]
	v_mfma_f32_16x16x32_bf16 v[0:3], v[216:219], v[198:201], v[0:3]
	v_mfma_f32_16x16x32_bf16 v[52:55], v[212:215], v[178:181], v[52:55]
	v_mfma_f32_16x16x32_bf16 v[48:51], v[220:223], v[178:181], v[48:51]
	v_mfma_f32_16x16x32_bf16 v[36:39], v[212:215], v[186:189], v[36:39]
	v_mfma_f32_16x16x32_bf16 v[32:35], v[220:223], v[186:189], v[32:35]
	v_mfma_f32_16x16x32_bf16 v[20:23], v[212:215], v[194:197], v[20:23]
	v_mfma_f32_16x16x32_bf16 v[16:19], v[220:223], v[194:197], v[16:19]
	v_mfma_f32_16x16x32_bf16 v[4:7], v[212:215], v[204:207], v[4:7]
	v_mfma_f32_16x16x32_bf16 v[0:3], v[220:223], v[204:207], v[0:3]
	s_nop 0
	s_add_i32 s63, 0, 0x18000
	v_add_u32_e32 v132, s63, v170
	s_barrier
	ds_read_b128 v[150:153], v132
	ds_read_b128 v[154:157], v132 offset:1024
	ds_read_b128 v[158:161], v132 offset:2048
	ds_read_b128 v[162:165], v132 offset:3072
	s_add_u32 s28, s56, 0x80000
	s_addc_u32 s29, s57, 0
	s_mov_b32 m0, s73
	v_lshl_add_u64 v[208:209], s[28:29], 0, v[128:129]
	ds_read_b128 v[166:169], v175 offset:32768
	ds_read_b128 v[178:181], v175 offset:33792
	ds_read_b128 v[182:185], v175 offset:34816
	ds_read_b128 v[186:189], v175 offset:35840
	ds_read_b128 v[190:193], v175 offset:36864
	ds_read_b128 v[194:197], v175 offset:37888
	ds_read_b128 v[198:201], v175 offset:38912
	ds_read_b128 v[204:207], v175 offset:39936
	global_load_lds_dwordx4 v[208:209], off
	v_lshl_add_u64 v[208:209], s[28:29], 0, v[130:131]
	s_mov_b32 m0, s74
	s_nop 0
	global_load_lds_dwordx4 v[208:209], off
	s_waitcnt lgkmcnt(8)
	s_barrier
	s_waitcnt lgkmcnt(0)
	s_nop 0
	s_waitcnt lgkmcnt(0)
	v_mfma_f32_16x16x32_bf16 v[124:127], v[150:153], v[166:169], v[124:127]
	v_mfma_f32_16x16x32_bf16 v[120:123], v[158:161], v[166:169], v[120:123]
	v_mfma_f32_16x16x32_bf16 v[108:111], v[150:153], v[182:185], v[108:111]
	v_mfma_f32_16x16x32_bf16 v[104:107], v[158:161], v[182:185], v[104:107]
	v_mfma_f32_16x16x32_bf16 v[92:95], v[150:153], v[190:193], v[92:95]
	v_mfma_f32_16x16x32_bf16 v[88:91], v[158:161], v[190:193], v[88:91]
	v_mfma_f32_16x16x32_bf16 v[76:79], v[150:153], v[198:201], v[76:79]
	v_mfma_f32_16x16x32_bf16 v[72:75], v[158:161], v[198:201], v[72:75]
	v_mfma_f32_16x16x32_bf16 v[124:127], v[154:157], v[178:181], v[124:127]
	v_mfma_f32_16x16x32_bf16 v[120:123], v[162:165], v[178:181], v[120:123]
	v_mfma_f32_16x16x32_bf16 v[108:111], v[154:157], v[186:189], v[108:111]
	v_mfma_f32_16x16x32_bf16 v[104:107], v[162:165], v[186:189], v[104:107]
	v_mfma_f32_16x16x32_bf16 v[92:95], v[154:157], v[194:197], v[92:95]
	v_mfma_f32_16x16x32_bf16 v[88:91], v[162:165], v[194:197], v[88:91]
	v_mfma_f32_16x16x32_bf16 v[76:79], v[154:157], v[204:207], v[76:79]
	v_mfma_f32_16x16x32_bf16 v[72:75], v[162:165], v[204:207], v[72:75]
	s_nop 0
	s_barrier
	s_add_i32 s28, 0, 0x1c000
	s_add_i32 s29, s63, s70
	v_add_u32_e32 v132, s28, v170
	v_lshl_add_u64 v[224:225], v[224:225], 0, s[14:15]
	s_mov_b32 m0, s29
	ds_read_b128 v[208:211], v132
	ds_read_b128 v[212:215], v132 offset:1024
	ds_read_b128 v[216:219], v132 offset:2048
	ds_read_b128 v[220:223], v132 offset:3072
	global_load_lds_dwordx4 v[224:225], off
	v_lshl_add_u64 v[224:225], v[226:227], 0, s[14:15]
	s_add_i32 m0, s29, 0x2000
	s_nop 0
	global_load_lds_dwordx4 v[224:225], off
	s_barrier
	s_waitcnt lgkmcnt(0)
	s_nop 0
	s_waitcnt lgkmcnt(0)
	v_mfma_f32_16x16x32_bf16 v[116:119], v[208:211], v[166:169], v[116:119]
	v_mfma_f32_16x16x32_bf16 v[112:115], v[216:219], v[166:169], v[112:115]
	v_mfma_f32_16x16x32_bf16 v[100:103], v[208:211], v[182:185], v[100:103]
	v_mfma_f32_16x16x32_bf16 v[96:99], v[216:219], v[182:185], v[96:99]
	v_mfma_f32_16x16x32_bf16 v[84:87], v[208:211], v[190:193], v[84:87]
	v_mfma_f32_16x16x32_bf16 v[80:83], v[216:219], v[190:193], v[80:83]
	v_mfma_f32_16x16x32_bf16 v[68:71], v[208:211], v[198:201], v[68:71]
	v_mfma_f32_16x16x32_bf16 v[64:67], v[216:219], v[198:201], v[64:67]
	v_mfma_f32_16x16x32_bf16 v[116:119], v[212:215], v[178:181], v[116:119]
	v_mfma_f32_16x16x32_bf16 v[112:115], v[220:223], v[178:181], v[112:115]
	v_mfma_f32_16x16x32_bf16 v[100:103], v[212:215], v[186:189], v[100:103]
	v_mfma_f32_16x16x32_bf16 v[96:99], v[220:223], v[186:189], v[96:99]
	v_mfma_f32_16x16x32_bf16 v[84:87], v[212:215], v[194:197], v[84:87]
	v_mfma_f32_16x16x32_bf16 v[80:83], v[220:223], v[194:197], v[80:83]
	v_mfma_f32_16x16x32_bf16 v[68:71], v[212:215], v[204:207], v[68:71]
	v_mfma_f32_16x16x32_bf16 v[64:67], v[220:223], v[204:207], v[64:67]
	s_nop 0
	s_mov_b32 m0, s76
	v_lshl_add_u64 v[224:225], v[228:229], 0, s[14:15]
	s_barrier
; #define G_STAGE(bufoff, gbase, voff) do { _Pragma("unroll") for (int _i = 0; _i < 2; ++_i) \
;         __builtin_amdgcn_global_load_lds((const unsigned*)((const char*)(gbase) + (voff)[_i]), (LAS unsigned*)(lds + (bufoff) + ldsw + _i * 8192), 16, 0, 0); } while (0)
; #define G_MMA(ai, bj, At, Bt_) do { __builtin_amdgcn_s_setprio(1); _Pragma("unroll") for (int m = 0; m < 4; ++m) _Pragma("unroll") for (int n = 0; n < 2; ++n) _Pragma("unroll") for (int k = 0; k < 2; ++k) \
;         acc[ai][bj][m][n] = __builtin_amdgcn_mfma_f32_16x16x32_bf16(Bt_[n][k], At[m][k], acc[ai][bj][m][n], 0, 0, 0); __builtin_amdgcn_s_setprio(0); } while (0)
; #define G_BAR __builtin_amdgcn_s_barrier()
; template <class Epi, bool PERMROWS = false>
; DI void gemm_phase(LAS unsigned char* lds, const bf16_t* A, int lda, const bf16_t* Bt, int K, const Sched& S, const Epi& E) {
;     ...
;             G_BAR; G_WAIT_L(0); G_MMA(1, 0, At, B0); G_BAR; G_SCHED;
;             G_STAGE(G_SB(1, 1), b3 + hstepB, voffB);
;             G_WAIT_V(6); G_BAR; G_MMA(1, 1, At, B1); G_BAR;
;     DI void operator()(const f32x4 (&acc)[2][2][4][2], const Unit& u, int wr, int wc, int fr, int fq) const {
;         bf16_t* P = (bf16_t*)(ws + WS_P);
;         const int b = u.pm / 9;
; #pragma unroll
;         for (int ai = 0; ai < 2; ++ai)
; #pragma unroll
;             for (int m = 0; m < 4; ++m) {
;                 const int row = u.pm * BM + ai * HALF + wr * 64 + m * 16 + fr;
;                 const int r = row - b * RB; const bool lat = r >= CL; const int t = r - CL;
; #pragma unroll
;                 for (int bj = 0; bj < 2; ++bj) {
;                     const int colg = u.pn * BM + bj * HALF + wc * 32;
;                     f32x4 v0 = acc[ai][bj][m][0], v1 = acc[ai][bj][m][1];
;                     const int c0 = colg + 4 * fq;
;                     if (colg >= INW) continue;
;                     if (colg >= C_NAV && colg < C_CQ) {
;                         st_tr16x32(spare + (wr * 4 + wc) * 1024, (bf16_t*)(ws + WS_VTNA) + ((size_t)b * 768 + (colg - C_NAV)) * RB + (r - fr), v0, v1, fr, fq, fq * 16 + fr);
;                     } else if (colg >= C_RV && colg < C_RG) {
;                         st_tr16x32(spare + (wr * 4 + wc) * 1024, (bf16_t*)(ws + WS_VTR) + ((size_t)b * 640 + (colg - C_RV)) * RB + (r - fr), v0, v1, fr, fq, fq * 16 + fr);
;                     } else if (colg >= C_KPE && colg < C_RQ) {
	ds_read_b128 v[166:169], v175 offset:49152
	ds_read_b128 v[178:181], v175 offset:50176
	ds_read_b128 v[182:185], v175 offset:51200
	ds_read_b128 v[186:189], v175 offset:52224
	ds_read_b128 v[190:193], v175 offset:53248
	ds_read_b128 v[194:197], v175 offset:54272
	ds_read_b128 v[198:201], v175 offset:55296
	ds_read_b128 v[204:207], v175 offset:56320
	global_load_lds_dwordx4 v[224:225], off
	v_lshl_add_u64 v[224:225], v[230:231], 0, s[14:15]
	s_mov_b32 m0, s77
	s_nop 0
	global_load_lds_dwordx4 v[224:225], off
	s_barrier
	s_waitcnt lgkmcnt(0)
	s_nop 0
	s_waitcnt lgkmcnt(0)
	v_mfma_f32_16x16x32_bf16 v[60:63], v[150:153], v[166:169], v[60:63]
	v_mfma_f32_16x16x32_bf16 v[56:59], v[158:161], v[166:169], v[56:59]
	v_mfma_f32_16x16x32_bf16 v[44:47], v[150:153], v[182:185], v[44:47]
	v_mfma_f32_16x16x32_bf16 v[40:43], v[158:161], v[182:185], v[40:43]
	v_mfma_f32_16x16x32_bf16 v[28:31], v[150:153], v[190:193], v[28:31]
	v_mfma_f32_16x16x32_bf16 v[24:27], v[158:161], v[190:193], v[24:27]
	v_mfma_f32_16x16x32_bf16 v[12:15], v[150:153], v[198:201], v[12:15]
	v_mfma_f32_16x16x32_bf16 v[8:11], v[158:161], v[198:201], v[8:11]
	v_mfma_f32_16x16x32_bf16 v[60:63], v[154:157], v[178:181], v[60:63]
	v_mfma_f32_16x16x32_bf16 v[56:59], v[162:165], v[178:181], v[56:59]
	v_mfma_f32_16x16x32_bf16 v[44:47], v[154:157], v[186:189], v[44:47]
	v_mfma_f32_16x16x32_bf16 v[40:43], v[162:165], v[186:189], v[40:43]
	v_mfma_f32_16x16x32_bf16 v[28:31], v[154:157], v[194:197], v[28:31]
	v_mfma_f32_16x16x32_bf16 v[24:27], v[162:165], v[194:197], v[24:27]
	v_mfma_f32_16x16x32_bf16 v[12:15], v[154:157], v[204:207], v[12:15]
	v_mfma_f32_16x16x32_bf16 v[8:11], v[162:165], v[204:207], v[8:11]
	s_nop 0
	s_barrier
	s_add_u32 s12, s12, 0x80080
	s_addc_u32 s13, s13, 0
	s_add_i32 s28, s28, s70
	v_lshl_add_u64 v[150:151], s[12:13], 0, v[128:129]
	s_mov_b32 m0, s28
	s_nop 0
	global_load_lds_dwordx4 v[150:151], off
	v_lshl_add_u64 v[150:151], s[12:13], 0, v[130:131]
	s_add_i32 m0, s28, 0x2000
	s_nop 0
	global_load_lds_dwordx4 v[150:151], off
	s_waitcnt vmcnt(6)
	s_barrier
	s_nop 0
	v_mfma_f32_16x16x32_bf16 v[52:55], v[208:211], v[166:169], v[52:55]
	v_mfma_f32_16x16x32_bf16 v[48:51], v[216:219], v[166:169], v[48:51]
	v_mfma_f32_16x16x32_bf16 v[36:39], v[208:211], v[182:185], v[36:39]
	v_mfma_f32_16x16x32_bf16 v[32:35], v[216:219], v[182:185], v[32:35]
	v_mfma_f32_16x16x32_bf16 v[20:23], v[208:211], v[190:193], v[20:23]
	v_mfma_f32_16x16x32_bf16 v[16:19], v[216:219], v[190:193], v[16:19]
	v_mfma_f32_16x16x32_bf16 v[4:7], v[208:211], v[198:201], v[4:7]
	v_mfma_f32_16x16x32_bf16 v[0:3], v[216:219], v[198:201], v[0:3]
	v_mfma_f32_16x16x32_bf16 v[52:55], v[212:215], v[178:181], v[52:55]
	v_mfma_f32_16x16x32_bf16 v[48:51], v[220:223], v[178:181], v[48:51]
	v_mfma_f32_16x16x32_bf16 v[36:39], v[212:215], v[186:189], v[36:39]
	v_mfma_f32_16x16x32_bf16 v[32:35], v[220:223], v[186:189], v[32:35]
	v_mfma_f32_16x16x32_bf16 v[20:23], v[212:215], v[194:197], v[20:23]
	v_mfma_f32_16x16x32_bf16 v[16:19], v[220:223], v[194:197], v[16:19]
	v_mfma_f32_16x16x32_bf16 v[4:7], v[212:215], v[204:207], v[4:7]
	v_mfma_f32_16x16x32_bf16 v[0:3], v[220:223], v[204:207], v[0:3]
	s_nop 0
	s_add_i32 s62, s62, 2
	s_add_u32 s35, s35, 0x100
	s_addc_u32 s37, s37, 0
	s_add_u32 s10, s10, 0x100
	s_addc_u32 s11, s11, 0
	s_cmp_gt_u32 s62, 29
	s_barrier
	s_cbranch_scc0 .LBB0_534
	v_bfe_u32 v194, v202, 6, 2
	v_and_b32_e32 v169, 15, v202
	v_readfirstlane_b32 s9, v194
	s_lshl_b32 s35, s0, 8
	s_lshl_b32 s93, s9, 5
	s_add_u32 s35, s35, s93
	s_mov_b32 s37, 1
	s_cmpk_lt_u32 s35, 0x600
	s_cbranch_scc1 .Lip0_c0_d
	s_mov_b32 s37, 4
	s_cmpk_lt_u32 s35, 0x900
	s_cbranch_scc1 .Lip0_c0_d
	s_mov_b32 s37, 6
	s_cmpk_lt_u32 s35, 0xd00
	s_cbranch_scc1 .Lip0_c0_d
	s_mov_b32 s37, 7
	s_cmpk_lt_u32 s35, 0xd40
	s_cbranch_scc1 .Lip0_c0_d
	s_mov_b32 s37, 2
	s_cmpk_lt_u32 s35, 0xfc0
	s_cbranch_scc1 .Lip0_c0_d
	s_mov_b32 s37, 3
	s_cmpk_lt_u32 s35, 0x1240
	s_cbranch_scc1 .Lip0_c0_d
	s_mov_b32 s37, 5
	s_cmpk_lt_u32 s35, 0x14c0
	s_cbranch_scc1 .Lip0_c0_d
	s_mov_b32 s37, 1
	s_cmpk_lt_u32 s35, 0x1740
	s_cbranch_scc1 .Lip0_c0_d
	s_mov_b32 s37, 0

; #define G_STAGE(bufoff, gbase, voff) do { _Pragma("unroll") for (int _i = 0; _i < 2; ++_i) \
;         __builtin_amdgcn_global_load_lds((const unsigned*)((const char*)(gbase) + (voff)[_i]), (LAS unsigned*)(lds + (bufoff) + ldsw + _i * 8192), 16, 0, 0); } while (0)
; #define G_LDA(dst, b, h) do { _Pragma("unroll") for (int m = 0; m < 4; ++m) _Pragma("unroll") for (int k = 0; k < 2; ++k) dst[m][k] = *(const LAS bf16x8*)(lds + G_SA(b, h) + aoff + m * 2048 + k * 1024); } while (0)
; #define G_LDB(dst, b, h) do { _Pragma("unroll") for (int n = 0; n < 2; ++n) _Pragma("unroll") for (int k = 0; k < 2; ++k) dst[n][k] = *(const LAS bf16x8*)(lds + G_SB(b, h) + boff + n * 2048 + k * 1024); } while (0)
; #define G_MMA(ai, bj, At, Bt_) do { __builtin_amdgcn_s_setprio(1); _Pragma("unroll") for (int m = 0; m < 4; ++m) _Pragma("unroll") for (int n = 0; n < 2; ++n) _Pragma("unroll") for (int k = 0; k < 2; ++k) \
;         acc[ai][bj][m][n] = __builtin_amdgcn_mfma_f32_16x16x32_bf16(Bt_[n][k], At[m][k], acc[ai][bj][m][n], 0, 0, 0); __builtin_amdgcn_s_setprio(0); } while (0)
; #define G_WAIT_V(n) asm volatile("s_waitcnt vmcnt(" #n ")" ::: "memory")
; #define G_WAIT_L(n) asm volatile("s_waitcnt lgkmcnt(" #n ")" ::: "memory")
; #define G_BAR __builtin_amdgcn_s_barrier()
; #define G_SCHED __builtin_amdgcn_sched_barrier(0)
; template <class Epi, bool PERMROWS = false>
; DI void gemm_phase(LAS unsigned char* lds, const bf16_t* A, int lda, const bf16_t* Bt, int K, const Sched& S, const Epi& E) {
;     ...
;             G_LDB(B0, 0, 0); G_SCHED; G_LDA(At, 0, 0); G_STAGE(G_SA(1, 1), a1 + hstepA, voffA);
;             G_WAIT_L(8); G_BAR; G_WAIT_L(0); G_MMA(0, 0, At, B0); G_BAR; G_SCHED;
;             G_LDB(B1, 0, 1); G_STAGE(G_SB(0, 0), b2, voffB);
;             G_BAR; G_WAIT_L(0); G_MMA(0, 1, At, B1); G_BAR;
;             G_LDA(At, 0, 1); G_STAGE(G_SA(0, 0), a2, voffA);
;             G_BAR; G_WAIT_L(0); G_MMA(1, 0, At, B0); G_BAR; G_SCHED;
;             G_STAGE(G_SB(0, 1), b2 + hstepB, voffB);
;             G_WAIT_V(6); G_BAR; G_MMA(1, 1, At, B1); G_BAR;
.LBB0_1519:
	ds_read_b128 v[128:131], v187
	ds_read_b128 v[132:135], v187 offset:1024
	ds_read_b128 v[136:139], v187 offset:2048
	ds_read_b128 v[140:143], v187 offset:3072
	s_add_u32 s82, s80, 0x100
	s_addc_u32 s83, s81, 0
	s_cmp_eq_u32 s29, 28
	s_cselect_b32 s87, s73, s83
	s_cselect_b32 s86, s79, s82
	s_cselect_b32 s85, s71, s28
	s_cselect_b32 s84, vcc_lo, vcc_hi
	v_lshl_add_u64 v[200:201], s[80:81], 0, v[158:159]
	s_add_i32 m0, s27, 0xc000
	ds_read_b128 v[164:167], v188
	ds_read_b128 v[168:171], v188 offset:1024
	ds_read_b128 v[172:175], v188 offset:2048
	ds_read_b128 v[176:179], v188 offset:3072
	ds_read_b128 v[180:183], v188 offset:4096
	ds_read_b128 v[192:195], v188 offset:5120
	ds_read_b128 v[196:199], v188 offset:6144
	ds_read_b128 v[204:207], v188 offset:7168
	global_load_lds_dwordx4 v[200:201], off
	v_lshl_add_u64 v[200:201], s[80:81], 0, v[156:157]
	s_add_i32 m0, s27, 0xe000
	s_nop 0
	global_load_lds_dwordx4 v[200:201], off
	s_waitcnt lgkmcnt(8)
	s_barrier
	s_waitcnt lgkmcnt(0)
	s_nop 0
	s_waitcnt lgkmcnt(0)
	v_mfma_f32_16x16x32_bf16 v[84:87], v[128:131], v[164:167], v[84:87]
	v_mfma_f32_16x16x32_bf16 v[12:15], v[136:139], v[164:167], v[12:15]
	v_mfma_f32_16x16x32_bf16 v[88:91], v[128:131], v[172:175], v[88:91]
	v_mfma_f32_16x16x32_bf16 v[60:63], v[136:139], v[172:175], v[60:63]
	v_mfma_f32_16x16x32_bf16 v[80:83], v[128:131], v[180:183], v[80:83]
	v_mfma_f32_16x16x32_bf16 v[52:55], v[136:139], v[180:183], v[52:55]
	v_mfma_f32_16x16x32_bf16 v[76:79], v[128:131], v[196:199], v[76:79]
	v_mfma_f32_16x16x32_bf16 v[44:47], v[136:139], v[196:199], v[44:47]
	v_mfma_f32_16x16x32_bf16 v[84:87], v[132:135], v[168:171], v[84:87]
	v_mfma_f32_16x16x32_bf16 v[12:15], v[140:143], v[168:171], v[12:15]
	v_mfma_f32_16x16x32_bf16 v[88:91], v[132:135], v[176:179], v[88:91]
	v_mfma_f32_16x16x32_bf16 v[60:63], v[140:143], v[176:179], v[60:63]
	v_mfma_f32_16x16x32_bf16 v[80:83], v[132:135], v[192:195], v[80:83]
	v_mfma_f32_16x16x32_bf16 v[52:55], v[140:143], v[192:195], v[52:55]
	v_mfma_f32_16x16x32_bf16 v[76:79], v[132:135], v[204:207], v[76:79]
	v_mfma_f32_16x16x32_bf16 v[44:47], v[140:143], v[204:207], v[44:47]
	s_nop 0
	s_barrier
	s_add_i32 s80, s16, s5
	v_lshl_add_u64 v[200:201], s[84:85], 0, v[148:149]
	s_mov_b32 m0, s80
	ds_read_b128 v[208:211], v189
	ds_read_b128 v[212:215], v189 offset:1024
	ds_read_b128 v[216:219], v189 offset:2048
	ds_read_b128 v[220:223], v189 offset:3072
	global_load_lds_dwordx4 v[200:201], off
	v_lshl_add_u64 v[224:225], s[84:85], 0, v[144:145]
	s_add_i32 m0, s80, 0x2000
	s_nop 0
	global_load_lds_dwordx4 v[224:225], off
	s_barrier
	s_waitcnt lgkmcnt(0)
	s_nop 0
	s_waitcnt lgkmcnt(0)
	v_mfma_f32_16x16x32_bf16 v[72:75], v[208:211], v[164:167], v[72:75]
	v_mfma_f32_16x16x32_bf16 v[8:11], v[216:219], v[164:167], v[8:11]
	v_mfma_f32_16x16x32_bf16 v[124:127], v[208:211], v[172:175], v[124:127]
	v_mfma_f32_16x16x32_bf16 v[56:59], v[216:219], v[172:175], v[56:59]
	v_mfma_f32_16x16x32_bf16 v[120:123], v[208:211], v[180:183], v[120:123]
	v_mfma_f32_16x16x32_bf16 v[48:51], v[216:219], v[180:183], v[48:51]
	v_mfma_f32_16x16x32_bf16 v[116:119], v[208:211], v[196:199], v[116:119]
	v_mfma_f32_16x16x32_bf16 v[40:43], v[216:219], v[196:199], v[40:43]
	v_mfma_f32_16x16x32_bf16 v[72:75], v[212:215], v[168:171], v[72:75]
	v_mfma_f32_16x16x32_bf16 v[8:11], v[220:223], v[168:171], v[8:11]
	v_mfma_f32_16x16x32_bf16 v[124:127], v[212:215], v[176:179], v[124:127]
	v_mfma_f32_16x16x32_bf16 v[56:59], v[220:223], v[176:179], v[56:59]
	v_mfma_f32_16x16x32_bf16 v[120:123], v[212:215], v[192:195], v[120:123]
	v_mfma_f32_16x16x32_bf16 v[48:51], v[220:223], v[192:195], v[48:51]
	v_mfma_f32_16x16x32_bf16 v[116:119], v[212:215], v[204:207], v[116:119]
	v_mfma_f32_16x16x32_bf16 v[40:43], v[220:223], v[204:207], v[40:43]
	s_nop 0
	s_mov_b32 m0, s27
	v_lshl_add_u64 v[226:227], s[86:87], 0, v[150:151]
	s_barrier
	ds_read_b128 v[164:167], v188 offset:16384
	ds_read_b128 v[168:171], v188 offset:17408
	ds_read_b128 v[172:175], v188 offset:18432
	ds_read_b128 v[176:179], v188 offset:19456
	ds_read_b128 v[180:183], v188 offset:20480
	ds_read_b128 v[192:195], v188 offset:21504
	ds_read_b128 v[196:199], v188 offset:22528
	ds_read_b128 v[204:207], v188 offset:23552
	global_load_lds_dwordx4 v[226:227], off
	v_lshl_add_u64 v[228:229], s[86:87], 0, v[146:147]
	s_mov_b32 m0, s30
	s_nop 0
	global_load_lds_dwordx4 v[228:229], off
	s_barrier
	s_waitcnt lgkmcnt(0)
	s_nop 0
	s_waitcnt lgkmcnt(0)
	v_mfma_f32_16x16x32_bf16 v[112:115], v[128:131], v[164:167], v[112:115]
	v_mfma_f32_16x16x32_bf16 v[36:39], v[136:139], v[164:167], v[36:39]
	v_mfma_f32_16x16x32_bf16 v[104:107], v[128:131], v[172:175], v[104:107]
	v_mfma_f32_16x16x32_bf16 v[28:31], v[136:139], v[172:175], v[28:31]
	v_mfma_f32_16x16x32_bf16 v[96:99], v[128:131], v[180:183], v[96:99]
	v_mfma_f32_16x16x32_bf16 v[20:23], v[136:139], v[180:183], v[20:23]
	v_mfma_f32_16x16x32_bf16 v[68:71], v[128:131], v[196:199], v[68:71]
	v_mfma_f32_16x16x32_bf16 v[4:7], v[136:139], v[196:199], v[4:7]
	v_mfma_f32_16x16x32_bf16 v[112:115], v[132:135], v[168:171], v[112:115]
	v_mfma_f32_16x16x32_bf16 v[36:39], v[140:143], v[168:171], v[36:39]
	v_mfma_f32_16x16x32_bf16 v[104:107], v[132:135], v[176:179], v[104:107]
	v_mfma_f32_16x16x32_bf16 v[28:31], v[140:143], v[176:179], v[28:31]
	v_mfma_f32_16x16x32_bf16 v[96:99], v[132:135], v[192:195], v[96:99]
	v_mfma_f32_16x16x32_bf16 v[20:23], v[140:143], v[192:195], v[20:23]
	v_mfma_f32_16x16x32_bf16 v[68:71], v[132:135], v[204:207], v[68:71]
	v_mfma_f32_16x16x32_bf16 v[4:7], v[140:143], v[204:207], v[4:7]
	s_nop 0
	s_barrier
; #define G_STAGE(bufoff, gbase, voff) do { _Pragma("unroll") for (int _i = 0; _i < 2; ++_i) \
;         __builtin_amdgcn_global_load_lds((const unsigned*)((const char*)(gbase) + (voff)[_i]), (LAS unsigned*)(lds + (bufoff) + ldsw + _i * 8192), 16, 0, 0); } while (0)
; #define G_LDA(dst, b, h) do { _Pragma("unroll") for (int m = 0; m < 4; ++m) _Pragma("unroll") for (int k = 0; k < 2; ++k) dst[m][k] = *(const LAS bf16x8*)(lds + G_SA(b, h) + aoff + m * 2048 + k * 1024); } while (0)
; #define G_LDB(dst, b, h) do { _Pragma("unroll") for (int n = 0; n < 2; ++n) _Pragma("unroll") for (int k = 0; k < 2; ++k) dst[n][k] = *(const LAS bf16x8*)(lds + G_SB(b, h) + boff + n * 2048 + k * 1024); } while (0)
; #define G_MMA(ai, bj, At, Bt_) do { __builtin_amdgcn_s_setprio(1); _Pragma("unroll") for (int m = 0; m < 4; ++m) _Pragma("unroll") for (int n = 0; n < 2; ++n) _Pragma("unroll") for (int k = 0; k < 2; ++k) \
;         acc[ai][bj][m][n] = __builtin_amdgcn_mfma_f32_16x16x32_bf16(Bt_[n][k], At[m][k], acc[ai][bj][m][n], 0, 0, 0); __builtin_amdgcn_s_setprio(0); } while (0)
; #define G_WAIT_V(n) asm volatile("s_waitcnt vmcnt(" #n ")" ::: "memory")
; #define G_WAIT_L(n) asm volatile("s_waitcnt lgkmcnt(" #n ")" ::: "memory")
; #define G_BAR __builtin_amdgcn_s_barrier()
; #define G_SCHED __builtin_amdgcn_sched_barrier(0)
; template <class Epi, bool PERMROWS = false>
; DI void gemm_phase(LAS unsigned char* lds, const bf16_t* A, int lda, const bf16_t* Bt, int K, const Sched& S, const Epi& E) {
;     ...
;             G_WAIT_V(6); G_BAR; G_MMA(1, 1, At, B1); G_BAR;
;             G_LDB(B0, 1, 0); G_SCHED; G_LDA(At, 1, 0); G_STAGE(G_SA(0, 1), a2 + hstepA, voffA);
;             G_WAIT_L(8); G_BAR; G_WAIT_L(0); G_MMA(0, 0, At, B0); G_BAR; G_SCHED;
;             G_LDB(B1, 1, 1); G_STAGE(G_SB(1, 0), b3, voffB);
;             G_BAR; G_WAIT_L(0); G_MMA(0, 1, At, B1); G_BAR;
;             G_LDA(At, 1, 1); G_STAGE(G_SA(1, 0), a3, voffA);
;             G_BAR; G_WAIT_L(0); G_MMA(1, 0, At, B0); G_BAR; G_SCHED;
;             G_STAGE(G_SB(1, 1), b3 + hstepB, voffB);
	s_add_u32 s80, s84, 0x80000
	s_addc_u32 s81, s85, 0
	s_add_i32 s90, s17, s5
	v_lshl_add_u64 v[128:129], s[80:81], 0, v[148:149]
	s_mov_b32 m0, s90
	s_nop 0
	global_load_lds_dwordx4 v[128:129], off
	v_lshl_add_u64 v[128:129], s[80:81], 0, v[144:145]
	s_add_i32 m0, s90, 0x2000
	s_nop 0
	global_load_lds_dwordx4 v[128:129], off
	s_waitcnt vmcnt(6)
	s_barrier
	s_nop 0
	v_mfma_f32_16x16x32_bf16 v[108:111], v[208:211], v[164:167], v[108:111]
	v_mfma_f32_16x16x32_bf16 v[32:35], v[216:219], v[164:167], v[32:35]
	v_mfma_f32_16x16x32_bf16 v[100:103], v[208:211], v[172:175], v[100:103]
	v_mfma_f32_16x16x32_bf16 v[24:27], v[216:219], v[172:175], v[24:27]
	v_mfma_f32_16x16x32_bf16 v[92:95], v[208:211], v[180:183], v[92:95]
	v_mfma_f32_16x16x32_bf16 v[16:19], v[216:219], v[180:183], v[16:19]
	v_mfma_f32_16x16x32_bf16 v[64:67], v[208:211], v[196:199], v[64:67]
	v_mfma_f32_16x16x32_bf16 v[0:3], v[216:219], v[196:199], v[0:3]
	v_mfma_f32_16x16x32_bf16 v[108:111], v[212:215], v[168:171], v[108:111]
	v_mfma_f32_16x16x32_bf16 v[32:35], v[220:223], v[168:171], v[32:35]
	v_mfma_f32_16x16x32_bf16 v[100:103], v[212:215], v[176:179], v[100:103]
	v_mfma_f32_16x16x32_bf16 v[24:27], v[220:223], v[176:179], v[24:27]
	v_mfma_f32_16x16x32_bf16 v[92:95], v[212:215], v[192:195], v[92:95]
	v_mfma_f32_16x16x32_bf16 v[16:19], v[220:223], v[192:195], v[16:19]
	v_mfma_f32_16x16x32_bf16 v[64:67], v[212:215], v[204:207], v[64:67]
	v_mfma_f32_16x16x32_bf16 v[0:3], v[220:223], v[204:207], v[0:3]
	s_nop 0
	s_add_i32 s90, 0, 0x18000
	v_add_u32_e32 v140, s90, v185
	s_barrier
	ds_read_b128 v[128:131], v140
	ds_read_b128 v[132:135], v140 offset:1024
	ds_read_b128 v[136:139], v140 offset:2048
	ds_read_b128 v[140:143], v140 offset:3072
	s_add_u32 s80, s86, 0x4000
	s_addc_u32 s81, s87, 0
	s_mov_b32 m0, s31
	v_lshl_add_u64 v[208:209], s[80:81], 0, v[150:151]
	ds_read_b128 v[164:167], v188 offset:32768
	ds_read_b128 v[168:171], v188 offset:33792
	ds_read_b128 v[172:175], v188 offset:34816
	ds_read_b128 v[176:179], v188 offset:35840
	ds_read_b128 v[180:183], v188 offset:36864
	ds_read_b128 v[192:195], v188 offset:37888
	ds_read_b128 v[196:199], v188 offset:38912
	ds_read_b128 v[204:207], v188 offset:39936
	global_load_lds_dwordx4 v[208:209], off
	v_lshl_add_u64 v[208:209], s[80:81], 0, v[146:147]
	s_mov_b32 m0, s34
	s_nop 0
	global_load_lds_dwordx4 v[208:209], off
	s_waitcnt lgkmcnt(8)
	s_barrier
	s_waitcnt lgkmcnt(0)
	s_nop 0
	s_waitcnt lgkmcnt(0)
	v_mfma_f32_16x16x32_bf16 v[84:87], v[128:131], v[164:167], v[84:87]
	v_mfma_f32_16x16x32_bf16 v[12:15], v[136:139], v[164:167], v[12:15]
	v_mfma_f32_16x16x32_bf16 v[88:91], v[128:131], v[172:175], v[88:91]
	v_mfma_f32_16x16x32_bf16 v[60:63], v[136:139], v[172:175], v[60:63]
	v_mfma_f32_16x16x32_bf16 v[80:83], v[128:131], v[180:183], v[80:83]
	v_mfma_f32_16x16x32_bf16 v[52:55], v[136:139], v[180:183], v[52:55]
	v_mfma_f32_16x16x32_bf16 v[76:79], v[128:131], v[196:199], v[76:79]
	v_mfma_f32_16x16x32_bf16 v[44:47], v[136:139], v[196:199], v[44:47]
	v_mfma_f32_16x16x32_bf16 v[84:87], v[132:135], v[168:171], v[84:87]
	v_mfma_f32_16x16x32_bf16 v[12:15], v[140:143], v[168:171], v[12:15]
	v_mfma_f32_16x16x32_bf16 v[88:91], v[132:135], v[176:179], v[88:91]
	v_mfma_f32_16x16x32_bf16 v[60:63], v[140:143], v[176:179], v[60:63]
	v_mfma_f32_16x16x32_bf16 v[80:83], v[132:135], v[192:195], v[80:83]
	v_mfma_f32_16x16x32_bf16 v[52:55], v[140:143], v[192:195], v[52:55]
	v_mfma_f32_16x16x32_bf16 v[76:79], v[132:135], v[204:207], v[76:79]
	v_mfma_f32_16x16x32_bf16 v[44:47], v[140:143], v[204:207], v[44:47]
	s_nop 0
	s_barrier
	s_add_i32 s86, 0, 0x1c000
	s_add_i32 s80, s90, s5
	v_add_u32_e32 v191, s86, v185
	v_lshl_add_u64 v[200:201], v[200:201], 0, s[18:19]
	s_mov_b32 m0, s80
	ds_read_b128 v[208:211], v191
	ds_read_b128 v[212:215], v191 offset:1024
	ds_read_b128 v[216:219], v191 offset:2048
	ds_read_b128 v[220:223], v191 offset:3072
	global_load_lds_dwordx4 v[200:201], off
	v_lshl_add_u64 v[200:201], v[224:225], 0, s[18:19]
	s_add_i32 m0, s80, 0x2000
	s_nop 0
	global_load_lds_dwordx4 v[200:201], off
	s_barrier
	s_waitcnt lgkmcnt(0)
	s_nop 0
	s_waitcnt lgkmcnt(0)
	v_mfma_f32_16x16x32_bf16 v[72:75], v[208:211], v[164:167], v[72:75]
	v_mfma_f32_16x16x32_bf16 v[8:11], v[216:219], v[164:167], v[8:11]
	v_mfma_f32_16x16x32_bf16 v[124:127], v[208:211], v[172:175], v[124:127]
	v_mfma_f32_16x16x32_bf16 v[56:59], v[216:219], v[172:175], v[56:59]
	v_mfma_f32_16x16x32_bf16 v[120:123], v[208:211], v[180:183], v[120:123]
	v_mfma_f32_16x16x32_bf16 v[48:51], v[216:219], v[180:183], v[48:51]
	v_mfma_f32_16x16x32_bf16 v[116:119], v[208:211], v[196:199], v[116:119]
	v_mfma_f32_16x16x32_bf16 v[40:43], v[216:219], v[196:199], v[40:43]
	v_mfma_f32_16x16x32_bf16 v[72:75], v[212:215], v[168:171], v[72:75]
	v_mfma_f32_16x16x32_bf16 v[8:11], v[220:223], v[168:171], v[8:11]
	v_mfma_f32_16x16x32_bf16 v[124:127], v[212:215], v[176:179], v[124:127]
	v_mfma_f32_16x16x32_bf16 v[56:59], v[220:223], v[176:179], v[56:59]
	v_mfma_f32_16x16x32_bf16 v[120:123], v[212:215], v[192:195], v[120:123]
	v_mfma_f32_16x16x32_bf16 v[48:51], v[220:223], v[192:195], v[48:51]
	v_mfma_f32_16x16x32_bf16 v[116:119], v[212:215], v[204:207], v[116:119]
	v_mfma_f32_16x16x32_bf16 v[40:43], v[220:223], v[204:207], v[40:43]
	s_nop 0
	s_mov_b32 m0, s89
	v_lshl_add_u64 v[200:201], v[226:227], 0, s[18:19]
	s_barrier
	ds_read_b128 v[164:167], v188 offset:49152
	ds_read_b128 v[168:171], v188 offset:50176
	ds_read_b128 v[172:175], v188 offset:51200
	ds_read_b128 v[176:179], v188 offset:52224
	ds_read_b128 v[180:183], v188 offset:53248
	ds_read_b128 v[192:195], v188 offset:54272
	ds_read_b128 v[196:199], v188 offset:55296
	ds_read_b128 v[204:207], v188 offset:56320
	global_load_lds_dwordx4 v[200:201], off
	v_lshl_add_u64 v[200:201], v[228:229], 0, s[18:19]
	s_mov_b32 m0, s96
	s_nop 0
	global_load_lds_dwordx4 v[200:201], off
	s_barrier
; #define G_STAGE(bufoff, gbase, voff) do { _Pragma("unroll") for (int _i = 0; _i < 2; ++_i) \
;         __builtin_amdgcn_global_load_lds((const unsigned*)((const char*)(gbase) + (voff)[_i]), (LAS unsigned*)(lds + (bufoff) + ldsw + _i * 8192), 16, 0, 0); } while (0)
; #define G_MMA(ai, bj, At, Bt_) do { __builtin_amdgcn_s_setprio(1); _Pragma("unroll") for (int m = 0; m < 4; ++m) _Pragma("unroll") for (int n = 0; n < 2; ++n) _Pragma("unroll") for (int k = 0; k < 2; ++k) \
;         acc[ai][bj][m][n] = __builtin_amdgcn_mfma_f32_16x16x32_bf16(Bt_[n][k], At[m][k], acc[ai][bj][m][n], 0, 0, 0); __builtin_amdgcn_s_setprio(0); } while (0)
; #define G_WAIT_V(n) asm volatile("s_waitcnt vmcnt(" #n ")" ::: "memory")
; #define G_BAR __builtin_amdgcn_s_barrier()
; template <class Epi, bool PERMROWS = false>
; DI void gemm_phase(LAS unsigned char* lds, const bf16_t* A, int lda, const bf16_t* Bt, int K, const Sched& S, const Epi& E) {
;     ...
;             G_STAGE(G_SB(1, 1), b3 + hstepB, voffB);
;             G_WAIT_V(6); G_BAR; G_MMA(1, 1, At, B1); G_BAR;
;     DI void operator()(const f32x4 (&acc)[2][2][4][2], const Unit& u, int wr, int wc, int fr, int fq) const {
;         bf16_t* G = (bf16_t*)(ws + WS_G);
;         float* EA = (float*)(ws + WS_EDGE); float* EP = EA + (size_t)36 * 4 * DFF; float* EU = EP + (size_t)36 * 4 * DFF;
;         const int tok0 = (wr * 16 + fr) * 8;
;         const size_t row0 = (size_t)u.pm * BM + tok0;
;         const bool e_lo = (fr == 0), e_hi = (fr == 15);
; #pragma unroll
;         for (int n = 0; n < 2; ++n) {
;             const int col = u.pn * 128 + wc * 32 + n * 16 + 4 * fq;
;             const f32x4 w0 = *(const f32x4*)(cw + col), w1 = *(const f32x4*)(cw + DFF + col), w2 = *(const f32x4*)(cw + 2 * DFF + col), bb = *(const f32x4*)(cb + col);
;             f32x4 g[8];
;             f32x4 ed_a, ed_p, ed_u;
	s_waitcnt lgkmcnt(0)
	s_nop 0
	s_waitcnt lgkmcnt(0)
	v_mfma_f32_16x16x32_bf16 v[112:115], v[128:131], v[164:167], v[112:115]
	v_mfma_f32_16x16x32_bf16 v[36:39], v[136:139], v[164:167], v[36:39]
	v_mfma_f32_16x16x32_bf16 v[104:107], v[128:131], v[172:175], v[104:107]
	v_mfma_f32_16x16x32_bf16 v[28:31], v[136:139], v[172:175], v[28:31]
	v_mfma_f32_16x16x32_bf16 v[96:99], v[128:131], v[180:183], v[96:99]
	v_mfma_f32_16x16x32_bf16 v[20:23], v[136:139], v[180:183], v[20:23]
	v_mfma_f32_16x16x32_bf16 v[68:71], v[128:131], v[196:199], v[68:71]
	v_mfma_f32_16x16x32_bf16 v[4:7], v[136:139], v[196:199], v[4:7]
	v_mfma_f32_16x16x32_bf16 v[112:115], v[132:135], v[168:171], v[112:115]
	v_mfma_f32_16x16x32_bf16 v[36:39], v[140:143], v[168:171], v[36:39]
	v_mfma_f32_16x16x32_bf16 v[104:107], v[132:135], v[176:179], v[104:107]
	v_mfma_f32_16x16x32_bf16 v[28:31], v[140:143], v[176:179], v[28:31]
	v_mfma_f32_16x16x32_bf16 v[96:99], v[132:135], v[192:195], v[96:99]
	v_mfma_f32_16x16x32_bf16 v[20:23], v[140:143], v[192:195], v[20:23]
	v_mfma_f32_16x16x32_bf16 v[68:71], v[132:135], v[204:207], v[68:71]
	v_mfma_f32_16x16x32_bf16 v[4:7], v[140:143], v[204:207], v[4:7]
	s_nop 0
	s_barrier
	s_add_u32 s80, s84, 0x80080
	s_addc_u32 s81, s85, 0
	s_add_i32 s84, s86, s5
	v_lshl_add_u64 v[128:129], s[80:81], 0, v[148:149]
	s_mov_b32 m0, s84
	s_nop 0
	global_load_lds_dwordx4 v[128:129], off
	v_lshl_add_u64 v[128:129], s[80:81], 0, v[144:145]
	s_add_i32 m0, s84, 0x2000
	s_nop 0
	global_load_lds_dwordx4 v[128:129], off
	s_waitcnt vmcnt(6)
	s_barrier
	s_nop 0
	v_mfma_f32_16x16x32_bf16 v[108:111], v[208:211], v[164:167], v[108:111]
	v_mfma_f32_16x16x32_bf16 v[32:35], v[216:219], v[164:167], v[32:35]
	v_mfma_f32_16x16x32_bf16 v[100:103], v[208:211], v[172:175], v[100:103]
	v_mfma_f32_16x16x32_bf16 v[24:27], v[216:219], v[172:175], v[24:27]
	v_mfma_f32_16x16x32_bf16 v[92:95], v[208:211], v[180:183], v[92:95]
	v_mfma_f32_16x16x32_bf16 v[16:19], v[216:219], v[180:183], v[16:19]
	v_mfma_f32_16x16x32_bf16 v[64:67], v[208:211], v[196:199], v[64:67]
	v_mfma_f32_16x16x32_bf16 v[0:3], v[216:219], v[196:199], v[0:3]
	v_mfma_f32_16x16x32_bf16 v[108:111], v[212:215], v[168:171], v[108:111]
	v_mfma_f32_16x16x32_bf16 v[32:35], v[220:223], v[168:171], v[32:35]
	v_mfma_f32_16x16x32_bf16 v[100:103], v[212:215], v[176:179], v[100:103]
	v_mfma_f32_16x16x32_bf16 v[24:27], v[220:223], v[176:179], v[24:27]
	v_mfma_f32_16x16x32_bf16 v[92:95], v[212:215], v[192:195], v[92:95]
	v_mfma_f32_16x16x32_bf16 v[16:19], v[220:223], v[192:195], v[16:19]
	v_mfma_f32_16x16x32_bf16 v[64:67], v[212:215], v[204:207], v[64:67]
	v_mfma_f32_16x16x32_bf16 v[0:3], v[220:223], v[204:207], v[0:3]
	s_nop 0
	s_add_i32 s29, s29, 2
	s_add_u32 vcc_hi, vcc_hi, 0x100
	s_addc_u32 s28, s28, 0
	s_cmp_gt_u32 s29, 29
	s_mov_b64 s[80:81], s[82:83]
	s_barrier
	s_cbranch_scc0 .LBB0_1519
	s_mov_b32 s71, s91
	v_and_b32_e32 v131, 15, v202
	v_bfe_u32 v134, v202, 8, 1
	v_bfe_u32 v135, v202, 6, 2
	v_bfe_u32 v138, v202, 4, 2
	s_lshl_b32 s29, s43, 7
	v_lshlrev_b32_e32 v139, 5, v135
	v_lshl_add_u32 v139, v138, 2, v139
	v_add_u32_e32 v139, s29, v139
	v_lshlrev_b32_e32 v128, 2, v139
	v_lshl_add_u32 v140, v134, 4, v131
	v_mul_u32_u24_e32 v129, 0x16000, v140
	v_lshl_add_u32 v129, v139, 1, v129
	v_cmp_eq_u32_e64 s[84:85], 0, v131
	v_cmp_eq_u32_e64 s[86:87], 15, v131
	v_lshlrev_b32_e32 v130, 1, v134
	v_cndmask_b32_e64 v141, 0, 1, s[86:87]
	v_add_u32_e32 v130, v130, v141
	v_mul_u32_u24_e32 v130, 0x5800, v130
	v_add_u32_e32 v130, v130, v128
	v_mov_b32_e32 v132, 0xbfb8aa3b
	v_mov_b32_e32 v133, 0xbfb8aa3b
	s_mov_b64 s[82:83], s[38:39]
	global_load_dwordx4 v[204:207], v128, s[82:83] offset:0
	global_load_dwordx4 v[220:223], v128, s[82:83] offset:64
	s_add_u32 s82, s82, 0x5800
	s_addc_u32 s83, s83, 0
	global_load_dwordx4 v[208:211], v128, s[82:83] offset:0
	global_load_dwordx4 v[224:227], v128, s[82:83] offset:64
	s_add_u32 s82, s82, 0x5800
	s_addc_u32 s83, s83, 0
	global_load_dwordx4 v[212:215], v128, s[82:83] offset:0
	global_load_dwordx4 v[228:231], v128, s[82:83] offset:64
	global_load_dwordx4 v[216:219], v128, s[40:41] offset:0
	global_load_dwordx4 v[232:235], v128, s[40:41] offset:64
	s_mul_i32 s29, s78, 0x2c0000
	s_mul_i32 s32, s78, 0x16000
	s_waitcnt vmcnt(0)
; DI float silu(float v) { return v * __builtin_amdgcn_rcpf(1.f + __builtin_amdgcn_exp2f(-1.4426950408889634f * v)); }
; DI void st_bf16x4(bf16_t* p, f32x4 v) { u32x2 w; w.x = cvt_pk_bf16(v[0], v[1]); w.y = cvt_pk_bf16(v[2], v[3]); *(u32x2*)p = w; }
;     DI void operator()(const f32x4 (&acc)[2][2][4][2], const Unit& u, int wr, int wc, int fr, int fq) const {
;         bf16_t* G = (bf16_t*)(ws + WS_G);
;         float* EA = (float*)(ws + WS_EDGE); float* EP = EA + (size_t)36 * 4 * DFF; float* EU = EP + (size_t)36 * 4 * DFF;
;         const int tok0 = (wr * 16 + fr) * 8;
;         const size_t row0 = (size_t)u.pm * BM + tok0;
;         const bool e_lo = (fr == 0), e_hi = (fr == 15);
; #pragma unroll
;         for (int n = 0; n < 2; ++n) {
;             const int col = u.pn * 128 + wc * 32 + n * 16 + 4 * fq;
;             const f32x4 w0 = *(const f32x4*)(cw + col), w1 = *(const f32x4*)(cw + DFF + col), w2 = *(const f32x4*)(cw + 2 * DFF + col), bb = *(const f32x4*)(cb + col);
;             f32x4 g[8];
;             f32x4 ed_a, ed_p, ed_u;
; #pragma unroll
;             for (int j = 0; j < 4; ++j) {
;                 float a[8], uu[8];
; #pragma unroll
;                 for (int k = 0; k < 8; ++k) { a[k] = acc[k >> 2][0][k & 3][n][j]; uu[k] = acc[k >> 2][1][k & 3][n][j]; }
;                 const float aprev = __shfl_up(a[7], 1), anext = __shfl_down(a[0], 1);
; #pragma unroll
;                 for (int k = 0; k < 8; ++k) {
;                     const float c = bb[j] + w0[j] * (k > 0 ? a[k - 1] : aprev) + w1[j] * a[k] + w2[j] * (k < 7 ? a[k + 1] : anext);
;                     g[k][j] = silu(c) * uu[k];
;                 }
;                 if (e_lo) { ed_a[j] = a[0]; ed_p[j] = bb[j] + w1[j] * a[0] + w2[j] * a[1]; ed_u[j] = uu[0]; }
;                 if (e_hi) { ed_a[j] = a[7]; ed_p[j] = bb[j] + w0[j] * a[6] + w1[j] * a[7]; ed_u[j] = uu[7]; }
;             }
; #pragma unroll
;             for (int k = 0; k < 8; ++k) {
;                 if ((k == 0 && e_lo) || (k == 7 && e_hi)) continue;
;                 st_bf16x4(G + (row0 + k) * DFF + col, g[k]);
;             }
;             if (e_lo || e_hi) {
;                 const size_t eo = ((size_t)u.pm * 4 + wr * 2 + (e_hi ? 1 : 0)) * DFF + col;
;                 *(f32x4*)(EA + eo) = ed_a; *(f32x4*)(EP + eo) = ed_p; *(f32x4*)(EU + eo) = ed_u;
	v_mov_b32_dpp v164, v68 row_shr:1 row_mask:0xf bank_mask:0xf bound_ctrl:0
	v_mov_b32_dpp v165, v69 row_shr:1 row_mask:0xf bank_mask:0xf bound_ctrl:0
	v_mov_b32_dpp v166, v70 row_shr:1 row_mask:0xf bank_mask:0xf bound_ctrl:0
	v_mov_b32_dpp v167, v71 row_shr:1 row_mask:0xf bank_mask:0xf bound_ctrl:0
	v_mov_b32_dpp v168, v84 row_shl:1 row_mask:0xf bank_mask:0xf bound_ctrl:0
	v_mov_b32_dpp v169, v85 row_shl:1 row_mask:0xf bank_mask:0xf bound_ctrl:0
	v_mov_b32_dpp v170, v86 row_shl:1 row_mask:0xf bank_mask:0xf bound_ctrl:0
	v_mov_b32_dpp v171, v87 row_shl:1 row_mask:0xf bank_mask:0xf bound_ctrl:0
	s_mov_b64 exec, s[84:85]
	v_pk_fma_f32 v[172:173], v[208:209], v[84:85], v[216:217]
	v_pk_fma_f32 v[172:173], v[212:213], v[88:89], v[172:173]
	v_pk_fma_f32 v[174:175], v[210:211], v[86:87], v[218:219]
	v_pk_fma_f32 v[174:175], v[214:215], v[90:91], v[174:175]
	s_add_u32 s82, s50, 0x113a0000
	s_addc_u32 s83, s51, 0
	s_add_u32 s82, s82, s32
	s_addc_u32 s83, s83, 0
	global_store_dwordx4 v130, v[84:87], s[82:83] offset:0
	s_add_u32 s82, s82, 0x318000
	s_addc_u32 s83, s83, 0
	global_store_dwordx4 v130, v[172:175], s[82:83] offset:0
	s_add_u32 s82, s82, 0x318000
	s_addc_u32 s83, s83, 0
	global_store_dwordx4 v130, v[72:75], s[82:83] offset:0
	s_nop 1
	s_mov_b64 exec, s[86:87]
	v_pk_fma_f32 v[172:173], v[204:205], v[96:97], v[216:217]
	v_pk_fma_f32 v[172:173], v[208:209], v[68:69], v[172:173]
	v_pk_fma_f32 v[174:175], v[206:207], v[98:99], v[218:219]
	v_pk_fma_f32 v[174:175], v[210:211], v[70:71], v[174:175]
	s_add_u32 s82, s50, 0x113a0000
	s_addc_u32 s83, s51, 0
	s_add_u32 s82, s82, s32
	s_addc_u32 s83, s83, 0
	global_store_dwordx4 v130, v[68:71], s[82:83] offset:0
	s_add_u32 s82, s82, 0x318000
	s_addc_u32 s83, s83, 0
	global_store_dwordx4 v130, v[172:175], s[82:83] offset:0
	s_add_u32 s82, s82, 0x318000
	s_addc_u32 s83, s83, 0
	global_store_dwordx4 v130, v[64:67], s[82:83] offset:0
	s_nop 1
	s_mov_b64 exec, -1
	s_add_u32 s80, s50, 0x1d9a0000
	s_addc_u32 s81, s51, 0
	s_add_u32 s80, s80, s29
	s_addc_u32 s81, s81, 0
	v_pk_fma_f32 v[236:237], v[204:205], v[164:165], v[216:217]
	v_pk_fma_f32 v[236:237], v[208:209], v[84:85], v[236:237]
	v_pk_fma_f32 v[236:237], v[212:213], v[88:89], v[236:237]
	v_pk_fma_f32 v[238:239], v[206:207], v[166:167], v[218:219]
	v_pk_fma_f32 v[238:239], v[210:211], v[86:87], v[238:239]
	v_pk_fma_f32 v[238:239], v[214:215], v[90:91], v[238:239]
	v_pk_mul_f32 v[244:245], v[236:237], v[132:133]
	v_pk_mul_f32 v[246:247], v[238:239], v[132:133]
	v_exp_f32_e32 v244, v244
	v_exp_f32_e32 v245, v245
	v_exp_f32_e32 v246, v246
	v_exp_f32_e32 v247, v247
	v_pk_add_f32 v[244:245], v[244:245], 1.0 op_sel_hi:[1,0]
	v_pk_add_f32 v[246:247], v[246:247], 1.0 op_sel_hi:[1,0]
	v_rcp_f32_e32 v244, v244
	v_rcp_f32_e32 v245, v245
	v_rcp_f32_e32 v246, v246
	v_rcp_f32_e32 v247, v247
	v_pk_mul_f32 v[236:237], v[236:237], v[244:245]
	v_pk_mul_f32 v[238:239], v[238:239], v[246:247]
	v_pk_mul_f32 v[72:73], v[72:73], v[236:237]
	v_pk_mul_f32 v[74:75], v[74:75], v[238:239]
	v_cvt_pk_bf16_f32 v72, v72, v73
	v_cvt_pk_bf16_f32 v73, v74, v75
	s_andn2_b64 exec, exec, s[84:85]
	global_store_dwordx2 v129, v[72:73], s[80:81] offset:0
	s_mov_b64 exec, -1
	s_add_u32 s80, s80, 0x2c00
	s_addc_u32 s81, s81, 0
	v_pk_fma_f32 v[236:237], v[204:205], v[84:85], v[216:217]
	v_pk_fma_f32 v[236:237], v[208:209], v[88:89], v[236:237]
	v_pk_fma_f32 v[236:237], v[212:213], v[80:81], v[236:237]
	v_pk_fma_f32 v[238:239], v[206:207], v[86:87], v[218:219]
	v_pk_fma_f32 v[238:239], v[210:211], v[90:91], v[238:239]
	v_pk_fma_f32 v[238:239], v[214:215], v[82:83], v[238:239]
	v_pk_mul_f32 v[244:245], v[236:237], v[132:133]
	v_pk_mul_f32 v[246:247], v[238:239], v[132:133]
	v_exp_f32_e32 v244, v244
	v_exp_f32_e32 v245, v245
	v_exp_f32_e32 v246, v246
	v_exp_f32_e32 v247, v247
	v_pk_add_f32 v[244:245], v[244:245], 1.0 op_sel_hi:[1,0]
	v_pk_add_f32 v[246:247], v[246:247], 1.0 op_sel_hi:[1,0]
	v_rcp_f32_e32 v244, v244
	v_rcp_f32_e32 v245, v245
	v_rcp_f32_e32 v246, v246
	v_rcp_f32_e32 v247, v247
	v_pk_mul_f32 v[236:237], v[236:237], v[244:245]
	v_pk_mul_f32 v[238:239], v[238:239], v[246:247]
	v_pk_mul_f32 v[124:125], v[124:125], v[236:237]
	v_pk_mul_f32 v[126:127], v[126:127], v[238:239]
	v_cvt_pk_bf16_f32 v124, v124, v125
	v_cvt_pk_bf16_f32 v125, v126, v127
	global_store_dwordx2 v129, v[124:125], s[80:81] offset:0
	s_add_u32 s80, s80, 0x2c00
	s_addc_u32 s81, s81, 0
	v_pk_fma_f32 v[236:237], v[204:205], v[88:89], v[216:217]
	v_pk_fma_f32 v[236:237], v[208:209], v[80:81], v[236:237]
	v_pk_fma_f32 v[236:237], v[212:213], v[76:77], v[236:237]
	v_pk_fma_f32 v[238:239], v[206:207], v[90:91], v[218:219]
	v_pk_fma_f32 v[238:239], v[210:211], v[82:83], v[238:239]
	v_pk_fma_f32 v[238:239], v[214:215], v[78:79], v[238:239]
	v_pk_mul_f32 v[244:245], v[236:237], v[132:133]
	v_pk_mul_f32 v[246:247], v[238:239], v[132:133]
	v_exp_f32_e32 v244, v244
	v_exp_f32_e32 v245, v245
	v_exp_f32_e32 v246, v246
	v_exp_f32_e32 v247, v247
	v_pk_add_f32 v[244:245], v[244:245], 1.0 op_sel_hi:[1,0]
	v_pk_add_f32 v[246:247], v[246:247], 1.0 op_sel_hi:[1,0]
	v_rcp_f32_e32 v244, v244
	v_rcp_f32_e32 v245, v245
	v_rcp_f32_e32 v246, v246
	v_rcp_f32_e32 v247, v247
	v_pk_mul_f32 v[236:237], v[236:237], v[244:245]
	v_pk_mul_f32 v[238:239], v[238:239], v[246:247]
	v_pk_mul_f32 v[120:121], v[120:121], v[236:237]
	v_pk_mul_f32 v[122:123], v[122:123], v[238:239]
	v_cvt_pk_bf16_f32 v120, v120, v121
	v_cvt_pk_bf16_f32 v121, v122, v123
	global_store_dwordx2 v129, v[120:121], s[80:81] offset:0
	s_add_u32 s80, s80, 0x2c00
	s_addc_u32 s81, s81, 0
	v_pk_fma_f32 v[236:237], v[204:205], v[80:81], v[216:217]
	v_pk_fma_f32 v[236:237], v[208:209], v[76:77], v[236:237]
; DI float silu(float v) { return v * __builtin_amdgcn_rcpf(1.f + __builtin_amdgcn_exp2f(-1.4426950408889634f * v)); }
; DI void st_bf16x4(bf16_t* p, f32x4 v) { u32x2 w; w.x = cvt_pk_bf16(v[0], v[1]); w.y = cvt_pk_bf16(v[2], v[3]); *(u32x2*)p = w; }
;     DI void operator()(const f32x4 (&acc)[2][2][4][2], const Unit& u, int wr, int wc, int fr, int fq) const {
;     ...
;                 for (int k = 0; k < 8; ++k) { a[k] = acc[k >> 2][0][k & 3][n][j]; uu[k] = acc[k >> 2][1][k & 3][n][j]; }
;                 const float aprev = __shfl_up(a[7], 1), anext = __shfl_down(a[0], 1);
; #pragma unroll
;                 for (int k = 0; k < 8; ++k) {
;                     const float c = bb[j] + w0[j] * (k > 0 ? a[k - 1] : aprev) + w1[j] * a[k] + w2[j] * (k < 7 ? a[k + 1] : anext);
;                     g[k][j] = silu(c) * uu[k];
;                 }
;                 if (e_lo) { ed_a[j] = a[0]; ed_p[j] = bb[j] + w1[j] * a[0] + w2[j] * a[1]; ed_u[j] = uu[0]; }
;                 if (e_hi) { ed_a[j] = a[7]; ed_p[j] = bb[j] + w0[j] * a[6] + w1[j] * a[7]; ed_u[j] = uu[7]; }
;             }
; #pragma unroll
;             for (int k = 0; k < 8; ++k) {
;                 if ((k == 0 && e_lo) || (k == 7 && e_hi)) continue;
;                 st_bf16x4(G + (row0 + k) * DFF + col, g[k]);
	v_pk_fma_f32 v[236:237], v[212:213], v[112:113], v[236:237]
	v_pk_fma_f32 v[238:239], v[206:207], v[82:83], v[218:219]
	v_pk_fma_f32 v[238:239], v[210:211], v[78:79], v[238:239]
	v_pk_fma_f32 v[238:239], v[214:215], v[114:115], v[238:239]
	v_pk_mul_f32 v[244:245], v[236:237], v[132:133]
	v_pk_mul_f32 v[246:247], v[238:239], v[132:133]
	v_exp_f32_e32 v244, v244
	v_exp_f32_e32 v245, v245
	v_exp_f32_e32 v246, v246
	v_exp_f32_e32 v247, v247
	v_pk_add_f32 v[244:245], v[244:245], 1.0 op_sel_hi:[1,0]
	v_pk_add_f32 v[246:247], v[246:247], 1.0 op_sel_hi:[1,0]
	v_rcp_f32_e32 v244, v244
	v_rcp_f32_e32 v245, v245
	v_rcp_f32_e32 v246, v246
	v_rcp_f32_e32 v247, v247
	v_pk_mul_f32 v[236:237], v[236:237], v[244:245]
	v_pk_mul_f32 v[238:239], v[238:239], v[246:247]
	v_pk_mul_f32 v[116:117], v[116:117], v[236:237]
	v_pk_mul_f32 v[118:119], v[118:119], v[238:239]
	v_cvt_pk_bf16_f32 v116, v116, v117
	v_cvt_pk_bf16_f32 v117, v118, v119
	global_store_dwordx2 v129, v[116:117], s[80:81] offset:0
	s_add_u32 s80, s80, 0x2c00
	s_addc_u32 s81, s81, 0
	v_pk_fma_f32 v[236:237], v[204:205], v[76:77], v[216:217]
	v_pk_fma_f32 v[236:237], v[208:209], v[112:113], v[236:237]
	v_pk_fma_f32 v[236:237], v[212:213], v[104:105], v[236:237]
	v_pk_fma_f32 v[238:239], v[206:207], v[78:79], v[218:219]
	v_pk_fma_f32 v[238:239], v[210:211], v[114:115], v[238:239]
	v_pk_fma_f32 v[238:239], v[214:215], v[106:107], v[238:239]
	v_pk_mul_f32 v[244:245], v[236:237], v[132:133]
	v_pk_mul_f32 v[246:247], v[238:239], v[132:133]
	v_exp_f32_e32 v244, v244
	v_exp_f32_e32 v245, v245
	v_exp_f32_e32 v246, v246
	v_exp_f32_e32 v247, v247
	v_pk_add_f32 v[244:245], v[244:245], 1.0 op_sel_hi:[1,0]
	v_pk_add_f32 v[246:247], v[246:247], 1.0 op_sel_hi:[1,0]
	v_rcp_f32_e32 v244, v244
	v_rcp_f32_e32 v245, v245
	v_rcp_f32_e32 v246, v246
	v_rcp_f32_e32 v247, v247
	v_pk_mul_f32 v[236:237], v[236:237], v[244:245]
	v_pk_mul_f32 v[238:239], v[238:239], v[246:247]
	v_pk_mul_f32 v[108:109], v[108:109], v[236:237]
	v_pk_mul_f32 v[110:111], v[110:111], v[238:239]
	v_cvt_pk_bf16_f32 v108, v108, v109
	v_cvt_pk_bf16_f32 v109, v110, v111
	global_store_dwordx2 v129, v[108:109], s[80:81] offset:0
	s_add_u32 s80, s80, 0x2c00
	s_addc_u32 s81, s81, 0
	v_pk_fma_f32 v[236:237], v[204:205], v[112:113], v[216:217]
	v_pk_fma_f32 v[236:237], v[208:209], v[104:105], v[236:237]
	v_pk_fma_f32 v[236:237], v[212:213], v[96:97], v[236:237]
	v_pk_fma_f32 v[238:239], v[206:207], v[114:115], v[218:219]
	v_pk_fma_f32 v[238:239], v[210:211], v[106:107], v[238:239]
	v_pk_fma_f32 v[238:239], v[214:215], v[98:99], v[238:239]
	v_pk_mul_f32 v[244:245], v[236:237], v[132:133]
	v_pk_mul_f32 v[246:247], v[238:239], v[132:133]
	v_exp_f32_e32 v244, v244
	v_exp_f32_e32 v245, v245
	v_exp_f32_e32 v246, v246
	v_exp_f32_e32 v247, v247
	v_pk_add_f32 v[244:245], v[244:245], 1.0 op_sel_hi:[1,0]
	v_pk_add_f32 v[246:247], v[246:247], 1.0 op_sel_hi:[1,0]
	v_rcp_f32_e32 v244, v244
	v_rcp_f32_e32 v245, v245
	v_rcp_f32_e32 v246, v246
	v_rcp_f32_e32 v247, v247
	v_pk_mul_f32 v[236:237], v[236:237], v[244:245]
	v_pk_mul_f32 v[238:239], v[238:239], v[246:247]
	v_pk_mul_f32 v[100:101], v[100:101], v[236:237]
	v_pk_mul_f32 v[102:103], v[102:103], v[238:239]
	v_cvt_pk_bf16_f32 v100, v100, v101
	v_cvt_pk_bf16_f32 v101, v102, v103
	global_store_dwordx2 v129, v[100:101], s[80:81] offset:0
	s_add_u32 s80, s80, 0x2c00
	s_addc_u32 s81, s81, 0
	v_pk_fma_f32 v[236:237], v[204:205], v[104:105], v[216:217]
	v_pk_fma_f32 v[236:237], v[208:209], v[96:97], v[236:237]
	v_pk_fma_f32 v[236:237], v[212:213], v[68:69], v[236:237]
	v_pk_fma_f32 v[238:239], v[206:207], v[106:107], v[218:219]
	v_pk_fma_f32 v[238:239], v[210:211], v[98:99], v[238:239]
	v_pk_fma_f32 v[238:239], v[214:215], v[70:71], v[238:239]
	v_pk_mul_f32 v[244:245], v[236:237], v[132:133]
	v_pk_mul_f32 v[246:247], v[238:239], v[132:133]
	v_exp_f32_e32 v244, v244
	v_exp_f32_e32 v245, v245
	v_exp_f32_e32 v246, v246
	v_exp_f32_e32 v247, v247
	v_pk_add_f32 v[244:245], v[244:245], 1.0 op_sel_hi:[1,0]
	v_pk_add_f32 v[246:247], v[246:247], 1.0 op_sel_hi:[1,0]
	v_rcp_f32_e32 v244, v244
	v_rcp_f32_e32 v245, v245
	v_rcp_f32_e32 v246, v246
	v_rcp_f32_e32 v247, v247
	v_pk_mul_f32 v[236:237], v[236:237], v[244:245]
	v_pk_mul_f32 v[238:239], v[238:239], v[246:247]
	v_pk_mul_f32 v[92:93], v[92:93], v[236:237]
	v_pk_mul_f32 v[94:95], v[94:95], v[238:239]
	v_cvt_pk_bf16_f32 v92, v92, v93
	v_cvt_pk_bf16_f32 v93, v94, v95
	global_store_dwordx2 v129, v[92:93], s[80:81] offset:0
	s_add_u32 s80, s80, 0x2c00
	s_addc_u32 s81, s81, 0
	v_pk_fma_f32 v[236:237], v[204:205], v[96:97], v[216:217]
	v_pk_fma_f32 v[236:237], v[208:209], v[68:69], v[236:237]
	v_pk_fma_f32 v[236:237], v[212:213], v[168:169], v[236:237]
	v_pk_fma_f32 v[238:239], v[206:207], v[98:99], v[218:219]
	v_pk_fma_f32 v[238:239], v[210:211], v[70:71], v[238:239]
	v_pk_fma_f32 v[238:239], v[214:215], v[170:171], v[238:239]
	v_pk_mul_f32 v[244:245], v[236:237], v[132:133]
	v_pk_mul_f32 v[246:247], v[238:239], v[132:133]
	v_exp_f32_e32 v244, v244
	v_exp_f32_e32 v245, v245
	v_exp_f32_e32 v246, v246
	v_exp_f32_e32 v247, v247
	v_pk_add_f32 v[244:245], v[244:245], 1.0 op_sel_hi:[1,0]
	v_pk_add_f32 v[246:247], v[246:247], 1.0 op_sel_hi:[1,0]
	v_rcp_f32_e32 v244, v244
	v_rcp_f32_e32 v245, v245
	v_rcp_f32_e32 v246, v246
	v_rcp_f32_e32 v247, v247
	v_pk_mul_f32 v[236:237], v[236:237], v[244:245]
	v_pk_mul_f32 v[238:239], v[238:239], v[246:247]
	v_pk_mul_f32 v[64:65], v[64:65], v[236:237]
	v_pk_mul_f32 v[66:67], v[66:67], v[238:239]
	v_cvt_pk_bf16_f32 v64, v64, v65
	v_cvt_pk_bf16_f32 v65, v66, v67
	s_andn2_b64 exec, exec, s[86:87]
	global_store_dwordx2 v129, v[64:65], s[80:81] offset:0
; DI float silu(float v) { return v * __builtin_amdgcn_rcpf(1.f + __builtin_amdgcn_exp2f(-1.4426950408889634f * v)); }
; DI void st_bf16x4(bf16_t* p, f32x4 v) { u32x2 w; w.x = cvt_pk_bf16(v[0], v[1]); w.y = cvt_pk_bf16(v[2], v[3]); *(u32x2*)p = w; }
;     DI void operator()(const f32x4 (&acc)[2][2][4][2], const Unit& u, int wr, int wc, int fr, int fq) const {
;     ...
;         for (int n = 0; n < 2; ++n) {
;             const int col = u.pn * 128 + wc * 32 + n * 16 + 4 * fq;
;             const f32x4 w0 = *(const f32x4*)(cw + col), w1 = *(const f32x4*)(cw + DFF + col), w2 = *(const f32x4*)(cw + 2 * DFF + col), bb = *(const f32x4*)(cb + col);
;             f32x4 g[8];
;             f32x4 ed_a, ed_p, ed_u;
; #pragma unroll
;             for (int j = 0; j < 4; ++j) {
;                 float a[8], uu[8];
; #pragma unroll
;                 for (int k = 0; k < 8; ++k) { a[k] = acc[k >> 2][0][k & 3][n][j]; uu[k] = acc[k >> 2][1][k & 3][n][j]; }
;                 const float aprev = __shfl_up(a[7], 1), anext = __shfl_down(a[0], 1);
; #pragma unroll
;                 for (int k = 0; k < 8; ++k) {
;                     const float c = bb[j] + w0[j] * (k > 0 ? a[k - 1] : aprev) + w1[j] * a[k] + w2[j] * (k < 7 ? a[k + 1] : anext);
;                     g[k][j] = silu(c) * uu[k];
;                 }
;                 if (e_lo) { ed_a[j] = a[0]; ed_p[j] = bb[j] + w1[j] * a[0] + w2[j] * a[1]; ed_u[j] = uu[0]; }
;                 if (e_hi) { ed_a[j] = a[7]; ed_p[j] = bb[j] + w0[j] * a[6] + w1[j] * a[7]; ed_u[j] = uu[7]; }
;             }
; #pragma unroll
;             for (int k = 0; k < 8; ++k) {
;                 if ((k == 0 && e_lo) || (k == 7 && e_hi)) continue;
;                 st_bf16x4(G + (row0 + k) * DFF + col, g[k]);
;             }
;             if (e_lo || e_hi) {
;                 const size_t eo = ((size_t)u.pm * 4 + wr * 2 + (e_hi ? 1 : 0)) * DFF + col;
;                 *(f32x4*)(EA + eo) = ed_a; *(f32x4*)(EP + eo) = ed_p; *(f32x4*)(EU + eo) = ed_u;
	s_mov_b64 exec, -1
	v_mov_b32_dpp v164, v4 row_shr:1 row_mask:0xf bank_mask:0xf bound_ctrl:0
	v_mov_b32_dpp v165, v5 row_shr:1 row_mask:0xf bank_mask:0xf bound_ctrl:0
	v_mov_b32_dpp v166, v6 row_shr:1 row_mask:0xf bank_mask:0xf bound_ctrl:0
	v_mov_b32_dpp v167, v7 row_shr:1 row_mask:0xf bank_mask:0xf bound_ctrl:0
	v_mov_b32_dpp v168, v12 row_shl:1 row_mask:0xf bank_mask:0xf bound_ctrl:0
	v_mov_b32_dpp v169, v13 row_shl:1 row_mask:0xf bank_mask:0xf bound_ctrl:0
	v_mov_b32_dpp v170, v14 row_shl:1 row_mask:0xf bank_mask:0xf bound_ctrl:0
	v_mov_b32_dpp v171, v15 row_shl:1 row_mask:0xf bank_mask:0xf bound_ctrl:0
	s_mov_b64 exec, s[84:85]
	v_pk_fma_f32 v[172:173], v[224:225], v[12:13], v[232:233]
	v_pk_fma_f32 v[172:173], v[228:229], v[60:61], v[172:173]
	v_pk_fma_f32 v[174:175], v[226:227], v[14:15], v[234:235]
	v_pk_fma_f32 v[174:175], v[230:231], v[62:63], v[174:175]
	s_add_u32 s82, s50, 0x113a0000
	s_addc_u32 s83, s51, 0
	s_add_u32 s82, s82, s32
	s_addc_u32 s83, s83, 0
	global_store_dwordx4 v130, v[12:15], s[82:83] offset:64
	s_add_u32 s82, s82, 0x318000
	s_addc_u32 s83, s83, 0
	global_store_dwordx4 v130, v[172:175], s[82:83] offset:64
	s_add_u32 s82, s82, 0x318000
	s_addc_u32 s83, s83, 0
	global_store_dwordx4 v130, v[8:11], s[82:83] offset:64
	s_nop 1
	s_mov_b64 exec, s[86:87]
	v_pk_fma_f32 v[172:173], v[220:221], v[20:21], v[232:233]
	v_pk_fma_f32 v[172:173], v[224:225], v[4:5], v[172:173]
	v_pk_fma_f32 v[174:175], v[222:223], v[22:23], v[234:235]
	v_pk_fma_f32 v[174:175], v[226:227], v[6:7], v[174:175]
	s_add_u32 s82, s50, 0x113a0000
	s_addc_u32 s83, s51, 0
	s_add_u32 s82, s82, s32
	s_addc_u32 s83, s83, 0
	global_store_dwordx4 v130, v[4:7], s[82:83] offset:64
	s_add_u32 s82, s82, 0x318000
	s_addc_u32 s83, s83, 0
	global_store_dwordx4 v130, v[172:175], s[82:83] offset:64
	s_add_u32 s82, s82, 0x318000
	s_addc_u32 s83, s83, 0
	global_store_dwordx4 v130, v[0:3], s[82:83] offset:64
	s_nop 1
	s_mov_b64 exec, -1
	s_add_u32 s80, s50, 0x1d9a0000
	s_addc_u32 s81, s51, 0
	s_add_u32 s80, s80, s29
	s_addc_u32 s81, s81, 0
	v_pk_fma_f32 v[236:237], v[220:221], v[164:165], v[232:233]
	v_pk_fma_f32 v[236:237], v[224:225], v[12:13], v[236:237]
	v_pk_fma_f32 v[236:237], v[228:229], v[60:61], v[236:237]
	v_pk_fma_f32 v[238:239], v[222:223], v[166:167], v[234:235]
	v_pk_fma_f32 v[238:239], v[226:227], v[14:15], v[238:239]
	v_pk_fma_f32 v[238:239], v[230:231], v[62:63], v[238:239]
	v_pk_mul_f32 v[244:245], v[236:237], v[132:133]
	v_pk_mul_f32 v[246:247], v[238:239], v[132:133]
	v_exp_f32_e32 v244, v244
	v_exp_f32_e32 v245, v245
	v_exp_f32_e32 v246, v246
	v_exp_f32_e32 v247, v247
	v_pk_add_f32 v[244:245], v[244:245], 1.0 op_sel_hi:[1,0]
	v_pk_add_f32 v[246:247], v[246:247], 1.0 op_sel_hi:[1,0]
	v_rcp_f32_e32 v244, v244
	v_rcp_f32_e32 v245, v245
	v_rcp_f32_e32 v246, v246
	v_rcp_f32_e32 v247, v247
	v_pk_mul_f32 v[236:237], v[236:237], v[244:245]
	v_pk_mul_f32 v[238:239], v[238:239], v[246:247]
	v_pk_mul_f32 v[8:9], v[8:9], v[236:237]
	v_pk_mul_f32 v[10:11], v[10:11], v[238:239]
	v_cvt_pk_bf16_f32 v8, v8, v9
	v_cvt_pk_bf16_f32 v9, v10, v11
	s_andn2_b64 exec, exec, s[84:85]
	global_store_dwordx2 v129, v[8:9], s[80:81] offset:32
	s_mov_b64 exec, -1
	s_add_u32 s80, s80, 0x2c00
	s_addc_u32 s81, s81, 0
	v_pk_fma_f32 v[236:237], v[220:221], v[12:13], v[232:233]
	v_pk_fma_f32 v[236:237], v[224:225], v[60:61], v[236:237]
	v_pk_fma_f32 v[236:237], v[228:229], v[52:53], v[236:237]
	v_pk_fma_f32 v[238:239], v[222:223], v[14:15], v[234:235]
	v_pk_fma_f32 v[238:239], v[226:227], v[62:63], v[238:239]
	v_pk_fma_f32 v[238:239], v[230:231], v[54:55], v[238:239]
	v_pk_mul_f32 v[244:245], v[236:237], v[132:133]
	v_pk_mul_f32 v[246:247], v[238:239], v[132:133]
	v_exp_f32_e32 v244, v244
	v_exp_f32_e32 v245, v245
	v_exp_f32_e32 v246, v246
	v_exp_f32_e32 v247, v247
	v_pk_add_f32 v[244:245], v[244:245], 1.0 op_sel_hi:[1,0]
	v_pk_add_f32 v[246:247], v[246:247], 1.0 op_sel_hi:[1,0]
	v_rcp_f32_e32 v244, v244
	v_rcp_f32_e32 v245, v245
	v_rcp_f32_e32 v246, v246
	v_rcp_f32_e32 v247, v247
	v_pk_mul_f32 v[236:237], v[236:237], v[244:245]
	v_pk_mul_f32 v[238:239], v[238:239], v[246:247]
	v_pk_mul_f32 v[56:57], v[56:57], v[236:237]
	v_pk_mul_f32 v[58:59], v[58:59], v[238:239]
	v_cvt_pk_bf16_f32 v56, v56, v57
	v_cvt_pk_bf16_f32 v57, v58, v59
	global_store_dwordx2 v129, v[56:57], s[80:81] offset:32
	s_add_u32 s80, s80, 0x2c00
	s_addc_u32 s81, s81, 0
	v_pk_fma_f32 v[236:237], v[220:221], v[60:61], v[232:233]
	v_pk_fma_f32 v[236:237], v[224:225], v[52:53], v[236:237]
	v_pk_fma_f32 v[236:237], v[228:229], v[44:45], v[236:237]
	v_pk_fma_f32 v[238:239], v[222:223], v[62:63], v[234:235]
	v_pk_fma_f32 v[238:239], v[226:227], v[54:55], v[238:239]
	v_pk_fma_f32 v[238:239], v[230:231], v[46:47], v[238:239]
	v_pk_mul_f32 v[244:245], v[236:237], v[132:133]
	v_pk_mul_f32 v[246:247], v[238:239], v[132:133]
	v_exp_f32_e32 v244, v244
	v_exp_f32_e32 v245, v245
	v_exp_f32_e32 v246, v246
	v_exp_f32_e32 v247, v247
	v_pk_add_f32 v[244:245], v[244:245], 1.0 op_sel_hi:[1,0]
	v_pk_add_f32 v[246:247], v[246:247], 1.0 op_sel_hi:[1,0]
	v_rcp_f32_e32 v244, v244
	v_rcp_f32_e32 v245, v245
	v_rcp_f32_e32 v246, v246
	v_rcp_f32_e32 v247, v247
	v_pk_mul_f32 v[236:237], v[236:237], v[244:245]
	v_pk_mul_f32 v[238:239], v[238:239], v[246:247]
	v_pk_mul_f32 v[48:49], v[48:49], v[236:237]
	v_pk_mul_f32 v[50:51], v[50:51], v[238:239]
	v_cvt_pk_bf16_f32 v48, v48, v49
	v_cvt_pk_bf16_f32 v49, v50, v51
	global_store_dwordx2 v129, v[48:49], s[80:81] offset:32
	s_add_u32 s80, s80, 0x2c00
	s_addc_u32 s81, s81, 0
	v_pk_fma_f32 v[236:237], v[220:221], v[52:53], v[232:233]
	v_pk_fma_f32 v[236:237], v[224:225], v[44:45], v[236:237]
; DI float silu(float v) { return v * __builtin_amdgcn_rcpf(1.f + __builtin_amdgcn_exp2f(-1.4426950408889634f * v)); }
; DI void st_bf16x4(bf16_t* p, f32x4 v) { u32x2 w; w.x = cvt_pk_bf16(v[0], v[1]); w.y = cvt_pk_bf16(v[2], v[3]); *(u32x2*)p = w; }
;     DI void operator()(const f32x4 (&acc)[2][2][4][2], const Unit& u, int wr, int wc, int fr, int fq) const {
;     ...
;                 for (int k = 0; k < 8; ++k) { a[k] = acc[k >> 2][0][k & 3][n][j]; uu[k] = acc[k >> 2][1][k & 3][n][j]; }
;                 const float aprev = __shfl_up(a[7], 1), anext = __shfl_down(a[0], 1);
; #pragma unroll
;                 for (int k = 0; k < 8; ++k) {
;                     const float c = bb[j] + w0[j] * (k > 0 ? a[k - 1] : aprev) + w1[j] * a[k] + w2[j] * (k < 7 ? a[k + 1] : anext);
;                     g[k][j] = silu(c) * uu[k];
;                 }
;                 if (e_lo) { ed_a[j] = a[0]; ed_p[j] = bb[j] + w1[j] * a[0] + w2[j] * a[1]; ed_u[j] = uu[0]; }
;                 if (e_hi) { ed_a[j] = a[7]; ed_p[j] = bb[j] + w0[j] * a[6] + w1[j] * a[7]; ed_u[j] = uu[7]; }
;             }
; #pragma unroll
;             for (int k = 0; k < 8; ++k) {
;                 if ((k == 0 && e_lo) || (k == 7 && e_hi)) continue;
;                 st_bf16x4(G + (row0 + k) * DFF + col, g[k]);
	v_pk_fma_f32 v[236:237], v[228:229], v[36:37], v[236:237]
	v_pk_fma_f32 v[238:239], v[222:223], v[54:55], v[234:235]
	v_pk_fma_f32 v[238:239], v[226:227], v[46:47], v[238:239]
	v_pk_fma_f32 v[238:239], v[230:231], v[38:39], v[238:239]
	v_pk_mul_f32 v[244:245], v[236:237], v[132:133]
	v_pk_mul_f32 v[246:247], v[238:239], v[132:133]
	v_exp_f32_e32 v244, v244
	v_exp_f32_e32 v245, v245
	v_exp_f32_e32 v246, v246
	v_exp_f32_e32 v247, v247
	v_pk_add_f32 v[244:245], v[244:245], 1.0 op_sel_hi:[1,0]
	v_pk_add_f32 v[246:247], v[246:247], 1.0 op_sel_hi:[1,0]
	v_rcp_f32_e32 v244, v244
	v_rcp_f32_e32 v245, v245
	v_rcp_f32_e32 v246, v246
	v_rcp_f32_e32 v247, v247
	v_pk_mul_f32 v[236:237], v[236:237], v[244:245]
	v_pk_mul_f32 v[238:239], v[238:239], v[246:247]
	v_pk_mul_f32 v[40:41], v[40:41], v[236:237]
	v_pk_mul_f32 v[42:43], v[42:43], v[238:239]
	v_cvt_pk_bf16_f32 v40, v40, v41
	v_cvt_pk_bf16_f32 v41, v42, v43
	global_store_dwordx2 v129, v[40:41], s[80:81] offset:32
	s_add_u32 s80, s80, 0x2c00
	s_addc_u32 s81, s81, 0
	v_pk_fma_f32 v[236:237], v[220:221], v[44:45], v[232:233]
	v_pk_fma_f32 v[236:237], v[224:225], v[36:37], v[236:237]
	v_pk_fma_f32 v[236:237], v[228:229], v[28:29], v[236:237]
	v_pk_fma_f32 v[238:239], v[222:223], v[46:47], v[234:235]
	v_pk_fma_f32 v[238:239], v[226:227], v[38:39], v[238:239]
	v_pk_fma_f32 v[238:239], v[230:231], v[30:31], v[238:239]
	v_pk_mul_f32 v[244:245], v[236:237], v[132:133]
	v_pk_mul_f32 v[246:247], v[238:239], v[132:133]
	v_exp_f32_e32 v244, v244
	v_exp_f32_e32 v245, v245
	v_exp_f32_e32 v246, v246
	v_exp_f32_e32 v247, v247
	v_pk_add_f32 v[244:245], v[244:245], 1.0 op_sel_hi:[1,0]
	v_pk_add_f32 v[246:247], v[246:247], 1.0 op_sel_hi:[1,0]
	v_rcp_f32_e32 v244, v244
	v_rcp_f32_e32 v245, v245
	v_rcp_f32_e32 v246, v246
	v_rcp_f32_e32 v247, v247
	v_pk_mul_f32 v[236:237], v[236:237], v[244:245]
	v_pk_mul_f32 v[238:239], v[238:239], v[246:247]
	v_pk_mul_f32 v[32:33], v[32:33], v[236:237]
	v_pk_mul_f32 v[34:35], v[34:35], v[238:239]
	v_cvt_pk_bf16_f32 v32, v32, v33
	v_cvt_pk_bf16_f32 v33, v34, v35
	global_store_dwordx2 v129, v[32:33], s[80:81] offset:32
	s_add_u32 s80, s80, 0x2c00
	s_addc_u32 s81, s81, 0
	v_pk_fma_f32 v[236:237], v[220:221], v[36:37], v[232:233]
	v_pk_fma_f32 v[236:237], v[224:225], v[28:29], v[236:237]
	v_pk_fma_f32 v[236:237], v[228:229], v[20:21], v[236:237]
	v_pk_fma_f32 v[238:239], v[222:223], v[38:39], v[234:235]
	v_pk_fma_f32 v[238:239], v[226:227], v[30:31], v[238:239]
	v_pk_fma_f32 v[238:239], v[230:231], v[22:23], v[238:239]
	v_pk_mul_f32 v[244:245], v[236:237], v[132:133]
	v_pk_mul_f32 v[246:247], v[238:239], v[132:133]
	v_exp_f32_e32 v244, v244
	v_exp_f32_e32 v245, v245
	v_exp_f32_e32 v246, v246
	v_exp_f32_e32 v247, v247
	v_pk_add_f32 v[244:245], v[244:245], 1.0 op_sel_hi:[1,0]
	v_pk_add_f32 v[246:247], v[246:247], 1.0 op_sel_hi:[1,0]
	v_rcp_f32_e32 v244, v244
	v_rcp_f32_e32 v245, v245
	v_rcp_f32_e32 v246, v246
	v_rcp_f32_e32 v247, v247
	v_pk_mul_f32 v[236:237], v[236:237], v[244:245]
	v_pk_mul_f32 v[238:239], v[238:239], v[246:247]
	v_pk_mul_f32 v[24:25], v[24:25], v[236:237]
	v_pk_mul_f32 v[26:27], v[26:27], v[238:239]
	v_cvt_pk_bf16_f32 v24, v24, v25
	v_cvt_pk_bf16_f32 v25, v26, v27
	global_store_dwordx2 v129, v[24:25], s[80:81] offset:32
	s_add_u32 s80, s80, 0x2c00
	s_addc_u32 s81, s81, 0
	v_pk_fma_f32 v[236:237], v[220:221], v[28:29], v[232:233]
	v_pk_fma_f32 v[236:237], v[224:225], v[20:21], v[236:237]
	v_pk_fma_f32 v[236:237], v[228:229], v[4:5], v[236:237]
	v_pk_fma_f32 v[238:239], v[222:223], v[30:31], v[234:235]
	v_pk_fma_f32 v[238:239], v[226:227], v[22:23], v[238:239]
	v_pk_fma_f32 v[238:239], v[230:231], v[6:7], v[238:239]
	v_pk_mul_f32 v[244:245], v[236:237], v[132:133]
	v_pk_mul_f32 v[246:247], v[238:239], v[132:133]
	v_exp_f32_e32 v244, v244
	v_exp_f32_e32 v245, v245
	v_exp_f32_e32 v246, v246
	v_exp_f32_e32 v247, v247
	v_pk_add_f32 v[244:245], v[244:245], 1.0 op_sel_hi:[1,0]
	v_pk_add_f32 v[246:247], v[246:247], 1.0 op_sel_hi:[1,0]
	v_rcp_f32_e32 v244, v244
	v_rcp_f32_e32 v245, v245
	v_rcp_f32_e32 v246, v246
	v_rcp_f32_e32 v247, v247
	v_pk_mul_f32 v[236:237], v[236:237], v[244:245]
	v_pk_mul_f32 v[238:239], v[238:239], v[246:247]
	v_pk_mul_f32 v[16:17], v[16:17], v[236:237]
	v_pk_mul_f32 v[18:19], v[18:19], v[238:239]
	v_cvt_pk_bf16_f32 v16, v16, v17
	v_cvt_pk_bf16_f32 v17, v18, v19
	global_store_dwordx2 v129, v[16:17], s[80:81] offset:32
	s_add_u32 s80, s80, 0x2c00
	s_addc_u32 s81, s81, 0
	v_pk_fma_f32 v[236:237], v[220:221], v[20:21], v[232:233]
	v_pk_fma_f32 v[236:237], v[224:225], v[4:5], v[236:237]
	v_pk_fma_f32 v[236:237], v[228:229], v[168:169], v[236:237]
	v_pk_fma_f32 v[238:239], v[222:223], v[22:23], v[234:235]
	v_pk_fma_f32 v[238:239], v[226:227], v[6:7], v[238:239]
	v_pk_fma_f32 v[238:239], v[230:231], v[170:171], v[238:239]
	v_pk_mul_f32 v[244:245], v[236:237], v[132:133]
	v_pk_mul_f32 v[246:247], v[238:239], v[132:133]
	v_exp_f32_e32 v244, v244
	v_exp_f32_e32 v245, v245
	v_exp_f32_e32 v246, v246
	v_exp_f32_e32 v247, v247
	v_pk_add_f32 v[244:245], v[244:245], 1.0 op_sel_hi:[1,0]
	v_pk_add_f32 v[246:247], v[246:247], 1.0 op_sel_hi:[1,0]
	v_rcp_f32_e32 v244, v244
	v_rcp_f32_e32 v245, v245
	v_rcp_f32_e32 v246, v246
	v_rcp_f32_e32 v247, v247
	v_pk_mul_f32 v[236:237], v[236:237], v[244:245]
	v_pk_mul_f32 v[238:239], v[238:239], v[246:247]
	v_pk_mul_f32 v[0:1], v[0:1], v[236:237]
	v_pk_mul_f32 v[2:3], v[2:3], v[238:239]
	v_cvt_pk_bf16_f32 v0, v0, v1
	v_cvt_pk_bf16_f32 v1, v2, v3
	s_andn2_b64 exec, exec, s[86:87]
	global_store_dwordx2 v129, v[0:1], s[80:81] offset:32
	s_mov_b64 exec, -1
	s_mov_b64 s[78:79], exec
	s_branch .LBB0_1515

; #define G_STAGE(bufoff, gbase, voff) do { _Pragma("unroll") for (int _i = 0; _i < 2; ++_i) \
;         __builtin_amdgcn_global_load_lds((const unsigned*)((const char*)(gbase) + (voff)[_i]), (LAS unsigned*)(lds + (bufoff) + ldsw + _i * 8192), 16, 0, 0); } while (0)
; #define G_LDA(dst, b, h) do { _Pragma("unroll") for (int m = 0; m < 4; ++m) _Pragma("unroll") for (int k = 0; k < 2; ++k) dst[m][k] = *(const LAS bf16x8*)(lds + G_SA(b, h) + aoff + m * 2048 + k * 1024); } while (0)
; #define G_LDB(dst, b, h) do { _Pragma("unroll") for (int n = 0; n < 2; ++n) _Pragma("unroll") for (int k = 0; k < 2; ++k) dst[n][k] = *(const LAS bf16x8*)(lds + G_SB(b, h) + boff + n * 2048 + k * 1024); } while (0)
; #define G_MMA(ai, bj, At, Bt_) do { __builtin_amdgcn_s_setprio(1); _Pragma("unroll") for (int m = 0; m < 4; ++m) _Pragma("unroll") for (int n = 0; n < 2; ++n) _Pragma("unroll") for (int k = 0; k < 2; ++k) \
;         acc[ai][bj][m][n] = __builtin_amdgcn_mfma_f32_16x16x32_bf16(Bt_[n][k], At[m][k], acc[ai][bj][m][n], 0, 0, 0); __builtin_amdgcn_s_setprio(0); } while (0)
; #define G_WAIT_L(n) asm volatile("s_waitcnt lgkmcnt(" #n ")" ::: "memory")
; #define G_BAR __builtin_amdgcn_s_barrier()
; #define G_SCHED __builtin_amdgcn_sched_barrier(0)
; template <class Epi, bool PERMROWS = false>
; DI void gemm_phase(LAS unsigned char* lds, const bf16_t* A, int lda, const bf16_t* Bt, int K, const Sched& S, const Epi& E) {
;     ...
;         for (int t = 0; t < nt; t += 2) {
;             const bool last = (t == nt - 2);
;             const char* a1 = cA + (size_t)(t + 1) * kstep;
;             const char* a2 = last ? nA : cA + (size_t)(t + 2) * kstep; const char* b2 = last ? nB : cB + (size_t)(t + 2) * kstep;
;             const char* a3 = a2 + kstep; const char* b3 = b2 + kstep;
;             G_LDB(B0, 0, 0); G_SCHED; G_LDA(At, 0, 0); G_STAGE(G_SA(1, 1), a1 + hstepA, voffA);
;             G_WAIT_L(8); G_BAR; G_WAIT_L(0); G_MMA(0, 0, At, B0); G_BAR; G_SCHED;
;             G_LDB(B1, 0, 1); G_STAGE(G_SB(0, 0), b2, voffB);
;             G_BAR; G_WAIT_L(0); G_MMA(0, 1, At, B1); G_BAR;
;             G_LDA(At, 0, 1); G_STAGE(G_SA(0, 0), a2, voffA);
;             G_BAR; G_WAIT_L(0); G_MMA(1, 0, At, B0); G_BAR; G_SCHED;
.LBB0_1981:
	s_waitcnt lgkmcnt(0)
	ds_read_b128 v[150:153], v174
	ds_read_b128 v[154:157], v174 offset:1024
	ds_read_b128 v[158:161], v174 offset:2048
	ds_read_b128 v[162:165], v174 offset:3072
	s_add_u32 s14, s12, 0xfff80080
	s_addc_u32 s15, s13, -1
	s_cmp_eq_u32 s43, 28
	s_cselect_b32 s77, s11, s15
	s_cselect_b32 s76, s20, s14
	s_cselect_b32 s15, s21, s42
	s_cselect_b32 s14, s22, s27
	v_lshl_add_u64 v[208:209], s[12:13], 0, v[144:145]
	s_add_i32 m0, s86, 0xc000
	ds_read_b128 v[166:169], v175
	ds_read_b128 v[178:181], v175 offset:1024
	ds_read_b128 v[182:185], v175 offset:2048
	ds_read_b128 v[186:189], v175 offset:3072
	ds_read_b128 v[190:193], v175 offset:4096
	ds_read_b128 v[194:197], v175 offset:5120
	ds_read_b128 v[198:201], v175 offset:6144
	ds_read_b128 v[204:207], v175 offset:7168
	global_load_lds_dwordx4 v[208:209], off
	v_lshl_add_u64 v[208:209], s[12:13], 0, v[142:143]
	s_add_i32 m0, s86, 0xe000
	s_nop 0
	global_load_lds_dwordx4 v[208:209], off
	s_waitcnt lgkmcnt(8)
	s_barrier
	s_waitcnt lgkmcnt(0)
	s_nop 0
	s_waitcnt lgkmcnt(0)
	v_mfma_f32_16x16x32_bf16 v[124:127], v[150:153], v[166:169], v[124:127]
	v_mfma_f32_16x16x32_bf16 v[120:123], v[158:161], v[166:169], v[120:123]
	v_mfma_f32_16x16x32_bf16 v[108:111], v[150:153], v[182:185], v[108:111]
	v_mfma_f32_16x16x32_bf16 v[104:107], v[158:161], v[182:185], v[104:107]
	v_mfma_f32_16x16x32_bf16 v[92:95], v[150:153], v[190:193], v[92:95]
	v_mfma_f32_16x16x32_bf16 v[88:91], v[158:161], v[190:193], v[88:91]
	v_mfma_f32_16x16x32_bf16 v[76:79], v[150:153], v[198:201], v[76:79]
	v_mfma_f32_16x16x32_bf16 v[72:75], v[158:161], v[198:201], v[72:75]
	v_mfma_f32_16x16x32_bf16 v[124:127], v[154:157], v[178:181], v[124:127]
	v_mfma_f32_16x16x32_bf16 v[120:123], v[162:165], v[178:181], v[120:123]
	v_mfma_f32_16x16x32_bf16 v[108:111], v[154:157], v[186:189], v[108:111]
	v_mfma_f32_16x16x32_bf16 v[104:107], v[162:165], v[186:189], v[104:107]
	v_mfma_f32_16x16x32_bf16 v[92:95], v[154:157], v[194:197], v[92:95]
	v_mfma_f32_16x16x32_bf16 v[88:91], v[162:165], v[194:197], v[88:91]
	v_mfma_f32_16x16x32_bf16 v[76:79], v[154:157], v[204:207], v[76:79]
	v_mfma_f32_16x16x32_bf16 v[72:75], v[162:165], v[204:207], v[72:75]
	s_nop 0
	s_barrier
	s_add_i32 s28, s6, s83
	v_lshl_add_u64 v[224:225], s[14:15], 0, v[128:129]
	s_mov_b32 m0, s28
	ds_read_b128 v[208:211], v176
	ds_read_b128 v[212:215], v176 offset:1024
	ds_read_b128 v[216:219], v176 offset:2048
	ds_read_b128 v[220:223], v176 offset:3072
	global_load_lds_dwordx4 v[224:225], off
	v_lshl_add_u64 v[226:227], s[14:15], 0, v[130:131]
	s_add_i32 m0, s28, 0x2000
	s_nop 0
	global_load_lds_dwordx4 v[226:227], off
	s_barrier
	s_waitcnt lgkmcnt(0)
	s_nop 0
	s_waitcnt lgkmcnt(0)
	v_mfma_f32_16x16x32_bf16 v[116:119], v[208:211], v[166:169], v[116:119]
	v_mfma_f32_16x16x32_bf16 v[112:115], v[216:219], v[166:169], v[112:115]
	v_mfma_f32_16x16x32_bf16 v[100:103], v[208:211], v[182:185], v[100:103]
	v_mfma_f32_16x16x32_bf16 v[96:99], v[216:219], v[182:185], v[96:99]
	v_mfma_f32_16x16x32_bf16 v[84:87], v[208:211], v[190:193], v[84:87]
	v_mfma_f32_16x16x32_bf16 v[80:83], v[216:219], v[190:193], v[80:83]
	v_mfma_f32_16x16x32_bf16 v[68:71], v[208:211], v[198:201], v[68:71]
	v_mfma_f32_16x16x32_bf16 v[64:67], v[216:219], v[198:201], v[64:67]
	v_mfma_f32_16x16x32_bf16 v[116:119], v[212:215], v[178:181], v[116:119]
	v_mfma_f32_16x16x32_bf16 v[112:115], v[220:223], v[178:181], v[112:115]
	v_mfma_f32_16x16x32_bf16 v[100:103], v[212:215], v[186:189], v[100:103]
	v_mfma_f32_16x16x32_bf16 v[96:99], v[220:223], v[186:189], v[96:99]
	v_mfma_f32_16x16x32_bf16 v[84:87], v[212:215], v[194:197], v[84:87]
	v_mfma_f32_16x16x32_bf16 v[80:83], v[220:223], v[194:197], v[80:83]
	v_mfma_f32_16x16x32_bf16 v[68:71], v[212:215], v[204:207], v[68:71]
	v_mfma_f32_16x16x32_bf16 v[64:67], v[220:223], v[204:207], v[64:67]
	s_nop 0
	s_mov_b32 m0, s86
	v_lshl_add_u64 v[228:229], s[76:77], 0, v[128:129]
	s_barrier
	ds_read_b128 v[166:169], v175 offset:16384
	ds_read_b128 v[178:181], v175 offset:17408
	ds_read_b128 v[182:185], v175 offset:18432
	ds_read_b128 v[186:189], v175 offset:19456
	ds_read_b128 v[190:193], v175 offset:20480
	ds_read_b128 v[194:197], v175 offset:21504
	ds_read_b128 v[198:201], v175 offset:22528
	ds_read_b128 v[204:207], v175 offset:23552
	global_load_lds_dwordx4 v[228:229], off
	v_lshl_add_u64 v[230:231], s[76:77], 0, v[130:131]
	s_mov_b32 m0, s87
	s_nop 0
	global_load_lds_dwordx4 v[230:231], off
	s_barrier
	s_waitcnt lgkmcnt(0)
	s_nop 0
	s_waitcnt lgkmcnt(0)
	v_mfma_f32_16x16x32_bf16 v[60:63], v[150:153], v[166:169], v[60:63]
	v_mfma_f32_16x16x32_bf16 v[56:59], v[158:161], v[166:169], v[56:59]
	v_mfma_f32_16x16x32_bf16 v[44:47], v[150:153], v[182:185], v[44:47]
	v_mfma_f32_16x16x32_bf16 v[40:43], v[158:161], v[182:185], v[40:43]
	v_mfma_f32_16x16x32_bf16 v[28:31], v[150:153], v[190:193], v[28:31]
	v_mfma_f32_16x16x32_bf16 v[24:27], v[158:161], v[190:193], v[24:27]
	v_mfma_f32_16x16x32_bf16 v[12:15], v[150:153], v[198:201], v[12:15]
	v_mfma_f32_16x16x32_bf16 v[8:11], v[158:161], v[198:201], v[8:11]
	v_mfma_f32_16x16x32_bf16 v[60:63], v[154:157], v[178:181], v[60:63]
	v_mfma_f32_16x16x32_bf16 v[56:59], v[162:165], v[178:181], v[56:59]
	v_mfma_f32_16x16x32_bf16 v[44:47], v[154:157], v[186:189], v[44:47]
	v_mfma_f32_16x16x32_bf16 v[40:43], v[162:165], v[186:189], v[40:43]
	v_mfma_f32_16x16x32_bf16 v[28:31], v[154:157], v[194:197], v[28:31]
	v_mfma_f32_16x16x32_bf16 v[24:27], v[162:165], v[194:197], v[24:27]
	v_mfma_f32_16x16x32_bf16 v[12:15], v[154:157], v[204:207], v[12:15]
	v_mfma_f32_16x16x32_bf16 v[8:11], v[162:165], v[204:207], v[8:11]
	s_nop 0
	s_barrier
; #define G_STAGE(bufoff, gbase, voff) do { _Pragma("unroll") for (int _i = 0; _i < 2; ++_i) \
;         __builtin_amdgcn_global_load_lds((const unsigned*)((const char*)(gbase) + (voff)[_i]), (LAS unsigned*)(lds + (bufoff) + ldsw + _i * 8192), 16, 0, 0); } while (0)
; #define G_LDA(dst, b, h) do { _Pragma("unroll") for (int m = 0; m < 4; ++m) _Pragma("unroll") for (int k = 0; k < 2; ++k) dst[m][k] = *(const LAS bf16x8*)(lds + G_SA(b, h) + aoff + m * 2048 + k * 1024); } while (0)
; #define G_LDB(dst, b, h) do { _Pragma("unroll") for (int n = 0; n < 2; ++n) _Pragma("unroll") for (int k = 0; k < 2; ++k) dst[n][k] = *(const LAS bf16x8*)(lds + G_SB(b, h) + boff + n * 2048 + k * 1024); } while (0)
; #define G_MMA(ai, bj, At, Bt_) do { __builtin_amdgcn_s_setprio(1); _Pragma("unroll") for (int m = 0; m < 4; ++m) _Pragma("unroll") for (int n = 0; n < 2; ++n) _Pragma("unroll") for (int k = 0; k < 2; ++k) \
;         acc[ai][bj][m][n] = __builtin_amdgcn_mfma_f32_16x16x32_bf16(Bt_[n][k], At[m][k], acc[ai][bj][m][n], 0, 0, 0); __builtin_amdgcn_s_setprio(0); } while (0)
; #define G_WAIT_V(n) asm volatile("s_waitcnt vmcnt(" #n ")" ::: "memory")
; #define G_WAIT_L(n) asm volatile("s_waitcnt lgkmcnt(" #n ")" ::: "memory")
; #define G_BAR __builtin_amdgcn_s_barrier()
; #define G_SCHED __builtin_amdgcn_sched_barrier(0)
; template <class Epi, bool PERMROWS = false>
; DI void gemm_phase(LAS unsigned char* lds, const bf16_t* A, int lda, const bf16_t* Bt, int K, const Sched& S, const Epi& E) {
;     ...
;             G_STAGE(G_SB(0, 1), b2 + hstepB, voffB);
;             G_WAIT_V(6); G_BAR; G_MMA(1, 1, At, B1); G_BAR;
;             G_LDB(B0, 1, 0); G_SCHED; G_LDA(At, 1, 0); G_STAGE(G_SA(0, 1), a2 + hstepA, voffA);
;             G_WAIT_L(8); G_BAR; G_WAIT_L(0); G_MMA(0, 0, At, B0); G_BAR; G_SCHED;
;             G_LDB(B1, 1, 1); G_STAGE(G_SB(1, 0), b3, voffB);
;             G_BAR; G_WAIT_L(0); G_MMA(0, 1, At, B1); G_BAR;
	s_add_u32 s28, s14, 0x80000
	s_addc_u32 s29, s15, 0
	s_add_i32 s54, s7, s83
	v_lshl_add_u64 v[150:151], s[28:29], 0, v[128:129]
	s_mov_b32 m0, s54
	s_nop 0
	global_load_lds_dwordx4 v[150:151], off
	v_lshl_add_u64 v[150:151], s[28:29], 0, v[130:131]
	s_add_i32 m0, s54, 0x2000
	s_nop 0
	global_load_lds_dwordx4 v[150:151], off
	s_waitcnt vmcnt(6)
	s_barrier
	s_nop 0
	v_mfma_f32_16x16x32_bf16 v[52:55], v[208:211], v[166:169], v[52:55]
	v_mfma_f32_16x16x32_bf16 v[48:51], v[216:219], v[166:169], v[48:51]
	v_mfma_f32_16x16x32_bf16 v[36:39], v[208:211], v[182:185], v[36:39]
	v_mfma_f32_16x16x32_bf16 v[32:35], v[216:219], v[182:185], v[32:35]
	v_mfma_f32_16x16x32_bf16 v[20:23], v[208:211], v[190:193], v[20:23]
	v_mfma_f32_16x16x32_bf16 v[16:19], v[216:219], v[190:193], v[16:19]
	v_mfma_f32_16x16x32_bf16 v[4:7], v[208:211], v[198:201], v[4:7]
	v_mfma_f32_16x16x32_bf16 v[0:3], v[216:219], v[198:201], v[0:3]
	v_mfma_f32_16x16x32_bf16 v[52:55], v[212:215], v[178:181], v[52:55]
	v_mfma_f32_16x16x32_bf16 v[48:51], v[220:223], v[178:181], v[48:51]
	v_mfma_f32_16x16x32_bf16 v[36:39], v[212:215], v[186:189], v[36:39]
	v_mfma_f32_16x16x32_bf16 v[32:35], v[220:223], v[186:189], v[32:35]
	v_mfma_f32_16x16x32_bf16 v[20:23], v[212:215], v[194:197], v[20:23]
	v_mfma_f32_16x16x32_bf16 v[16:19], v[220:223], v[194:197], v[16:19]
	v_mfma_f32_16x16x32_bf16 v[4:7], v[212:215], v[204:207], v[4:7]
	v_mfma_f32_16x16x32_bf16 v[0:3], v[220:223], v[204:207], v[0:3]
	s_nop 0
	s_add_i32 s54, 0, 0x18000
	v_add_u32_e32 v132, s54, v170
	s_barrier
	ds_read_b128 v[150:153], v132
	ds_read_b128 v[154:157], v132 offset:1024
	ds_read_b128 v[158:161], v132 offset:2048
	ds_read_b128 v[162:165], v132 offset:3072
	s_add_u32 s28, s76, 0x80000
	s_addc_u32 s29, s77, 0
	s_mov_b32 m0, s94
	v_lshl_add_u64 v[208:209], s[28:29], 0, v[128:129]
	ds_read_b128 v[166:169], v175 offset:32768
	ds_read_b128 v[178:181], v175 offset:33792
	ds_read_b128 v[182:185], v175 offset:34816
	ds_read_b128 v[186:189], v175 offset:35840
	ds_read_b128 v[190:193], v175 offset:36864
	ds_read_b128 v[194:197], v175 offset:37888
	ds_read_b128 v[198:201], v175 offset:38912
	ds_read_b128 v[204:207], v175 offset:39936
	global_load_lds_dwordx4 v[208:209], off
	v_lshl_add_u64 v[208:209], s[28:29], 0, v[130:131]
	s_mov_b32 m0, s95
	s_nop 0
	global_load_lds_dwordx4 v[208:209], off
	s_waitcnt lgkmcnt(8)
	s_barrier
	s_waitcnt lgkmcnt(0)
	s_nop 0
	s_waitcnt lgkmcnt(0)
	v_mfma_f32_16x16x32_bf16 v[124:127], v[150:153], v[166:169], v[124:127]
	v_mfma_f32_16x16x32_bf16 v[120:123], v[158:161], v[166:169], v[120:123]
	v_mfma_f32_16x16x32_bf16 v[108:111], v[150:153], v[182:185], v[108:111]
	v_mfma_f32_16x16x32_bf16 v[104:107], v[158:161], v[182:185], v[104:107]
	v_mfma_f32_16x16x32_bf16 v[92:95], v[150:153], v[190:193], v[92:95]
	v_mfma_f32_16x16x32_bf16 v[88:91], v[158:161], v[190:193], v[88:91]
	v_mfma_f32_16x16x32_bf16 v[76:79], v[150:153], v[198:201], v[76:79]
	v_mfma_f32_16x16x32_bf16 v[72:75], v[158:161], v[198:201], v[72:75]
	v_mfma_f32_16x16x32_bf16 v[124:127], v[154:157], v[178:181], v[124:127]
	v_mfma_f32_16x16x32_bf16 v[120:123], v[162:165], v[178:181], v[120:123]
	v_mfma_f32_16x16x32_bf16 v[108:111], v[154:157], v[186:189], v[108:111]
	v_mfma_f32_16x16x32_bf16 v[104:107], v[162:165], v[186:189], v[104:107]
	v_mfma_f32_16x16x32_bf16 v[92:95], v[154:157], v[194:197], v[92:95]
	v_mfma_f32_16x16x32_bf16 v[88:91], v[162:165], v[194:197], v[88:91]
	v_mfma_f32_16x16x32_bf16 v[76:79], v[154:157], v[204:207], v[76:79]
	v_mfma_f32_16x16x32_bf16 v[72:75], v[162:165], v[204:207], v[72:75]
	s_nop 0
	s_barrier
	s_add_i32 s28, 0, 0x1c000
	s_add_i32 s29, s54, s83
	v_add_u32_e32 v132, s28, v170
	v_lshl_add_u64 v[224:225], v[224:225], 0, s[16:17]
	s_mov_b32 m0, s29
	ds_read_b128 v[208:211], v132
	ds_read_b128 v[212:215], v132 offset:1024
	ds_read_b128 v[216:219], v132 offset:2048
	ds_read_b128 v[220:223], v132 offset:3072
	global_load_lds_dwordx4 v[224:225], off
	v_lshl_add_u64 v[224:225], v[226:227], 0, s[16:17]
	s_add_i32 m0, s29, 0x2000
	s_nop 0
	global_load_lds_dwordx4 v[224:225], off
	s_barrier
	s_waitcnt lgkmcnt(0)
	s_nop 0
	s_waitcnt lgkmcnt(0)
	v_mfma_f32_16x16x32_bf16 v[116:119], v[208:211], v[166:169], v[116:119]
	v_mfma_f32_16x16x32_bf16 v[112:115], v[216:219], v[166:169], v[112:115]
	v_mfma_f32_16x16x32_bf16 v[100:103], v[208:211], v[182:185], v[100:103]
	v_mfma_f32_16x16x32_bf16 v[96:99], v[216:219], v[182:185], v[96:99]
	v_mfma_f32_16x16x32_bf16 v[84:87], v[208:211], v[190:193], v[84:87]
	v_mfma_f32_16x16x32_bf16 v[80:83], v[216:219], v[190:193], v[80:83]
	v_mfma_f32_16x16x32_bf16 v[68:71], v[208:211], v[198:201], v[68:71]
	v_mfma_f32_16x16x32_bf16 v[64:67], v[216:219], v[198:201], v[64:67]
	v_mfma_f32_16x16x32_bf16 v[116:119], v[212:215], v[178:181], v[116:119]
	v_mfma_f32_16x16x32_bf16 v[112:115], v[220:223], v[178:181], v[112:115]
	v_mfma_f32_16x16x32_bf16 v[100:103], v[212:215], v[186:189], v[100:103]
	v_mfma_f32_16x16x32_bf16 v[96:99], v[220:223], v[186:189], v[96:99]
	v_mfma_f32_16x16x32_bf16 v[84:87], v[212:215], v[194:197], v[84:87]
	v_mfma_f32_16x16x32_bf16 v[80:83], v[220:223], v[194:197], v[80:83]
	v_mfma_f32_16x16x32_bf16 v[68:71], v[212:215], v[204:207], v[68:71]
	v_mfma_f32_16x16x32_bf16 v[64:67], v[220:223], v[204:207], v[64:67]
	s_nop 0
	s_mov_b32 m0, s97
	v_lshl_add_u64 v[224:225], v[228:229], 0, s[16:17]
	s_barrier
; #define G_STAGE(bufoff, gbase, voff) do { _Pragma("unroll") for (int _i = 0; _i < 2; ++_i) \
;         __builtin_amdgcn_global_load_lds((const unsigned*)((const char*)(gbase) + (voff)[_i]), (LAS unsigned*)(lds + (bufoff) + ldsw + _i * 8192), 16, 0, 0); } while (0)
; #define G_LDA(dst, b, h) do { _Pragma("unroll") for (int m = 0; m < 4; ++m) _Pragma("unroll") for (int k = 0; k < 2; ++k) dst[m][k] = *(const LAS bf16x8*)(lds + G_SA(b, h) + aoff + m * 2048 + k * 1024); } while (0)
; #define G_MMA(ai, bj, At, Bt_) do { __builtin_amdgcn_s_setprio(1); _Pragma("unroll") for (int m = 0; m < 4; ++m) _Pragma("unroll") for (int n = 0; n < 2; ++n) _Pragma("unroll") for (int k = 0; k < 2; ++k) \
;         acc[ai][bj][m][n] = __builtin_amdgcn_mfma_f32_16x16x32_bf16(Bt_[n][k], At[m][k], acc[ai][bj][m][n], 0, 0, 0); __builtin_amdgcn_s_setprio(0); } while (0)
; #define G_WAIT_V(n) asm volatile("s_waitcnt vmcnt(" #n ")" ::: "memory")
; #define G_WAIT_L(n) asm volatile("s_waitcnt lgkmcnt(" #n ")" ::: "memory")
; #define G_BAR __builtin_amdgcn_s_barrier()
; template <class Epi, bool PERMROWS = false>
; DI void gemm_phase(LAS unsigned char* lds, const bf16_t* A, int lda, const bf16_t* Bt, int K, const Sched& S, const Epi& E) {
;     ...
;             G_LDA(At, 1, 1); G_STAGE(G_SA(1, 0), a3, voffA);
;             G_BAR; G_WAIT_L(0); G_MMA(1, 0, At, B0); G_BAR; G_SCHED;
;             G_STAGE(G_SB(1, 1), b3 + hstepB, voffB);
;             G_WAIT_V(6); G_BAR; G_MMA(1, 1, At, B1); G_BAR;
;         }
;     DI void operator()(const f32x4 (&acc)[2][2][4][2], const Unit& u, int wr, int wc, int fr, int fq) const {
;     ...
;                     const int colg = u.pn * BM + bj * HALF + wc * 32;
;                     f32x4 v0 = acc[ai][bj][m][0], v1 = acc[ai][bj][m][1];
;                     const int c0 = colg + 4 * fq;
;                     if (colg >= INW) continue;
;                     if (colg >= C_NAV && colg < C_CQ) {
;                         st_tr16x32(spare + (wr * 4 + wc) * 1024, (bf16_t*)(ws + WS_VTNA) + ((size_t)b * 768 + (colg - C_NAV)) * RB + (r - fr), v0, v1, fr, fq, fq * 16 + fr);
;                     } else if (colg >= C_RV && colg < C_RG) {
;                         st_tr16x32(spare + (wr * 4 + wc) * 1024, (bf16_t*)(ws + WS_VTR) + ((size_t)b * 640 + (colg - C_RV)) * RB + (r - fr), v0, v1, fr, fq, fq * 16 + fr);
;                     } else if (colg >= C_KPE && colg < C_RQ) {
	ds_read_b128 v[166:169], v175 offset:49152
	ds_read_b128 v[178:181], v175 offset:50176
	ds_read_b128 v[182:185], v175 offset:51200
	ds_read_b128 v[186:189], v175 offset:52224
	ds_read_b128 v[190:193], v175 offset:53248
	ds_read_b128 v[194:197], v175 offset:54272
	ds_read_b128 v[198:201], v175 offset:55296
	ds_read_b128 v[204:207], v175 offset:56320
	global_load_lds_dwordx4 v[224:225], off
	v_lshl_add_u64 v[224:225], v[230:231], 0, s[16:17]
	s_mov_b32 m0, s36
	s_nop 0
	global_load_lds_dwordx4 v[224:225], off
	s_barrier
	s_waitcnt lgkmcnt(0)
	s_nop 0
	s_waitcnt lgkmcnt(0)
	v_mfma_f32_16x16x32_bf16 v[60:63], v[150:153], v[166:169], v[60:63]
	v_mfma_f32_16x16x32_bf16 v[56:59], v[158:161], v[166:169], v[56:59]
	v_mfma_f32_16x16x32_bf16 v[44:47], v[150:153], v[182:185], v[44:47]
	v_mfma_f32_16x16x32_bf16 v[40:43], v[158:161], v[182:185], v[40:43]
	v_mfma_f32_16x16x32_bf16 v[28:31], v[150:153], v[190:193], v[28:31]
	v_mfma_f32_16x16x32_bf16 v[24:27], v[158:161], v[190:193], v[24:27]
	v_mfma_f32_16x16x32_bf16 v[12:15], v[150:153], v[198:201], v[12:15]
	v_mfma_f32_16x16x32_bf16 v[8:11], v[158:161], v[198:201], v[8:11]
	v_mfma_f32_16x16x32_bf16 v[60:63], v[154:157], v[178:181], v[60:63]
	v_mfma_f32_16x16x32_bf16 v[56:59], v[162:165], v[178:181], v[56:59]
	v_mfma_f32_16x16x32_bf16 v[44:47], v[154:157], v[186:189], v[44:47]
	v_mfma_f32_16x16x32_bf16 v[40:43], v[162:165], v[186:189], v[40:43]
	v_mfma_f32_16x16x32_bf16 v[28:31], v[154:157], v[194:197], v[28:31]
	v_mfma_f32_16x16x32_bf16 v[24:27], v[162:165], v[194:197], v[24:27]
	v_mfma_f32_16x16x32_bf16 v[12:15], v[154:157], v[204:207], v[12:15]
	v_mfma_f32_16x16x32_bf16 v[8:11], v[162:165], v[204:207], v[8:11]
	s_nop 0
	s_barrier
	s_add_u32 s14, s14, 0x80080
	s_addc_u32 s15, s15, 0
	s_add_i32 s28, s28, s83
	v_lshl_add_u64 v[150:151], s[14:15], 0, v[128:129]
	s_mov_b32 m0, s28
	s_nop 0
	global_load_lds_dwordx4 v[150:151], off
	v_lshl_add_u64 v[150:151], s[14:15], 0, v[130:131]
	s_add_i32 m0, s28, 0x2000
	s_nop 0
	global_load_lds_dwordx4 v[150:151], off
	s_waitcnt vmcnt(6)
	s_barrier
	s_nop 0
	v_mfma_f32_16x16x32_bf16 v[52:55], v[208:211], v[166:169], v[52:55]
	v_mfma_f32_16x16x32_bf16 v[48:51], v[216:219], v[166:169], v[48:51]
	v_mfma_f32_16x16x32_bf16 v[36:39], v[208:211], v[182:185], v[36:39]
	v_mfma_f32_16x16x32_bf16 v[32:35], v[216:219], v[182:185], v[32:35]
	v_mfma_f32_16x16x32_bf16 v[20:23], v[208:211], v[190:193], v[20:23]
	v_mfma_f32_16x16x32_bf16 v[16:19], v[216:219], v[190:193], v[16:19]
	v_mfma_f32_16x16x32_bf16 v[4:7], v[208:211], v[198:201], v[4:7]
	v_mfma_f32_16x16x32_bf16 v[0:3], v[216:219], v[198:201], v[0:3]
	v_mfma_f32_16x16x32_bf16 v[52:55], v[212:215], v[178:181], v[52:55]
	v_mfma_f32_16x16x32_bf16 v[48:51], v[220:223], v[178:181], v[48:51]
	v_mfma_f32_16x16x32_bf16 v[36:39], v[212:215], v[186:189], v[36:39]
	v_mfma_f32_16x16x32_bf16 v[32:35], v[220:223], v[186:189], v[32:35]
	v_mfma_f32_16x16x32_bf16 v[20:23], v[212:215], v[194:197], v[20:23]
	v_mfma_f32_16x16x32_bf16 v[16:19], v[220:223], v[194:197], v[16:19]
	v_mfma_f32_16x16x32_bf16 v[4:7], v[212:215], v[204:207], v[4:7]
	v_mfma_f32_16x16x32_bf16 v[0:3], v[220:223], v[204:207], v[0:3]
	s_nop 0
	s_add_i32 s43, s43, 2
	s_add_u32 s27, s27, 0x100
	s_addc_u32 s42, s42, 0
	s_add_u32 s12, s12, 0x100
	s_addc_u32 s13, s13, 0
	s_cmp_gt_u32 s43, 29
	s_barrier
	s_cbranch_scc0 .LBB0_1981
	v_bfe_u32 v194, v202, 6, 2
	v_and_b32_e32 v169, 15, v202
	v_readfirstlane_b32 s11, v194
	s_lshl_b32 s29, s0, 8
	s_lshl_b32 s54, s11, 5
	s_add_u32 s29, s29, s54
	s_mov_b32 s32, 1
	s_cmpk_lt_u32 s29, 0x600
	s_cbranch_scc1 .Lip1_c0_d
	s_mov_b32 s32, 4
	s_cmpk_lt_u32 s29, 0x900
	s_cbranch_scc1 .Lip1_c0_d
	s_mov_b32 s32, 6
	s_cmpk_lt_u32 s29, 0xd00
	s_cbranch_scc1 .Lip1_c0_d
	s_mov_b32 s32, 7
	s_cmpk_lt_u32 s29, 0xd40
	s_cbranch_scc1 .Lip1_c0_d
	s_mov_b32 s32, 2
	s_cmpk_lt_u32 s29, 0xfc0
	s_cbranch_scc1 .Lip1_c0_d
	s_mov_b32 s32, 3
	s_cmpk_lt_u32 s29, 0x1240
	s_cbranch_scc1 .Lip1_c0_d
	s_mov_b32 s32, 5
	s_cmpk_lt_u32 s29, 0x14c0
	s_cbranch_scc1 .Lip1_c0_d
	s_mov_b32 s32, 1
	s_cmpk_lt_u32 s29, 0x1740
	s_cbranch_scc1 .Lip1_c0_d
	s_mov_b32 s32, 0

; #define G_STAGE(bufoff, gbase, voff) do { _Pragma("unroll") for (int _i = 0; _i < 2; ++_i) \
;         __builtin_amdgcn_global_load_lds((const unsigned*)((const char*)(gbase) + (voff)[_i]), (LAS unsigned*)(lds + (bufoff) + ldsw + _i * 8192), 16, 0, 0); } while (0)
; #define G_LDA(dst, b, h) do { _Pragma("unroll") for (int m = 0; m < 4; ++m) _Pragma("unroll") for (int k = 0; k < 2; ++k) dst[m][k] = *(const LAS bf16x8*)(lds + G_SA(b, h) + aoff + m * 2048 + k * 1024); } while (0)
; #define G_LDB(dst, b, h) do { _Pragma("unroll") for (int n = 0; n < 2; ++n) _Pragma("unroll") for (int k = 0; k < 2; ++k) dst[n][k] = *(const LAS bf16x8*)(lds + G_SB(b, h) + boff + n * 2048 + k * 1024); } while (0)
; #define G_MMA(ai, bj, At, Bt_) do { __builtin_amdgcn_s_setprio(1); _Pragma("unroll") for (int m = 0; m < 4; ++m) _Pragma("unroll") for (int n = 0; n < 2; ++n) _Pragma("unroll") for (int k = 0; k < 2; ++k) \
;         acc[ai][bj][m][n] = __builtin_amdgcn_mfma_f32_16x16x32_bf16(Bt_[n][k], At[m][k], acc[ai][bj][m][n], 0, 0, 0); __builtin_amdgcn_s_setprio(0); } while (0)
; #define G_WAIT_L(n) asm volatile("s_waitcnt lgkmcnt(" #n ")" ::: "memory")
; #define G_BAR __builtin_amdgcn_s_barrier()
; #define G_SCHED __builtin_amdgcn_sched_barrier(0)
; template <class Epi, bool PERMROWS = false>
; DI void gemm_phase(LAS unsigned char* lds, const bf16_t* A, int lda, const bf16_t* Bt, int K, const Sched& S, const Epi& E) {
;     ...
;         for (int t = 0; t < nt; t += 2) {
;             const bool last = (t == nt - 2);
;             const char* a1 = cA + (size_t)(t + 1) * kstep;
;             const char* a2 = last ? nA : cA + (size_t)(t + 2) * kstep; const char* b2 = last ? nB : cB + (size_t)(t + 2) * kstep;
;             const char* a3 = a2 + kstep; const char* b3 = b2 + kstep;
;             G_LDB(B0, 0, 0); G_SCHED; G_LDA(At, 0, 0); G_STAGE(G_SA(1, 1), a1 + hstepA, voffA);
;             G_WAIT_L(8); G_BAR; G_WAIT_L(0); G_MMA(0, 0, At, B0); G_BAR; G_SCHED;
;             G_LDB(B1, 0, 1); G_STAGE(G_SB(0, 0), b2, voffB);
;             G_BAR; G_WAIT_L(0); G_MMA(0, 1, At, B1); G_BAR;
;             G_LDA(At, 0, 1); G_STAGE(G_SA(0, 0), a2, voffA);
;             G_BAR; G_WAIT_L(0); G_MMA(1, 0, At, B0); G_BAR; G_SCHED;
.LBB0_2970:
	ds_read_b128 v[128:131], v183
	ds_read_b128 v[132:135], v183 offset:1024
	ds_read_b128 v[136:139], v183 offset:2048
	ds_read_b128 v[140:143], v183 offset:3072
	s_add_u32 s68, s62, 0x100
	s_addc_u32 s69, s63, 0
	s_cmp_eq_u32 s29, 28
	s_cselect_b32 s73, s43, s69
	s_cselect_b32 s72, s92, s68
	s_cselect_b32 s71, s41, s28
	s_cselect_b32 s70, s93, s94
	v_lshl_add_u64 v[200:201], s[62:63], 0, v[158:159]
	s_add_i32 m0, s54, 0xc000
	ds_read_b128 v[164:167], v184
	ds_read_b128 v[168:171], v184 offset:1024
	ds_read_b128 v[172:175], v184 offset:2048
	ds_read_b128 v[176:179], v184 offset:3072
	ds_read_b128 v[188:191], v184 offset:4096
	ds_read_b128 v[192:195], v184 offset:5120
	ds_read_b128 v[196:199], v184 offset:6144
	ds_read_b128 v[204:207], v184 offset:7168
	global_load_lds_dwordx4 v[200:201], off
	v_lshl_add_u64 v[200:201], s[62:63], 0, v[156:157]
	s_add_i32 m0, s54, 0xe000
	s_nop 0
	global_load_lds_dwordx4 v[200:201], off
	s_waitcnt lgkmcnt(8)
	s_barrier
	s_waitcnt lgkmcnt(0)
	s_nop 0
	s_waitcnt lgkmcnt(0)
	v_mfma_f32_16x16x32_bf16 v[84:87], v[128:131], v[164:167], v[84:87]
	v_mfma_f32_16x16x32_bf16 v[12:15], v[136:139], v[164:167], v[12:15]
	v_mfma_f32_16x16x32_bf16 v[88:91], v[128:131], v[172:175], v[88:91]
	v_mfma_f32_16x16x32_bf16 v[60:63], v[136:139], v[172:175], v[60:63]
	v_mfma_f32_16x16x32_bf16 v[80:83], v[128:131], v[188:191], v[80:83]
	v_mfma_f32_16x16x32_bf16 v[56:59], v[136:139], v[188:191], v[56:59]
	v_mfma_f32_16x16x32_bf16 v[76:79], v[128:131], v[196:199], v[76:79]
	v_mfma_f32_16x16x32_bf16 v[52:55], v[136:139], v[196:199], v[52:55]
	v_mfma_f32_16x16x32_bf16 v[84:87], v[132:135], v[168:171], v[84:87]
	v_mfma_f32_16x16x32_bf16 v[12:15], v[140:143], v[168:171], v[12:15]
	v_mfma_f32_16x16x32_bf16 v[88:91], v[132:135], v[176:179], v[88:91]
	v_mfma_f32_16x16x32_bf16 v[60:63], v[140:143], v[176:179], v[60:63]
	v_mfma_f32_16x16x32_bf16 v[80:83], v[132:135], v[192:195], v[80:83]
	v_mfma_f32_16x16x32_bf16 v[56:59], v[140:143], v[192:195], v[56:59]
	v_mfma_f32_16x16x32_bf16 v[76:79], v[132:135], v[204:207], v[76:79]
	v_mfma_f32_16x16x32_bf16 v[52:55], v[140:143], v[204:207], v[52:55]
	s_nop 0
	s_barrier
	s_add_i32 s62, s83, s23
	v_lshl_add_u64 v[200:201], s[70:71], 0, v[148:149]
	s_mov_b32 m0, s62
	ds_read_b128 v[208:211], v185
	ds_read_b128 v[212:215], v185 offset:1024
	ds_read_b128 v[216:219], v185 offset:2048
	ds_read_b128 v[220:223], v185 offset:3072
	global_load_lds_dwordx4 v[200:201], off
	v_lshl_add_u64 v[224:225], s[70:71], 0, v[144:145]
	s_add_i32 m0, s62, 0x2000
	s_nop 0
	global_load_lds_dwordx4 v[224:225], off
	s_barrier
	s_waitcnt lgkmcnt(0)
	s_nop 0
	s_waitcnt lgkmcnt(0)
	v_mfma_f32_16x16x32_bf16 v[72:75], v[208:211], v[164:167], v[72:75]
	v_mfma_f32_16x16x32_bf16 v[8:11], v[216:219], v[164:167], v[8:11]
	v_mfma_f32_16x16x32_bf16 v[124:127], v[208:211], v[172:175], v[124:127]
	v_mfma_f32_16x16x32_bf16 v[48:51], v[216:219], v[172:175], v[48:51]
	v_mfma_f32_16x16x32_bf16 v[120:123], v[208:211], v[188:191], v[120:123]
	v_mfma_f32_16x16x32_bf16 v[44:47], v[216:219], v[188:191], v[44:47]
	v_mfma_f32_16x16x32_bf16 v[116:119], v[208:211], v[196:199], v[116:119]
	v_mfma_f32_16x16x32_bf16 v[40:43], v[216:219], v[196:199], v[40:43]
	v_mfma_f32_16x16x32_bf16 v[72:75], v[212:215], v[168:171], v[72:75]
	v_mfma_f32_16x16x32_bf16 v[8:11], v[220:223], v[168:171], v[8:11]
	v_mfma_f32_16x16x32_bf16 v[124:127], v[212:215], v[176:179], v[124:127]
	v_mfma_f32_16x16x32_bf16 v[48:51], v[220:223], v[176:179], v[48:51]
	v_mfma_f32_16x16x32_bf16 v[120:123], v[212:215], v[192:195], v[120:123]
	v_mfma_f32_16x16x32_bf16 v[44:47], v[220:223], v[192:195], v[44:47]
	v_mfma_f32_16x16x32_bf16 v[116:119], v[212:215], v[204:207], v[116:119]
	v_mfma_f32_16x16x32_bf16 v[40:43], v[220:223], v[204:207], v[40:43]
	s_nop 0
	s_mov_b32 m0, s54
	v_lshl_add_u64 v[226:227], s[72:73], 0, v[150:151]
	s_barrier
	ds_read_b128 v[164:167], v184 offset:16384
	ds_read_b128 v[168:171], v184 offset:17408
	ds_read_b128 v[172:175], v184 offset:18432
	ds_read_b128 v[176:179], v184 offset:19456
	ds_read_b128 v[188:191], v184 offset:20480
	ds_read_b128 v[192:195], v184 offset:21504
	ds_read_b128 v[196:199], v184 offset:22528
	ds_read_b128 v[204:207], v184 offset:23552
	global_load_lds_dwordx4 v[226:227], off
	v_lshl_add_u64 v[228:229], s[72:73], 0, v[146:147]
	s_mov_b32 m0, s74
	s_nop 0
	global_load_lds_dwordx4 v[228:229], off
	s_barrier
	s_waitcnt lgkmcnt(0)
	s_nop 0
	s_waitcnt lgkmcnt(0)
	v_mfma_f32_16x16x32_bf16 v[112:115], v[128:131], v[164:167], v[112:115]
	v_mfma_f32_16x16x32_bf16 v[36:39], v[136:139], v[164:167], v[36:39]
	v_mfma_f32_16x16x32_bf16 v[108:111], v[128:131], v[172:175], v[108:111]
	v_mfma_f32_16x16x32_bf16 v[32:35], v[136:139], v[172:175], v[32:35]
	v_mfma_f32_16x16x32_bf16 v[104:107], v[128:131], v[188:191], v[104:107]
	v_mfma_f32_16x16x32_bf16 v[28:31], v[136:139], v[188:191], v[28:31]
	v_mfma_f32_16x16x32_bf16 v[68:71], v[128:131], v[196:199], v[68:71]
	v_mfma_f32_16x16x32_bf16 v[4:7], v[136:139], v[196:199], v[4:7]
	v_mfma_f32_16x16x32_bf16 v[112:115], v[132:135], v[168:171], v[112:115]
	v_mfma_f32_16x16x32_bf16 v[36:39], v[140:143], v[168:171], v[36:39]
	v_mfma_f32_16x16x32_bf16 v[108:111], v[132:135], v[176:179], v[108:111]
	v_mfma_f32_16x16x32_bf16 v[32:35], v[140:143], v[176:179], v[32:35]
	v_mfma_f32_16x16x32_bf16 v[104:107], v[132:135], v[192:195], v[104:107]
	v_mfma_f32_16x16x32_bf16 v[28:31], v[140:143], v[192:195], v[28:31]
	v_mfma_f32_16x16x32_bf16 v[68:71], v[132:135], v[204:207], v[68:71]
	v_mfma_f32_16x16x32_bf16 v[4:7], v[140:143], v[204:207], v[4:7]
	s_nop 0
	s_barrier
; #define G_STAGE(bufoff, gbase, voff) do { _Pragma("unroll") for (int _i = 0; _i < 2; ++_i) \
;         __builtin_amdgcn_global_load_lds((const unsigned*)((const char*)(gbase) + (voff)[_i]), (LAS unsigned*)(lds + (bufoff) + ldsw + _i * 8192), 16, 0, 0); } while (0)
; #define G_LDA(dst, b, h) do { _Pragma("unroll") for (int m = 0; m < 4; ++m) _Pragma("unroll") for (int k = 0; k < 2; ++k) dst[m][k] = *(const LAS bf16x8*)(lds + G_SA(b, h) + aoff + m * 2048 + k * 1024); } while (0)
; #define G_LDB(dst, b, h) do { _Pragma("unroll") for (int n = 0; n < 2; ++n) _Pragma("unroll") for (int k = 0; k < 2; ++k) dst[n][k] = *(const LAS bf16x8*)(lds + G_SB(b, h) + boff + n * 2048 + k * 1024); } while (0)
; #define G_MMA(ai, bj, At, Bt_) do { __builtin_amdgcn_s_setprio(1); _Pragma("unroll") for (int m = 0; m < 4; ++m) _Pragma("unroll") for (int n = 0; n < 2; ++n) _Pragma("unroll") for (int k = 0; k < 2; ++k) \
;         acc[ai][bj][m][n] = __builtin_amdgcn_mfma_f32_16x16x32_bf16(Bt_[n][k], At[m][k], acc[ai][bj][m][n], 0, 0, 0); __builtin_amdgcn_s_setprio(0); } while (0)
; #define G_WAIT_V(n) asm volatile("s_waitcnt vmcnt(" #n ")" ::: "memory")
; #define G_WAIT_L(n) asm volatile("s_waitcnt lgkmcnt(" #n ")" ::: "memory")
; #define G_BAR __builtin_amdgcn_s_barrier()
; #define G_SCHED __builtin_amdgcn_sched_barrier(0)
; template <class Epi, bool PERMROWS = false>
; DI void gemm_phase(LAS unsigned char* lds, const bf16_t* A, int lda, const bf16_t* Bt, int K, const Sched& S, const Epi& E) {
;     ...
;             G_STAGE(G_SB(0, 1), b2 + hstepB, voffB);
;             G_WAIT_V(6); G_BAR; G_MMA(1, 1, At, B1); G_BAR;
;             G_LDB(B0, 1, 0); G_SCHED; G_LDA(At, 1, 0); G_STAGE(G_SA(0, 1), a2 + hstepA, voffA);
;             G_WAIT_L(8); G_BAR; G_WAIT_L(0); G_MMA(0, 0, At, B0); G_BAR; G_SCHED;
;             G_LDB(B1, 1, 1); G_STAGE(G_SB(1, 0), b3, voffB);
;             G_BAR; G_WAIT_L(0); G_MMA(0, 1, At, B1); G_BAR;
;             G_LDA(At, 1, 1); G_STAGE(G_SA(1, 0), a3, voffA);
;             G_BAR; G_WAIT_L(0); G_MMA(1, 0, At, B0); G_BAR; G_SCHED;
;             G_STAGE(G_SB(1, 1), b3 + hstepB, voffB);
	s_add_u32 s62, s70, 0x80000
	s_addc_u32 s63, s71, 0
	s_add_i32 s95, s86, s23
	v_lshl_add_u64 v[128:129], s[62:63], 0, v[148:149]
	s_mov_b32 m0, s95
	s_nop 0
	global_load_lds_dwordx4 v[128:129], off
	v_lshl_add_u64 v[128:129], s[62:63], 0, v[144:145]
	s_add_i32 m0, s95, 0x2000
	s_nop 0
	global_load_lds_dwordx4 v[128:129], off
	s_waitcnt vmcnt(6)
	s_barrier
	s_nop 0
	v_mfma_f32_16x16x32_bf16 v[100:103], v[208:211], v[164:167], v[100:103]
	v_mfma_f32_16x16x32_bf16 v[24:27], v[216:219], v[164:167], v[24:27]
	v_mfma_f32_16x16x32_bf16 v[96:99], v[208:211], v[172:175], v[96:99]
	v_mfma_f32_16x16x32_bf16 v[20:23], v[216:219], v[172:175], v[20:23]
	v_mfma_f32_16x16x32_bf16 v[92:95], v[208:211], v[188:191], v[92:95]
	v_mfma_f32_16x16x32_bf16 v[16:19], v[216:219], v[188:191], v[16:19]
	v_mfma_f32_16x16x32_bf16 v[64:67], v[208:211], v[196:199], v[64:67]
	v_mfma_f32_16x16x32_bf16 v[0:3], v[216:219], v[196:199], v[0:3]
	v_mfma_f32_16x16x32_bf16 v[100:103], v[212:215], v[168:171], v[100:103]
	v_mfma_f32_16x16x32_bf16 v[24:27], v[220:223], v[168:171], v[24:27]
	v_mfma_f32_16x16x32_bf16 v[96:99], v[212:215], v[176:179], v[96:99]
	v_mfma_f32_16x16x32_bf16 v[20:23], v[220:223], v[176:179], v[20:23]
	v_mfma_f32_16x16x32_bf16 v[92:95], v[212:215], v[192:195], v[92:95]
	v_mfma_f32_16x16x32_bf16 v[16:19], v[220:223], v[192:195], v[16:19]
	v_mfma_f32_16x16x32_bf16 v[64:67], v[212:215], v[204:207], v[64:67]
	v_mfma_f32_16x16x32_bf16 v[0:3], v[220:223], v[204:207], v[0:3]
	s_nop 0
	s_add_i32 s95, 0, 0x18000
	v_add_u32_e32 v140, s95, v181
	s_barrier
	ds_read_b128 v[128:131], v140
	ds_read_b128 v[132:135], v140 offset:1024
	ds_read_b128 v[136:139], v140 offset:2048
	ds_read_b128 v[140:143], v140 offset:3072
	s_add_u32 s62, s72, 0x4000
	s_addc_u32 s63, s73, 0
	s_mov_b32 m0, s75
	v_lshl_add_u64 v[208:209], s[62:63], 0, v[150:151]
	ds_read_b128 v[164:167], v184 offset:32768
	ds_read_b128 v[168:171], v184 offset:33792
	ds_read_b128 v[172:175], v184 offset:34816
	ds_read_b128 v[176:179], v184 offset:35840
	ds_read_b128 v[188:191], v184 offset:36864
	ds_read_b128 v[192:195], v184 offset:37888
	ds_read_b128 v[196:199], v184 offset:38912
	ds_read_b128 v[204:207], v184 offset:39936
	global_load_lds_dwordx4 v[208:209], off
	v_lshl_add_u64 v[208:209], s[62:63], 0, v[146:147]
	s_mov_b32 m0, s76
	s_nop 0
	global_load_lds_dwordx4 v[208:209], off
	s_waitcnt lgkmcnt(8)
	s_barrier
	s_waitcnt lgkmcnt(0)
	s_nop 0
	s_waitcnt lgkmcnt(0)
	v_mfma_f32_16x16x32_bf16 v[84:87], v[128:131], v[164:167], v[84:87]
	v_mfma_f32_16x16x32_bf16 v[12:15], v[136:139], v[164:167], v[12:15]
	v_mfma_f32_16x16x32_bf16 v[88:91], v[128:131], v[172:175], v[88:91]
	v_mfma_f32_16x16x32_bf16 v[60:63], v[136:139], v[172:175], v[60:63]
	v_mfma_f32_16x16x32_bf16 v[80:83], v[128:131], v[188:191], v[80:83]
	v_mfma_f32_16x16x32_bf16 v[56:59], v[136:139], v[188:191], v[56:59]
	v_mfma_f32_16x16x32_bf16 v[76:79], v[128:131], v[196:199], v[76:79]
	v_mfma_f32_16x16x32_bf16 v[52:55], v[136:139], v[196:199], v[52:55]
	v_mfma_f32_16x16x32_bf16 v[84:87], v[132:135], v[168:171], v[84:87]
	v_mfma_f32_16x16x32_bf16 v[12:15], v[140:143], v[168:171], v[12:15]
	v_mfma_f32_16x16x32_bf16 v[88:91], v[132:135], v[176:179], v[88:91]
	v_mfma_f32_16x16x32_bf16 v[60:63], v[140:143], v[176:179], v[60:63]
	v_mfma_f32_16x16x32_bf16 v[80:83], v[132:135], v[192:195], v[80:83]
	v_mfma_f32_16x16x32_bf16 v[56:59], v[140:143], v[192:195], v[56:59]
	v_mfma_f32_16x16x32_bf16 v[76:79], v[132:135], v[204:207], v[76:79]
	v_mfma_f32_16x16x32_bf16 v[52:55], v[140:143], v[204:207], v[52:55]
	s_nop 0
	s_barrier
	s_add_i32 s72, 0, 0x1c000
	s_add_i32 s62, s95, s23
	v_add_u32_e32 v187, s72, v181
	v_lshl_add_u64 v[200:201], v[200:201], 0, s[18:19]
	s_mov_b32 m0, s62
	ds_read_b128 v[208:211], v187
	ds_read_b128 v[212:215], v187 offset:1024
	ds_read_b128 v[216:219], v187 offset:2048
	ds_read_b128 v[220:223], v187 offset:3072
	global_load_lds_dwordx4 v[200:201], off
	v_lshl_add_u64 v[200:201], v[224:225], 0, s[18:19]
	s_add_i32 m0, s62, 0x2000
	s_nop 0
	global_load_lds_dwordx4 v[200:201], off
	s_barrier
	s_waitcnt lgkmcnt(0)
	s_nop 0
	s_waitcnt lgkmcnt(0)
	v_mfma_f32_16x16x32_bf16 v[72:75], v[208:211], v[164:167], v[72:75]
	v_mfma_f32_16x16x32_bf16 v[8:11], v[216:219], v[164:167], v[8:11]
	v_mfma_f32_16x16x32_bf16 v[124:127], v[208:211], v[172:175], v[124:127]
	v_mfma_f32_16x16x32_bf16 v[48:51], v[216:219], v[172:175], v[48:51]
	v_mfma_f32_16x16x32_bf16 v[120:123], v[208:211], v[188:191], v[120:123]
	v_mfma_f32_16x16x32_bf16 v[44:47], v[216:219], v[188:191], v[44:47]
	v_mfma_f32_16x16x32_bf16 v[116:119], v[208:211], v[196:199], v[116:119]
	v_mfma_f32_16x16x32_bf16 v[40:43], v[216:219], v[196:199], v[40:43]
	v_mfma_f32_16x16x32_bf16 v[72:75], v[212:215], v[168:171], v[72:75]
	v_mfma_f32_16x16x32_bf16 v[8:11], v[220:223], v[168:171], v[8:11]
	v_mfma_f32_16x16x32_bf16 v[124:127], v[212:215], v[176:179], v[124:127]
	v_mfma_f32_16x16x32_bf16 v[48:51], v[220:223], v[176:179], v[48:51]
	v_mfma_f32_16x16x32_bf16 v[120:123], v[212:215], v[192:195], v[120:123]
	v_mfma_f32_16x16x32_bf16 v[44:47], v[220:223], v[192:195], v[44:47]
	v_mfma_f32_16x16x32_bf16 v[116:119], v[212:215], v[204:207], v[116:119]
	v_mfma_f32_16x16x32_bf16 v[40:43], v[220:223], v[204:207], v[40:43]
	s_nop 0
	s_mov_b32 m0, s79
	v_lshl_add_u64 v[200:201], v[226:227], 0, s[18:19]
	s_barrier
	ds_read_b128 v[164:167], v184 offset:49152
	ds_read_b128 v[168:171], v184 offset:50176
	ds_read_b128 v[172:175], v184 offset:51200
	ds_read_b128 v[176:179], v184 offset:52224
	ds_read_b128 v[188:191], v184 offset:53248
	ds_read_b128 v[192:195], v184 offset:54272
	ds_read_b128 v[196:199], v184 offset:55296
	ds_read_b128 v[204:207], v184 offset:56320
	global_load_lds_dwordx4 v[200:201], off
	v_lshl_add_u64 v[200:201], v[228:229], 0, s[18:19]
	s_mov_b32 m0, s81
	s_nop 0
	global_load_lds_dwordx4 v[200:201], off
	s_barrier
; #define G_WAIT_V(n) asm volatile("s_waitcnt vmcnt(" #n ")" ::: "memory")
; template <class Epi, bool PERMROWS = false>
; DI void gemm_phase(LAS unsigned char* lds, const bf16_t* A, int lda, const bf16_t* Bt, int K, const Sched& S, const Epi& E) {
;     ...
;             G_BAR; G_WAIT_L(0); G_MMA(0, 1, At, B1); G_BAR;
;             G_LDA(At, 1, 1); G_STAGE(G_SA(1, 0), a3, voffA);
;             G_BAR; G_WAIT_L(0); G_MMA(1, 0, At, B0); G_BAR; G_SCHED;
;             G_STAGE(G_SB(1, 1), b3 + hstepB, voffB);
;             G_WAIT_V(6); G_BAR; G_MMA(1, 1, At, B1); G_BAR;
;         }
;     DI void operator()(const f32x4 (&acc)[2][2][4][2], const Unit& u, int wr, int wc, int fr, int fq) const {
;     ...
;         const int tok0 = (wr * 16 + fr) * 8;
;         const size_t row0 = (size_t)u.pm * BM + tok0;
;         const bool e_lo = (fr == 0), e_hi = (fr == 15);
; #pragma unroll
;         for (int n = 0; n < 2; ++n) {
;             const int col = u.pn * 128 + wc * 32 + n * 16 + 4 * fq;
;             const f32x4 w0 = *(const f32x4*)(cw + col), w1 = *(const f32x4*)(cw + DFF + col), w2 = *(const f32x4*)(cw + 2 * DFF + col), bb = *(const f32x4*)(cb + col);
;             f32x4 g[8];
;             f32x4 ed_a, ed_p, ed_u;
; #pragma unroll
;             for (int j = 0; j < 4; ++j) {
;                 float a[8], uu[8];
; #pragma unroll
;                 for (int k = 0; k < 8; ++k) { a[k] = acc[k >> 2][0][k & 3][n][j]; uu[k] = acc[k >> 2][1][k & 3][n][j]; }
;                 const float aprev = __shfl_up(a[7], 1), anext = __shfl_down(a[0], 1);
; #pragma unroll
;                 for (int k = 0; k < 8; ++k) {
;                     const float c = bb[j] + w0[j] * (k > 0 ? a[k - 1] : aprev) + w1[j] * a[k] + w2[j] * (k < 7 ? a[k + 1] : anext);
;                     g[k][j] = silu(c) * uu[k];
;                 }
;                 if (e_lo) { ed_a[j] = a[0]; ed_p[j] = bb[j] + w1[j] * a[0] + w2[j] * a[1]; ed_u[j] = uu[0]; }
;                 if (e_hi) { ed_a[j] = a[7]; ed_p[j] = bb[j] + w0[j] * a[6] + w1[j] * a[7]; ed_u[j] = uu[7]; }
;             }
; #pragma unroll
;             for (int k = 0; k < 8; ++k) {
;                 if ((k == 0 && e_lo) || (k == 7 && e_hi)) continue;
;                 st_bf16x4(G + (row0 + k) * DFF + col, g[k]);
;             }
;             if (e_lo || e_hi) {
;                 const size_t eo = ((size_t)u.pm * 4 + wr * 2 + (e_hi ? 1 : 0)) * DFF + col;
	s_waitcnt lgkmcnt(0)
	s_nop 0
	s_waitcnt lgkmcnt(0)
	v_mfma_f32_16x16x32_bf16 v[112:115], v[128:131], v[164:167], v[112:115]
	v_mfma_f32_16x16x32_bf16 v[36:39], v[136:139], v[164:167], v[36:39]
	v_mfma_f32_16x16x32_bf16 v[108:111], v[128:131], v[172:175], v[108:111]
	v_mfma_f32_16x16x32_bf16 v[32:35], v[136:139], v[172:175], v[32:35]
	v_mfma_f32_16x16x32_bf16 v[104:107], v[128:131], v[188:191], v[104:107]
	v_mfma_f32_16x16x32_bf16 v[28:31], v[136:139], v[188:191], v[28:31]
	v_mfma_f32_16x16x32_bf16 v[68:71], v[128:131], v[196:199], v[68:71]
	v_mfma_f32_16x16x32_bf16 v[4:7], v[136:139], v[196:199], v[4:7]
	v_mfma_f32_16x16x32_bf16 v[112:115], v[132:135], v[168:171], v[112:115]
	v_mfma_f32_16x16x32_bf16 v[36:39], v[140:143], v[168:171], v[36:39]
	v_mfma_f32_16x16x32_bf16 v[108:111], v[132:135], v[176:179], v[108:111]
	v_mfma_f32_16x16x32_bf16 v[32:35], v[140:143], v[176:179], v[32:35]
	v_mfma_f32_16x16x32_bf16 v[104:107], v[132:135], v[192:195], v[104:107]
	v_mfma_f32_16x16x32_bf16 v[28:31], v[140:143], v[192:195], v[28:31]
	v_mfma_f32_16x16x32_bf16 v[68:71], v[132:135], v[204:207], v[68:71]
	v_mfma_f32_16x16x32_bf16 v[4:7], v[140:143], v[204:207], v[4:7]
	s_nop 0
	s_barrier
	s_add_u32 s62, s70, 0x80080
	s_addc_u32 s63, s71, 0
	s_add_i32 s70, s72, s23
	v_lshl_add_u64 v[128:129], s[62:63], 0, v[148:149]
	s_mov_b32 m0, s70
	s_nop 0
	global_load_lds_dwordx4 v[128:129], off
	v_lshl_add_u64 v[128:129], s[62:63], 0, v[144:145]
	s_add_i32 m0, s70, 0x2000
	s_nop 0
	global_load_lds_dwordx4 v[128:129], off
	s_waitcnt vmcnt(6)
	s_barrier
	s_nop 0
	v_mfma_f32_16x16x32_bf16 v[100:103], v[208:211], v[164:167], v[100:103]
	v_mfma_f32_16x16x32_bf16 v[24:27], v[216:219], v[164:167], v[24:27]
	v_mfma_f32_16x16x32_bf16 v[96:99], v[208:211], v[172:175], v[96:99]
	v_mfma_f32_16x16x32_bf16 v[20:23], v[216:219], v[172:175], v[20:23]
	v_mfma_f32_16x16x32_bf16 v[92:95], v[208:211], v[188:191], v[92:95]
	v_mfma_f32_16x16x32_bf16 v[16:19], v[216:219], v[188:191], v[16:19]
	v_mfma_f32_16x16x32_bf16 v[64:67], v[208:211], v[196:199], v[64:67]
	v_mfma_f32_16x16x32_bf16 v[0:3], v[216:219], v[196:199], v[0:3]
	v_mfma_f32_16x16x32_bf16 v[100:103], v[212:215], v[168:171], v[100:103]
	v_mfma_f32_16x16x32_bf16 v[24:27], v[220:223], v[168:171], v[24:27]
	v_mfma_f32_16x16x32_bf16 v[96:99], v[212:215], v[176:179], v[96:99]
	v_mfma_f32_16x16x32_bf16 v[20:23], v[220:223], v[176:179], v[20:23]
	v_mfma_f32_16x16x32_bf16 v[92:95], v[212:215], v[192:195], v[92:95]
	v_mfma_f32_16x16x32_bf16 v[16:19], v[220:223], v[192:195], v[16:19]
	v_mfma_f32_16x16x32_bf16 v[64:67], v[212:215], v[204:207], v[64:67]
	v_mfma_f32_16x16x32_bf16 v[0:3], v[220:223], v[204:207], v[0:3]
	s_nop 0
	s_add_i32 s29, s29, 2
	s_add_u32 s94, s94, 0x100
	s_addc_u32 s28, s28, 0
	s_cmp_gt_u32 s29, 29
	s_mov_b64 s[62:63], s[68:69]
	s_barrier
	s_cbranch_scc0 .LBB0_2970
	v_and_b32_e32 v131, 15, v202
	v_bfe_u32 v134, v202, 8, 1
	v_bfe_u32 v135, v202, 6, 2
	v_bfe_u32 v138, v202, 4, 2
	s_lshl_b32 s29, s61, 7
	v_lshlrev_b32_e32 v139, 5, v135
	v_lshl_add_u32 v139, v138, 2, v139
	v_add_u32_e32 v139, s29, v139
	v_lshlrev_b32_e32 v128, 2, v139
	v_lshl_add_u32 v140, v134, 4, v131
	v_mul_u32_u24_e32 v129, 0x16000, v140
	v_lshl_add_u32 v129, v139, 1, v129
	v_cmp_eq_u32_e64 s[70:71], 0, v131
	v_cmp_eq_u32_e64 s[72:73], 15, v131
	v_lshlrev_b32_e32 v130, 1, v134
	v_cndmask_b32_e64 v141, 0, 1, s[72:73]
	v_add_u32_e32 v130, v130, v141
	v_mul_u32_u24_e32 v130, 0x5800, v130
	v_add_u32_e32 v130, v130, v128
	v_mov_b32_e32 v132, 0xbfb8aa3b
	v_mov_b32_e32 v133, 0xbfb8aa3b
	s_mov_b64 s[68:69], s[0:1]
	global_load_dwordx4 v[204:207], v128, s[68:69] offset:0
	global_load_dwordx4 v[220:223], v128, s[68:69] offset:64
	s_add_u32 s68, s68, 0x5800
	s_addc_u32 s69, s69, 0
	global_load_dwordx4 v[208:211], v128, s[68:69] offset:0
	global_load_dwordx4 v[224:227], v128, s[68:69] offset:64
	s_add_u32 s68, s68, 0x5800
	s_addc_u32 s69, s69, 0
	global_load_dwordx4 v[212:215], v128, s[68:69] offset:0
	global_load_dwordx4 v[228:231], v128, s[68:69] offset:64
	global_load_dwordx4 v[216:219], v128, s[16:17] offset:0
	global_load_dwordx4 v[232:235], v128, s[16:17] offset:64
	s_mul_i32 s29, s60, 0x2c0000
	s_mul_i32 s32, s60, 0x16000
	s_waitcnt vmcnt(0)
	v_mov_b32_dpp v164, v68 row_shr:1 row_mask:0xf bank_mask:0xf bound_ctrl:0
	v_mov_b32_dpp v165, v69 row_shr:1 row_mask:0xf bank_mask:0xf bound_ctrl:0
	v_mov_b32_dpp v166, v70 row_shr:1 row_mask:0xf bank_mask:0xf bound_ctrl:0
	v_mov_b32_dpp v167, v71 row_shr:1 row_mask:0xf bank_mask:0xf bound_ctrl:0
	v_mov_b32_dpp v168, v84 row_shl:1 row_mask:0xf bank_mask:0xf bound_ctrl:0
	v_mov_b32_dpp v169, v85 row_shl:1 row_mask:0xf bank_mask:0xf bound_ctrl:0
	v_mov_b32_dpp v170, v86 row_shl:1 row_mask:0xf bank_mask:0xf bound_ctrl:0
	v_mov_b32_dpp v171, v87 row_shl:1 row_mask:0xf bank_mask:0xf bound_ctrl:0
	s_mov_b64 exec, s[70:71]
	v_pk_fma_f32 v[172:173], v[208:209], v[84:85], v[216:217]
	v_pk_fma_f32 v[172:173], v[212:213], v[88:89], v[172:173]
	v_pk_fma_f32 v[174:175], v[210:211], v[86:87], v[218:219]
	v_pk_fma_f32 v[174:175], v[214:215], v[90:91], v[174:175]
	s_add_u32 s68, s50, 0x113a0000
	s_addc_u32 s69, s51, 0
	s_add_u32 s68, s68, s32
	s_addc_u32 s69, s69, 0
	global_store_dwordx4 v130, v[84:87], s[68:69] offset:0
	s_add_u32 s68, s68, 0x318000
	s_addc_u32 s69, s69, 0
	global_store_dwordx4 v130, v[172:175], s[68:69] offset:0
	s_add_u32 s68, s68, 0x318000
	s_addc_u32 s69, s69, 0
	global_store_dwordx4 v130, v[72:75], s[68:69] offset:0
	s_nop 1
	s_mov_b64 exec, s[72:73]
	v_pk_fma_f32 v[172:173], v[204:205], v[104:105], v[216:217]
	v_pk_fma_f32 v[172:173], v[208:209], v[68:69], v[172:173]
	v_pk_fma_f32 v[174:175], v[206:207], v[106:107], v[218:219]
; DI float silu(float v) { return v * __builtin_amdgcn_rcpf(1.f + __builtin_amdgcn_exp2f(-1.4426950408889634f * v)); }
; DI void st_bf16x4(bf16_t* p, f32x4 v) { u32x2 w; w.x = cvt_pk_bf16(v[0], v[1]); w.y = cvt_pk_bf16(v[2], v[3]); *(u32x2*)p = w; }
;     DI void operator()(const f32x4 (&acc)[2][2][4][2], const Unit& u, int wr, int wc, int fr, int fq) const {
;     ...
;                 for (int k = 0; k < 8; ++k) { a[k] = acc[k >> 2][0][k & 3][n][j]; uu[k] = acc[k >> 2][1][k & 3][n][j]; }
;                 const float aprev = __shfl_up(a[7], 1), anext = __shfl_down(a[0], 1);
; #pragma unroll
;                 for (int k = 0; k < 8; ++k) {
;                     const float c = bb[j] + w0[j] * (k > 0 ? a[k - 1] : aprev) + w1[j] * a[k] + w2[j] * (k < 7 ? a[k + 1] : anext);
;                     g[k][j] = silu(c) * uu[k];
;                 }
;                 if (e_lo) { ed_a[j] = a[0]; ed_p[j] = bb[j] + w1[j] * a[0] + w2[j] * a[1]; ed_u[j] = uu[0]; }
;                 if (e_hi) { ed_a[j] = a[7]; ed_p[j] = bb[j] + w0[j] * a[6] + w1[j] * a[7]; ed_u[j] = uu[7]; }
;             }
; #pragma unroll
;             for (int k = 0; k < 8; ++k) {
;                 if ((k == 0 && e_lo) || (k == 7 && e_hi)) continue;
;                 st_bf16x4(G + (row0 + k) * DFF + col, g[k]);
;             }
;             if (e_lo || e_hi) {
;                 const size_t eo = ((size_t)u.pm * 4 + wr * 2 + (e_hi ? 1 : 0)) * DFF + col;
;                 *(f32x4*)(EA + eo) = ed_a; *(f32x4*)(EP + eo) = ed_p; *(f32x4*)(EU + eo) = ed_u;
	v_pk_fma_f32 v[174:175], v[210:211], v[70:71], v[174:175]
	s_add_u32 s68, s50, 0x113a0000
	s_addc_u32 s69, s51, 0
	s_add_u32 s68, s68, s32
	s_addc_u32 s69, s69, 0
	global_store_dwordx4 v130, v[68:71], s[68:69] offset:0
	s_add_u32 s68, s68, 0x318000
	s_addc_u32 s69, s69, 0
	global_store_dwordx4 v130, v[172:175], s[68:69] offset:0
	s_add_u32 s68, s68, 0x318000
	s_addc_u32 s69, s69, 0
	global_store_dwordx4 v130, v[64:67], s[68:69] offset:0
	s_nop 1
	s_mov_b64 exec, -1
	s_add_u32 s62, s50, 0x1d9a0000
	s_addc_u32 s63, s51, 0
	s_add_u32 s62, s62, s29
	s_addc_u32 s63, s63, 0
	v_pk_fma_f32 v[236:237], v[204:205], v[164:165], v[216:217]
	v_pk_fma_f32 v[236:237], v[208:209], v[84:85], v[236:237]
	v_pk_fma_f32 v[236:237], v[212:213], v[88:89], v[236:237]
	v_pk_fma_f32 v[238:239], v[206:207], v[166:167], v[218:219]
	v_pk_fma_f32 v[238:239], v[210:211], v[86:87], v[238:239]
	v_pk_fma_f32 v[238:239], v[214:215], v[90:91], v[238:239]
	v_pk_mul_f32 v[244:245], v[236:237], v[132:133]
	v_pk_mul_f32 v[246:247], v[238:239], v[132:133]
	v_exp_f32_e32 v244, v244
	v_exp_f32_e32 v245, v245
	v_exp_f32_e32 v246, v246
	v_exp_f32_e32 v247, v247
	v_pk_add_f32 v[244:245], v[244:245], 1.0 op_sel_hi:[1,0]
	v_pk_add_f32 v[246:247], v[246:247], 1.0 op_sel_hi:[1,0]
	v_rcp_f32_e32 v244, v244
	v_rcp_f32_e32 v245, v245
	v_rcp_f32_e32 v246, v246
	v_rcp_f32_e32 v247, v247
	v_pk_mul_f32 v[236:237], v[236:237], v[244:245]
	v_pk_mul_f32 v[238:239], v[238:239], v[246:247]
	v_pk_mul_f32 v[72:73], v[72:73], v[236:237]
	v_pk_mul_f32 v[74:75], v[74:75], v[238:239]
	v_cvt_pk_bf16_f32 v72, v72, v73
	v_cvt_pk_bf16_f32 v73, v74, v75
	s_andn2_b64 exec, exec, s[70:71]
	global_store_dwordx2 v129, v[72:73], s[62:63] offset:0
	s_mov_b64 exec, -1
	s_add_u32 s62, s62, 0x2c00
	s_addc_u32 s63, s63, 0
	v_pk_fma_f32 v[236:237], v[204:205], v[84:85], v[216:217]
	v_pk_fma_f32 v[236:237], v[208:209], v[88:89], v[236:237]
	v_pk_fma_f32 v[236:237], v[212:213], v[80:81], v[236:237]
	v_pk_fma_f32 v[238:239], v[206:207], v[86:87], v[218:219]
	v_pk_fma_f32 v[238:239], v[210:211], v[90:91], v[238:239]
	v_pk_fma_f32 v[238:239], v[214:215], v[82:83], v[238:239]
	v_pk_mul_f32 v[244:245], v[236:237], v[132:133]
	v_pk_mul_f32 v[246:247], v[238:239], v[132:133]
	v_exp_f32_e32 v244, v244
	v_exp_f32_e32 v245, v245
	v_exp_f32_e32 v246, v246
	v_exp_f32_e32 v247, v247
	v_pk_add_f32 v[244:245], v[244:245], 1.0 op_sel_hi:[1,0]
	v_pk_add_f32 v[246:247], v[246:247], 1.0 op_sel_hi:[1,0]
	v_rcp_f32_e32 v244, v244
	v_rcp_f32_e32 v245, v245
	v_rcp_f32_e32 v246, v246
	v_rcp_f32_e32 v247, v247
	v_pk_mul_f32 v[236:237], v[236:237], v[244:245]
	v_pk_mul_f32 v[238:239], v[238:239], v[246:247]
	v_pk_mul_f32 v[124:125], v[124:125], v[236:237]
	v_pk_mul_f32 v[126:127], v[126:127], v[238:239]
	v_cvt_pk_bf16_f32 v124, v124, v125
	v_cvt_pk_bf16_f32 v125, v126, v127
	global_store_dwordx2 v129, v[124:125], s[62:63] offset:0
	s_add_u32 s62, s62, 0x2c00
	s_addc_u32 s63, s63, 0
	v_pk_fma_f32 v[236:237], v[204:205], v[88:89], v[216:217]
	v_pk_fma_f32 v[236:237], v[208:209], v[80:81], v[236:237]
	v_pk_fma_f32 v[236:237], v[212:213], v[76:77], v[236:237]
	v_pk_fma_f32 v[238:239], v[206:207], v[90:91], v[218:219]
	v_pk_fma_f32 v[238:239], v[210:211], v[82:83], v[238:239]
	v_pk_fma_f32 v[238:239], v[214:215], v[78:79], v[238:239]
	v_pk_mul_f32 v[244:245], v[236:237], v[132:133]
	v_pk_mul_f32 v[246:247], v[238:239], v[132:133]
	v_exp_f32_e32 v244, v244
	v_exp_f32_e32 v245, v245
	v_exp_f32_e32 v246, v246
	v_exp_f32_e32 v247, v247
	v_pk_add_f32 v[244:245], v[244:245], 1.0 op_sel_hi:[1,0]
	v_pk_add_f32 v[246:247], v[246:247], 1.0 op_sel_hi:[1,0]
	v_rcp_f32_e32 v244, v244
	v_rcp_f32_e32 v245, v245
	v_rcp_f32_e32 v246, v246
	v_rcp_f32_e32 v247, v247
	v_pk_mul_f32 v[236:237], v[236:237], v[244:245]
	v_pk_mul_f32 v[238:239], v[238:239], v[246:247]
	v_pk_mul_f32 v[120:121], v[120:121], v[236:237]
	v_pk_mul_f32 v[122:123], v[122:123], v[238:239]
	v_cvt_pk_bf16_f32 v120, v120, v121
	v_cvt_pk_bf16_f32 v121, v122, v123
	global_store_dwordx2 v129, v[120:121], s[62:63] offset:0
	s_add_u32 s62, s62, 0x2c00
	s_addc_u32 s63, s63, 0
	v_pk_fma_f32 v[236:237], v[204:205], v[80:81], v[216:217]
	v_pk_fma_f32 v[236:237], v[208:209], v[76:77], v[236:237]
	v_pk_fma_f32 v[236:237], v[212:213], v[112:113], v[236:237]
	v_pk_fma_f32 v[238:239], v[206:207], v[82:83], v[218:219]
	v_pk_fma_f32 v[238:239], v[210:211], v[78:79], v[238:239]
	v_pk_fma_f32 v[238:239], v[214:215], v[114:115], v[238:239]
	v_pk_mul_f32 v[244:245], v[236:237], v[132:133]
	v_pk_mul_f32 v[246:247], v[238:239], v[132:133]
	v_exp_f32_e32 v244, v244
	v_exp_f32_e32 v245, v245
	v_exp_f32_e32 v246, v246
	v_exp_f32_e32 v247, v247
	v_pk_add_f32 v[244:245], v[244:245], 1.0 op_sel_hi:[1,0]
	v_pk_add_f32 v[246:247], v[246:247], 1.0 op_sel_hi:[1,0]
	v_rcp_f32_e32 v244, v244
	v_rcp_f32_e32 v245, v245
	v_rcp_f32_e32 v246, v246
	v_rcp_f32_e32 v247, v247
	v_pk_mul_f32 v[236:237], v[236:237], v[244:245]
	v_pk_mul_f32 v[238:239], v[238:239], v[246:247]
	v_pk_mul_f32 v[116:117], v[116:117], v[236:237]
	v_pk_mul_f32 v[118:119], v[118:119], v[238:239]
	v_cvt_pk_bf16_f32 v116, v116, v117
	v_cvt_pk_bf16_f32 v117, v118, v119
	global_store_dwordx2 v129, v[116:117], s[62:63] offset:0
	s_add_u32 s62, s62, 0x2c00
	s_addc_u32 s63, s63, 0
	v_pk_fma_f32 v[236:237], v[204:205], v[76:77], v[216:217]
	v_pk_fma_f32 v[236:237], v[208:209], v[112:113], v[236:237]
	v_pk_fma_f32 v[236:237], v[212:213], v[108:109], v[236:237]
	v_pk_fma_f32 v[238:239], v[206:207], v[78:79], v[218:219]
	v_pk_fma_f32 v[238:239], v[210:211], v[114:115], v[238:239]
	v_pk_fma_f32 v[238:239], v[214:215], v[110:111], v[238:239]
	v_pk_mul_f32 v[244:245], v[236:237], v[132:133]
; DI float silu(float v) { return v * __builtin_amdgcn_rcpf(1.f + __builtin_amdgcn_exp2f(-1.4426950408889634f * v)); }
; DI void st_bf16x4(bf16_t* p, f32x4 v) { u32x2 w; w.x = cvt_pk_bf16(v[0], v[1]); w.y = cvt_pk_bf16(v[2], v[3]); *(u32x2*)p = w; }
;     DI void operator()(const f32x4 (&acc)[2][2][4][2], const Unit& u, int wr, int wc, int fr, int fq) const {
;     ...
;                 for (int k = 0; k < 8; ++k) { a[k] = acc[k >> 2][0][k & 3][n][j]; uu[k] = acc[k >> 2][1][k & 3][n][j]; }
;                 const float aprev = __shfl_up(a[7], 1), anext = __shfl_down(a[0], 1);
; #pragma unroll
;                 for (int k = 0; k < 8; ++k) {
;                     const float c = bb[j] + w0[j] * (k > 0 ? a[k - 1] : aprev) + w1[j] * a[k] + w2[j] * (k < 7 ? a[k + 1] : anext);
;                     g[k][j] = silu(c) * uu[k];
;                 }
;                 if (e_lo) { ed_a[j] = a[0]; ed_p[j] = bb[j] + w1[j] * a[0] + w2[j] * a[1]; ed_u[j] = uu[0]; }
;                 if (e_hi) { ed_a[j] = a[7]; ed_p[j] = bb[j] + w0[j] * a[6] + w1[j] * a[7]; ed_u[j] = uu[7]; }
;             }
; #pragma unroll
;             for (int k = 0; k < 8; ++k) {
;                 if ((k == 0 && e_lo) || (k == 7 && e_hi)) continue;
;                 st_bf16x4(G + (row0 + k) * DFF + col, g[k]);
;             }
;             if (e_lo || e_hi) {
;                 const size_t eo = ((size_t)u.pm * 4 + wr * 2 + (e_hi ? 1 : 0)) * DFF + col;
;                 *(f32x4*)(EA + eo) = ed_a; *(f32x4*)(EP + eo) = ed_p; *(f32x4*)(EU + eo) = ed_u;
	v_pk_mul_f32 v[246:247], v[238:239], v[132:133]
	v_exp_f32_e32 v244, v244
	v_exp_f32_e32 v245, v245
	v_exp_f32_e32 v246, v246
	v_exp_f32_e32 v247, v247
	v_pk_add_f32 v[244:245], v[244:245], 1.0 op_sel_hi:[1,0]
	v_pk_add_f32 v[246:247], v[246:247], 1.0 op_sel_hi:[1,0]
	v_rcp_f32_e32 v244, v244
	v_rcp_f32_e32 v245, v245
	v_rcp_f32_e32 v246, v246
	v_rcp_f32_e32 v247, v247
	v_pk_mul_f32 v[236:237], v[236:237], v[244:245]
	v_pk_mul_f32 v[238:239], v[238:239], v[246:247]
	v_pk_mul_f32 v[100:101], v[100:101], v[236:237]
	v_pk_mul_f32 v[102:103], v[102:103], v[238:239]
	v_cvt_pk_bf16_f32 v100, v100, v101
	v_cvt_pk_bf16_f32 v101, v102, v103
	global_store_dwordx2 v129, v[100:101], s[62:63] offset:0
	s_add_u32 s62, s62, 0x2c00
	s_addc_u32 s63, s63, 0
	v_pk_fma_f32 v[236:237], v[204:205], v[112:113], v[216:217]
	v_pk_fma_f32 v[236:237], v[208:209], v[108:109], v[236:237]
	v_pk_fma_f32 v[236:237], v[212:213], v[104:105], v[236:237]
	v_pk_fma_f32 v[238:239], v[206:207], v[114:115], v[218:219]
	v_pk_fma_f32 v[238:239], v[210:211], v[110:111], v[238:239]
	v_pk_fma_f32 v[238:239], v[214:215], v[106:107], v[238:239]
	v_pk_mul_f32 v[244:245], v[236:237], v[132:133]
	v_pk_mul_f32 v[246:247], v[238:239], v[132:133]
	v_exp_f32_e32 v244, v244
	v_exp_f32_e32 v245, v245
	v_exp_f32_e32 v246, v246
	v_exp_f32_e32 v247, v247
	v_pk_add_f32 v[244:245], v[244:245], 1.0 op_sel_hi:[1,0]
	v_pk_add_f32 v[246:247], v[246:247], 1.0 op_sel_hi:[1,0]
	v_rcp_f32_e32 v244, v244
	v_rcp_f32_e32 v245, v245
	v_rcp_f32_e32 v246, v246
	v_rcp_f32_e32 v247, v247
	v_pk_mul_f32 v[236:237], v[236:237], v[244:245]
	v_pk_mul_f32 v[238:239], v[238:239], v[246:247]
	v_pk_mul_f32 v[96:97], v[96:97], v[236:237]
	v_pk_mul_f32 v[98:99], v[98:99], v[238:239]
	v_cvt_pk_bf16_f32 v96, v96, v97
	v_cvt_pk_bf16_f32 v97, v98, v99
	global_store_dwordx2 v129, v[96:97], s[62:63] offset:0
	s_add_u32 s62, s62, 0x2c00
	s_addc_u32 s63, s63, 0
	v_pk_fma_f32 v[236:237], v[204:205], v[108:109], v[216:217]
	v_pk_fma_f32 v[236:237], v[208:209], v[104:105], v[236:237]
	v_pk_fma_f32 v[236:237], v[212:213], v[68:69], v[236:237]
	v_pk_fma_f32 v[238:239], v[206:207], v[110:111], v[218:219]
	v_pk_fma_f32 v[238:239], v[210:211], v[106:107], v[238:239]
	v_pk_fma_f32 v[238:239], v[214:215], v[70:71], v[238:239]
	v_pk_mul_f32 v[244:245], v[236:237], v[132:133]
	v_pk_mul_f32 v[246:247], v[238:239], v[132:133]
	v_exp_f32_e32 v244, v244
	v_exp_f32_e32 v245, v245
	v_exp_f32_e32 v246, v246
	v_exp_f32_e32 v247, v247
	v_pk_add_f32 v[244:245], v[244:245], 1.0 op_sel_hi:[1,0]
	v_pk_add_f32 v[246:247], v[246:247], 1.0 op_sel_hi:[1,0]
	v_rcp_f32_e32 v244, v244
	v_rcp_f32_e32 v245, v245
	v_rcp_f32_e32 v246, v246
	v_rcp_f32_e32 v247, v247
	v_pk_mul_f32 v[236:237], v[236:237], v[244:245]
	v_pk_mul_f32 v[238:239], v[238:239], v[246:247]
	v_pk_mul_f32 v[92:93], v[92:93], v[236:237]
	v_pk_mul_f32 v[94:95], v[94:95], v[238:239]
	v_cvt_pk_bf16_f32 v92, v92, v93
	v_cvt_pk_bf16_f32 v93, v94, v95
	global_store_dwordx2 v129, v[92:93], s[62:63] offset:0
	s_add_u32 s62, s62, 0x2c00
	s_addc_u32 s63, s63, 0
	v_pk_fma_f32 v[236:237], v[204:205], v[104:105], v[216:217]
	v_pk_fma_f32 v[236:237], v[208:209], v[68:69], v[236:237]
	v_pk_fma_f32 v[236:237], v[212:213], v[168:169], v[236:237]
	v_pk_fma_f32 v[238:239], v[206:207], v[106:107], v[218:219]
	v_pk_fma_f32 v[238:239], v[210:211], v[70:71], v[238:239]
	v_pk_fma_f32 v[238:239], v[214:215], v[170:171], v[238:239]
	v_pk_mul_f32 v[244:245], v[236:237], v[132:133]
	v_pk_mul_f32 v[246:247], v[238:239], v[132:133]
	v_exp_f32_e32 v244, v244
	v_exp_f32_e32 v245, v245
	v_exp_f32_e32 v246, v246
	v_exp_f32_e32 v247, v247
	v_pk_add_f32 v[244:245], v[244:245], 1.0 op_sel_hi:[1,0]
	v_pk_add_f32 v[246:247], v[246:247], 1.0 op_sel_hi:[1,0]
	v_rcp_f32_e32 v244, v244
	v_rcp_f32_e32 v245, v245
	v_rcp_f32_e32 v246, v246
	v_rcp_f32_e32 v247, v247
	v_pk_mul_f32 v[236:237], v[236:237], v[244:245]
	v_pk_mul_f32 v[238:239], v[238:239], v[246:247]
	v_pk_mul_f32 v[64:65], v[64:65], v[236:237]
	v_pk_mul_f32 v[66:67], v[66:67], v[238:239]
	v_cvt_pk_bf16_f32 v64, v64, v65
	v_cvt_pk_bf16_f32 v65, v66, v67
	s_andn2_b64 exec, exec, s[72:73]
	global_store_dwordx2 v129, v[64:65], s[62:63] offset:0
	s_mov_b64 exec, -1
	v_mov_b32_dpp v164, v4 row_shr:1 row_mask:0xf bank_mask:0xf bound_ctrl:0
	v_mov_b32_dpp v165, v5 row_shr:1 row_mask:0xf bank_mask:0xf bound_ctrl:0
	v_mov_b32_dpp v166, v6 row_shr:1 row_mask:0xf bank_mask:0xf bound_ctrl:0
	v_mov_b32_dpp v167, v7 row_shr:1 row_mask:0xf bank_mask:0xf bound_ctrl:0
	v_mov_b32_dpp v168, v12 row_shl:1 row_mask:0xf bank_mask:0xf bound_ctrl:0
	v_mov_b32_dpp v169, v13 row_shl:1 row_mask:0xf bank_mask:0xf bound_ctrl:0
	v_mov_b32_dpp v170, v14 row_shl:1 row_mask:0xf bank_mask:0xf bound_ctrl:0
	v_mov_b32_dpp v171, v15 row_shl:1 row_mask:0xf bank_mask:0xf bound_ctrl:0
	s_mov_b64 exec, s[70:71]
	v_pk_fma_f32 v[172:173], v[224:225], v[12:13], v[232:233]
	v_pk_fma_f32 v[172:173], v[228:229], v[60:61], v[172:173]
	v_pk_fma_f32 v[174:175], v[226:227], v[14:15], v[234:235]
	v_pk_fma_f32 v[174:175], v[230:231], v[62:63], v[174:175]
	s_add_u32 s68, s50, 0x113a0000
	s_addc_u32 s69, s51, 0
	s_add_u32 s68, s68, s32
	s_addc_u32 s69, s69, 0
	global_store_dwordx4 v130, v[12:15], s[68:69] offset:64
	s_add_u32 s68, s68, 0x318000
	s_addc_u32 s69, s69, 0
	global_store_dwordx4 v130, v[172:175], s[68:69] offset:64
	s_add_u32 s68, s68, 0x318000
	s_addc_u32 s69, s69, 0
	global_store_dwordx4 v130, v[8:11], s[68:69] offset:64
	s_nop 1
	s_mov_b64 exec, s[72:73]
	v_pk_fma_f32 v[172:173], v[220:221], v[28:29], v[232:233]
	v_pk_fma_f32 v[172:173], v[224:225], v[4:5], v[172:173]
	v_pk_fma_f32 v[174:175], v[222:223], v[30:31], v[234:235]
; DI float silu(float v) { return v * __builtin_amdgcn_rcpf(1.f + __builtin_amdgcn_exp2f(-1.4426950408889634f * v)); }
; DI void st_bf16x4(bf16_t* p, f32x4 v) { u32x2 w; w.x = cvt_pk_bf16(v[0], v[1]); w.y = cvt_pk_bf16(v[2], v[3]); *(u32x2*)p = w; }
;     DI void operator()(const f32x4 (&acc)[2][2][4][2], const Unit& u, int wr, int wc, int fr, int fq) const {
;     ...
;                 for (int k = 0; k < 8; ++k) { a[k] = acc[k >> 2][0][k & 3][n][j]; uu[k] = acc[k >> 2][1][k & 3][n][j]; }
;                 const float aprev = __shfl_up(a[7], 1), anext = __shfl_down(a[0], 1);
; #pragma unroll
;                 for (int k = 0; k < 8; ++k) {
;                     const float c = bb[j] + w0[j] * (k > 0 ? a[k - 1] : aprev) + w1[j] * a[k] + w2[j] * (k < 7 ? a[k + 1] : anext);
;                     g[k][j] = silu(c) * uu[k];
;                 }
;                 if (e_lo) { ed_a[j] = a[0]; ed_p[j] = bb[j] + w1[j] * a[0] + w2[j] * a[1]; ed_u[j] = uu[0]; }
;                 if (e_hi) { ed_a[j] = a[7]; ed_p[j] = bb[j] + w0[j] * a[6] + w1[j] * a[7]; ed_u[j] = uu[7]; }
;             }
; #pragma unroll
;             for (int k = 0; k < 8; ++k) {
;                 if ((k == 0 && e_lo) || (k == 7 && e_hi)) continue;
;                 st_bf16x4(G + (row0 + k) * DFF + col, g[k]);
	v_pk_fma_f32 v[174:175], v[226:227], v[6:7], v[174:175]
	s_add_u32 s68, s50, 0x113a0000
	s_addc_u32 s69, s51, 0
	s_add_u32 s68, s68, s32
	s_addc_u32 s69, s69, 0
	global_store_dwordx4 v130, v[4:7], s[68:69] offset:64
	s_add_u32 s68, s68, 0x318000
	s_addc_u32 s69, s69, 0
	global_store_dwordx4 v130, v[172:175], s[68:69] offset:64
	s_add_u32 s68, s68, 0x318000
	s_addc_u32 s69, s69, 0
	global_store_dwordx4 v130, v[0:3], s[68:69] offset:64
	s_nop 1
	s_mov_b64 exec, -1
	s_add_u32 s62, s50, 0x1d9a0000
	s_addc_u32 s63, s51, 0
	s_add_u32 s62, s62, s29
	s_addc_u32 s63, s63, 0
	v_pk_fma_f32 v[236:237], v[220:221], v[164:165], v[232:233]
	v_pk_fma_f32 v[236:237], v[224:225], v[12:13], v[236:237]
	v_pk_fma_f32 v[236:237], v[228:229], v[60:61], v[236:237]
	v_pk_fma_f32 v[238:239], v[222:223], v[166:167], v[234:235]
	v_pk_fma_f32 v[238:239], v[226:227], v[14:15], v[238:239]
	v_pk_fma_f32 v[238:239], v[230:231], v[62:63], v[238:239]
	v_pk_mul_f32 v[244:245], v[236:237], v[132:133]
	v_pk_mul_f32 v[246:247], v[238:239], v[132:133]
	v_exp_f32_e32 v244, v244
	v_exp_f32_e32 v245, v245
	v_exp_f32_e32 v246, v246
	v_exp_f32_e32 v247, v247
	v_pk_add_f32 v[244:245], v[244:245], 1.0 op_sel_hi:[1,0]
	v_pk_add_f32 v[246:247], v[246:247], 1.0 op_sel_hi:[1,0]
	v_rcp_f32_e32 v244, v244
	v_rcp_f32_e32 v245, v245
	v_rcp_f32_e32 v246, v246
	v_rcp_f32_e32 v247, v247
	v_pk_mul_f32 v[236:237], v[236:237], v[244:245]
	v_pk_mul_f32 v[238:239], v[238:239], v[246:247]
	v_pk_mul_f32 v[8:9], v[8:9], v[236:237]
	v_pk_mul_f32 v[10:11], v[10:11], v[238:239]
	v_cvt_pk_bf16_f32 v8, v8, v9
	v_cvt_pk_bf16_f32 v9, v10, v11
	s_andn2_b64 exec, exec, s[70:71]
	global_store_dwordx2 v129, v[8:9], s[62:63] offset:32
	s_mov_b64 exec, -1
	s_add_u32 s62, s62, 0x2c00
	s_addc_u32 s63, s63, 0
	v_pk_fma_f32 v[236:237], v[220:221], v[12:13], v[232:233]
	v_pk_fma_f32 v[236:237], v[224:225], v[60:61], v[236:237]
	v_pk_fma_f32 v[236:237], v[228:229], v[56:57], v[236:237]
	v_pk_fma_f32 v[238:239], v[222:223], v[14:15], v[234:235]
	v_pk_fma_f32 v[238:239], v[226:227], v[62:63], v[238:239]
	v_pk_fma_f32 v[238:239], v[230:231], v[58:59], v[238:239]
	v_pk_mul_f32 v[244:245], v[236:237], v[132:133]
	v_pk_mul_f32 v[246:247], v[238:239], v[132:133]
	v_exp_f32_e32 v244, v244
	v_exp_f32_e32 v245, v245
	v_exp_f32_e32 v246, v246
	v_exp_f32_e32 v247, v247
	v_pk_add_f32 v[244:245], v[244:245], 1.0 op_sel_hi:[1,0]
	v_pk_add_f32 v[246:247], v[246:247], 1.0 op_sel_hi:[1,0]
	v_rcp_f32_e32 v244, v244
	v_rcp_f32_e32 v245, v245
	v_rcp_f32_e32 v246, v246
	v_rcp_f32_e32 v247, v247
	v_pk_mul_f32 v[236:237], v[236:237], v[244:245]
	v_pk_mul_f32 v[238:239], v[238:239], v[246:247]
	v_pk_mul_f32 v[48:49], v[48:49], v[236:237]
	v_pk_mul_f32 v[50:51], v[50:51], v[238:239]
	v_cvt_pk_bf16_f32 v48, v48, v49
	v_cvt_pk_bf16_f32 v49, v50, v51
	global_store_dwordx2 v129, v[48:49], s[62:63] offset:32
	s_add_u32 s62, s62, 0x2c00
	s_addc_u32 s63, s63, 0
	v_pk_fma_f32 v[236:237], v[220:221], v[60:61], v[232:233]
	v_pk_fma_f32 v[236:237], v[224:225], v[56:57], v[236:237]
	v_pk_fma_f32 v[236:237], v[228:229], v[52:53], v[236:237]
	v_pk_fma_f32 v[238:239], v[222:223], v[62:63], v[234:235]
	v_pk_fma_f32 v[238:239], v[226:227], v[58:59], v[238:239]
	v_pk_fma_f32 v[238:239], v[230:231], v[54:55], v[238:239]
	v_pk_mul_f32 v[244:245], v[236:237], v[132:133]
	v_pk_mul_f32 v[246:247], v[238:239], v[132:133]
	v_exp_f32_e32 v244, v244
	v_exp_f32_e32 v245, v245
	v_exp_f32_e32 v246, v246
	v_exp_f32_e32 v247, v247
	v_pk_add_f32 v[244:245], v[244:245], 1.0 op_sel_hi:[1,0]
	v_pk_add_f32 v[246:247], v[246:247], 1.0 op_sel_hi:[1,0]
	v_rcp_f32_e32 v244, v244
	v_rcp_f32_e32 v245, v245
	v_rcp_f32_e32 v246, v246
	v_rcp_f32_e32 v247, v247
	v_pk_mul_f32 v[236:237], v[236:237], v[244:245]
	v_pk_mul_f32 v[238:239], v[238:239], v[246:247]
	v_pk_mul_f32 v[44:45], v[44:45], v[236:237]
	v_pk_mul_f32 v[46:47], v[46:47], v[238:239]
	v_cvt_pk_bf16_f32 v44, v44, v45
	v_cvt_pk_bf16_f32 v45, v46, v47
	global_store_dwordx2 v129, v[44:45], s[62:63] offset:32
	s_add_u32 s62, s62, 0x2c00
	s_addc_u32 s63, s63, 0
	v_pk_fma_f32 v[236:237], v[220:221], v[56:57], v[232:233]
	v_pk_fma_f32 v[236:237], v[224:225], v[52:53], v[236:237]
	v_pk_fma_f32 v[236:237], v[228:229], v[36:37], v[236:237]
	v_pk_fma_f32 v[238:239], v[222:223], v[58:59], v[234:235]
	v_pk_fma_f32 v[238:239], v[226:227], v[54:55], v[238:239]
	v_pk_fma_f32 v[238:239], v[230:231], v[38:39], v[238:239]
	v_pk_mul_f32 v[244:245], v[236:237], v[132:133]
	v_pk_mul_f32 v[246:247], v[238:239], v[132:133]
	v_exp_f32_e32 v244, v244
	v_exp_f32_e32 v245, v245
	v_exp_f32_e32 v246, v246
	v_exp_f32_e32 v247, v247
	v_pk_add_f32 v[244:245], v[244:245], 1.0 op_sel_hi:[1,0]
	v_pk_add_f32 v[246:247], v[246:247], 1.0 op_sel_hi:[1,0]
	v_rcp_f32_e32 v244, v244
	v_rcp_f32_e32 v245, v245
	v_rcp_f32_e32 v246, v246
	v_rcp_f32_e32 v247, v247
	v_pk_mul_f32 v[236:237], v[236:237], v[244:245]
; DI float silu(float v) { return v * __builtin_amdgcn_rcpf(1.f + __builtin_amdgcn_exp2f(-1.4426950408889634f * v)); }
; DI void st_bf16x4(bf16_t* p, f32x4 v) { u32x2 w; w.x = cvt_pk_bf16(v[0], v[1]); w.y = cvt_pk_bf16(v[2], v[3]); *(u32x2*)p = w; }
;     DI void operator()(const f32x4 (&acc)[2][2][4][2], const Unit& u, int wr, int wc, int fr, int fq) const {
;     ...
;                 for (int k = 0; k < 8; ++k) { a[k] = acc[k >> 2][0][k & 3][n][j]; uu[k] = acc[k >> 2][1][k & 3][n][j]; }
;                 const float aprev = __shfl_up(a[7], 1), anext = __shfl_down(a[0], 1);
; #pragma unroll
;                 for (int k = 0; k < 8; ++k) {
;                     const float c = bb[j] + w0[j] * (k > 0 ? a[k - 1] : aprev) + w1[j] * a[k] + w2[j] * (k < 7 ? a[k + 1] : anext);
;                     g[k][j] = silu(c) * uu[k];
;                 }
;                 if (e_lo) { ed_a[j] = a[0]; ed_p[j] = bb[j] + w1[j] * a[0] + w2[j] * a[1]; ed_u[j] = uu[0]; }
;                 if (e_hi) { ed_a[j] = a[7]; ed_p[j] = bb[j] + w0[j] * a[6] + w1[j] * a[7]; ed_u[j] = uu[7]; }
;             }
; #pragma unroll
;             for (int k = 0; k < 8; ++k) {
;                 if ((k == 0 && e_lo) || (k == 7 && e_hi)) continue;
;                 st_bf16x4(G + (row0 + k) * DFF + col, g[k]);
	v_pk_mul_f32 v[238:239], v[238:239], v[246:247]
	v_pk_mul_f32 v[40:41], v[40:41], v[236:237]
	v_pk_mul_f32 v[42:43], v[42:43], v[238:239]
	v_cvt_pk_bf16_f32 v40, v40, v41
	v_cvt_pk_bf16_f32 v41, v42, v43
	global_store_dwordx2 v129, v[40:41], s[62:63] offset:32
	s_add_u32 s62, s62, 0x2c00
	s_addc_u32 s63, s63, 0
	v_pk_fma_f32 v[236:237], v[220:221], v[52:53], v[232:233]
	v_pk_fma_f32 v[236:237], v[224:225], v[36:37], v[236:237]
	v_pk_fma_f32 v[236:237], v[228:229], v[32:33], v[236:237]
	v_pk_fma_f32 v[238:239], v[222:223], v[54:55], v[234:235]
	v_pk_fma_f32 v[238:239], v[226:227], v[38:39], v[238:239]
	v_pk_fma_f32 v[238:239], v[230:231], v[34:35], v[238:239]
	v_pk_mul_f32 v[244:245], v[236:237], v[132:133]
	v_pk_mul_f32 v[246:247], v[238:239], v[132:133]
	v_exp_f32_e32 v244, v244
	v_exp_f32_e32 v245, v245
	v_exp_f32_e32 v246, v246
	v_exp_f32_e32 v247, v247
	v_pk_add_f32 v[244:245], v[244:245], 1.0 op_sel_hi:[1,0]
	v_pk_add_f32 v[246:247], v[246:247], 1.0 op_sel_hi:[1,0]
	v_rcp_f32_e32 v244, v244
	v_rcp_f32_e32 v245, v245
	v_rcp_f32_e32 v246, v246
	v_rcp_f32_e32 v247, v247
	v_pk_mul_f32 v[236:237], v[236:237], v[244:245]
	v_pk_mul_f32 v[238:239], v[238:239], v[246:247]
	v_pk_mul_f32 v[24:25], v[24:25], v[236:237]
	v_pk_mul_f32 v[26:27], v[26:27], v[238:239]
	v_cvt_pk_bf16_f32 v24, v24, v25
	v_cvt_pk_bf16_f32 v25, v26, v27
	global_store_dwordx2 v129, v[24:25], s[62:63] offset:32
	s_add_u32 s62, s62, 0x2c00
	s_addc_u32 s63, s63, 0
	v_pk_fma_f32 v[236:237], v[220:221], v[36:37], v[232:233]
	v_pk_fma_f32 v[236:237], v[224:225], v[32:33], v[236:237]
	v_pk_fma_f32 v[236:237], v[228:229], v[28:29], v[236:237]
	v_pk_fma_f32 v[238:239], v[222:223], v[38:39], v[234:235]
	v_pk_fma_f32 v[238:239], v[226:227], v[34:35], v[238:239]
	v_pk_fma_f32 v[238:239], v[230:231], v[30:31], v[238:239]
	v_pk_mul_f32 v[244:245], v[236:237], v[132:133]
	v_pk_mul_f32 v[246:247], v[238:239], v[132:133]
	v_exp_f32_e32 v244, v244
	v_exp_f32_e32 v245, v245
	v_exp_f32_e32 v246, v246
	v_exp_f32_e32 v247, v247
	v_pk_add_f32 v[244:245], v[244:245], 1.0 op_sel_hi:[1,0]
	v_pk_add_f32 v[246:247], v[246:247], 1.0 op_sel_hi:[1,0]
	v_rcp_f32_e32 v244, v244
	v_rcp_f32_e32 v245, v245
	v_rcp_f32_e32 v246, v246
	v_rcp_f32_e32 v247, v247
	v_pk_mul_f32 v[236:237], v[236:237], v[244:245]
	v_pk_mul_f32 v[238:239], v[238:239], v[246:247]
	v_pk_mul_f32 v[20:21], v[20:21], v[236:237]
	v_pk_mul_f32 v[22:23], v[22:23], v[238:239]
	v_cvt_pk_bf16_f32 v20, v20, v21
	v_cvt_pk_bf16_f32 v21, v22, v23
	global_store_dwordx2 v129, v[20:21], s[62:63] offset:32
	s_add_u32 s62, s62, 0x2c00
	s_addc_u32 s63, s63, 0
	v_pk_fma_f32 v[236:237], v[220:221], v[32:33], v[232:233]
	v_pk_fma_f32 v[236:237], v[224:225], v[28:29], v[236:237]
	v_pk_fma_f32 v[236:237], v[228:229], v[4:5], v[236:237]
	v_pk_fma_f32 v[238:239], v[222:223], v[34:35], v[234:235]
	v_pk_fma_f32 v[238:239], v[226:227], v[30:31], v[238:239]
	v_pk_fma_f32 v[238:239], v[230:231], v[6:7], v[238:239]
	v_pk_mul_f32 v[244:245], v[236:237], v[132:133]
	v_pk_mul_f32 v[246:247], v[238:239], v[132:133]
	v_exp_f32_e32 v244, v244
	v_exp_f32_e32 v245, v245
	v_exp_f32_e32 v246, v246
	v_exp_f32_e32 v247, v247
	v_pk_add_f32 v[244:245], v[244:245], 1.0 op_sel_hi:[1,0]
	v_pk_add_f32 v[246:247], v[246:247], 1.0 op_sel_hi:[1,0]
	v_rcp_f32_e32 v244, v244
	v_rcp_f32_e32 v245, v245
	v_rcp_f32_e32 v246, v246
	v_rcp_f32_e32 v247, v247
	v_pk_mul_f32 v[236:237], v[236:237], v[244:245]
	v_pk_mul_f32 v[238:239], v[238:239], v[246:247]
	v_pk_mul_f32 v[16:17], v[16:17], v[236:237]
	v_pk_mul_f32 v[18:19], v[18:19], v[238:239]
	v_cvt_pk_bf16_f32 v16, v16, v17
	v_cvt_pk_bf16_f32 v17, v18, v19
	global_store_dwordx2 v129, v[16:17], s[62:63] offset:32
	s_add_u32 s62, s62, 0x2c00
	s_addc_u32 s63, s63, 0
	v_pk_fma_f32 v[236:237], v[220:221], v[28:29], v[232:233]
	v_pk_fma_f32 v[236:237], v[224:225], v[4:5], v[236:237]
	v_pk_fma_f32 v[236:237], v[228:229], v[168:169], v[236:237]
	v_pk_fma_f32 v[238:239], v[222:223], v[30:31], v[234:235]
	v_pk_fma_f32 v[238:239], v[226:227], v[6:7], v[238:239]
	v_pk_fma_f32 v[238:239], v[230:231], v[170:171], v[238:239]
	v_pk_mul_f32 v[244:245], v[236:237], v[132:133]
	v_pk_mul_f32 v[246:247], v[238:239], v[132:133]
	v_exp_f32_e32 v244, v244
	v_exp_f32_e32 v245, v245
	v_exp_f32_e32 v246, v246
	v_exp_f32_e32 v247, v247
	v_pk_add_f32 v[244:245], v[244:245], 1.0 op_sel_hi:[1,0]
	v_pk_add_f32 v[246:247], v[246:247], 1.0 op_sel_hi:[1,0]
	v_rcp_f32_e32 v244, v244
	v_rcp_f32_e32 v245, v245
	v_rcp_f32_e32 v246, v246
	v_rcp_f32_e32 v247, v247
	v_pk_mul_f32 v[236:237], v[236:237], v[244:245]
	v_pk_mul_f32 v[238:239], v[238:239], v[246:247]
	v_pk_mul_f32 v[0:1], v[0:1], v[236:237]
	v_pk_mul_f32 v[2:3], v[2:3], v[238:239]
	v_cvt_pk_bf16_f32 v0, v0, v1
	v_cvt_pk_bf16_f32 v1, v2, v3
	s_andn2_b64 exec, exec, s[72:73]
	global_store_dwordx2 v129, v[0:1], s[62:63] offset:32
	s_mov_b64 exec, -1
	s_mov_b64 s[60:61], exec
	s_branch .LBB0_2966
